# MFMA blocks: the priority drop/raise pair between the two halves of a block removed (priority held across the block)
# baseline (speedup 1.0000x reference)
; #define PG8_STAGE(bufoff, gbase, voff) do { _Pragma("unroll") for (int _i = 0; _i < 2; ++_i) \
;         __builtin_amdgcn_global_load_lds((const unsigned*)((const char*)(gbase) + (voff)[_i]), (PG8_LAS unsigned*)(lds + (bufoff) + ldsw + _i * 8192), 16, 0, 0); } while (0)
; #define PG8_LDA(dst, b, h) do { _Pragma("unroll") for (int m = 0; m < 4; ++m) _Pragma("unroll") for (int k = 0; k < 2; ++k) dst[m][k] = *(const PG8_LAS bf16x8*)(lds + PG8_SA(b, h) + aoff + m * 2048 + k * 1024); } while (0)
; #define PG8_LDB(dst, b, h) do { _Pragma("unroll") for (int n = 0; n < 2; ++n) _Pragma("unroll") for (int k = 0; k < 2; ++k) dst[n][k] = *(const PG8_LAS bf16x8*)(lds + PG8_SB(b, h) + boff + n * 2048 + k * 1024); } while (0)
; #define PG8_MMA(ai, bj, At, Bt) do { __builtin_amdgcn_s_setprio(1); _Pragma("unroll") for (int m = 0; m < 4; ++m) _Pragma("unroll") for (int n = 0; n < 2; ++n) _Pragma("unroll") for (int k = 0; k < 2; ++k) \
;         acc[ai][bj][m][n] = __builtin_amdgcn_mfma_f32_16x16x32_bf16(Bt[n][k], At[m][k], acc[ai][bj][m][n], 0, 0, 0); __builtin_amdgcn_s_setprio(0); } while (0)
; #define PG8_WAIT_V(n) asm volatile("s_waitcnt vmcnt(" #n ")" ::: "memory")
; #define PG8_WAIT_VN(n) asm volatile("s_waitcnt vmcnt(%0)" :: "n"(n) : "memory")
; #define PG8_WAIT_L(n) asm volatile("s_waitcnt lgkmcnt(" #n ")" ::: "memory")
; #define PG8_BAR __builtin_amdgcn_s_barrier()
; #define PG8_SCHED __builtin_amdgcn_sched_barrier(0)
; template <class Epi, class Sched, bool ALIGN_EPI = false, bool SP2 = false>
; __device__ __forceinline__ void gemm_phase(PG8_LAS unsigned char* lds, const Gemm g, const Sched& S, const Epi& E, const int wave_id) {
;     ...
;             PG8_WAIT_VN(8 + Epi::NS); if (strict) PG8_WAIT_V(8); PG8_WAIT_L(0); PG8_BAR; PG8_MMA(1, 0, At, B0); PG8_MMA(1, 1, At, B1); PG8_BAR; PG8_SCHED;
;             PG8_LDB(B0, 1, 0); PG8_LDB(B1, 1, 1); PG8_SCHED; PG8_LDA(At, 1, 0); PG8_STAGE(PG8_SA(0, 1), a2 + hstep, voffA);
;             PG8_WAIT_V(8); PG8_WAIT_L(0); PG8_BAR; PG8_MMA(0, 0, At, B0); PG8_MMA(0, 1, At, B1); PG8_BAR; PG8_SCHED;
.LBB0_157:
	s_waitcnt lgkmcnt(0)
	s_setprio 1
	s_barrier
	v_mfma_f32_16x16x32_bf16 v[62:65], v[146:149], v[186:189], v[62:65]
	v_mfma_f32_16x16x32_bf16 v[58:61], v[154:157], v[186:189], v[58:61]
	v_mfma_f32_16x16x32_bf16 v[54:57], v[146:149], v[178:181], v[54:57]
	v_mfma_f32_16x16x32_bf16 v[50:53], v[154:157], v[178:181], v[50:53]
	v_mfma_f32_16x16x32_bf16 v[30:33], v[146:149], v[170:173], v[30:33]
	v_mfma_f32_16x16x32_bf16 v[26:29], v[154:157], v[170:173], v[26:29]
	v_mfma_f32_16x16x32_bf16 v[22:25], v[146:149], v[162:165], v[22:25]
	v_mfma_f32_16x16x32_bf16 v[18:21], v[154:157], v[162:165], v[18:21]
	v_mfma_f32_16x16x32_bf16 v[62:65], v[150:153], v[190:193], v[62:65]
	v_mfma_f32_16x16x32_bf16 v[58:61], v[158:161], v[190:193], v[58:61]
	v_mfma_f32_16x16x32_bf16 v[54:57], v[150:153], v[182:185], v[54:57]
	v_mfma_f32_16x16x32_bf16 v[50:53], v[158:161], v[182:185], v[50:53]
	v_mfma_f32_16x16x32_bf16 v[30:33], v[150:153], v[174:177], v[30:33]
	v_mfma_f32_16x16x32_bf16 v[26:29], v[158:161], v[174:177], v[26:29]
	v_mfma_f32_16x16x32_bf16 v[22:25], v[150:153], v[166:169], v[22:25]
	v_mfma_f32_16x16x32_bf16 v[18:21], v[158:161], v[166:169], v[18:21]
	v_mfma_f32_16x16x32_bf16 v[46:49], v[130:133], v[186:189], v[46:49]
	v_mfma_f32_16x16x32_bf16 v[42:45], v[138:141], v[186:189], v[42:45]
	v_mfma_f32_16x16x32_bf16 v[38:41], v[130:133], v[178:181], v[38:41]
	v_mfma_f32_16x16x32_bf16 v[34:37], v[138:141], v[178:181], v[34:37]
	v_mfma_f32_16x16x32_bf16 v[14:17], v[130:133], v[170:173], v[14:17]
	v_mfma_f32_16x16x32_bf16 v[10:13], v[138:141], v[170:173], v[10:13]
	v_mfma_f32_16x16x32_bf16 v[6:9], v[130:133], v[162:165], v[6:9]
	v_mfma_f32_16x16x32_bf16 v[2:5], v[138:141], v[162:165], v[2:5]
	v_mfma_f32_16x16x32_bf16 v[46:49], v[134:137], v[190:193], v[46:49]
	v_mfma_f32_16x16x32_bf16 v[42:45], v[142:145], v[190:193], v[42:45]
	v_mfma_f32_16x16x32_bf16 v[38:41], v[134:137], v[182:185], v[38:41]
	v_mfma_f32_16x16x32_bf16 v[34:37], v[142:145], v[182:185], v[34:37]
	v_mfma_f32_16x16x32_bf16 v[14:17], v[134:137], v[174:177], v[14:17]
	v_mfma_f32_16x16x32_bf16 v[10:13], v[142:145], v[174:177], v[10:13]
	v_mfma_f32_16x16x32_bf16 v[6:9], v[134:137], v[166:169], v[6:9]
	v_mfma_f32_16x16x32_bf16 v[2:5], v[142:145], v[166:169], v[2:5]
	s_setprio 0
	s_barrier
	s_add_i32 s28, 0, 0x18000
	s_add_i32 s29, 0, 0x1c000
	v_add_u32_e32 v142, s28, v246
	v_add_u32_e32 v158, s29, v246
	ds_read_b128 v[130:133], v142
	ds_read_b128 v[134:137], v142 offset:1024
	ds_read_b128 v[138:141], v142 offset:2048
	ds_read_b128 v[142:145], v142 offset:3072
	ds_read_b128 v[146:149], v158
	ds_read_b128 v[150:153], v158 offset:1024
	ds_read_b128 v[154:157], v158 offset:2048
	ds_read_b128 v[158:161], v158 offset:3072
	s_add_u32 s26, s26, 0x40000
	s_addc_u32 s27, s27, 0
	s_mov_b32 m0, s52
	v_lshl_add_u64 v[194:195], s[26:27], 0, v[210:211]
	ds_read_b128 v[162:165], v249 offset:32768
	ds_read_b128 v[166:169], v249 offset:33792
	ds_read_b128 v[170:173], v249 offset:34816
	ds_read_b128 v[174:177], v249 offset:35840
	ds_read_b128 v[178:181], v249 offset:36864
	ds_read_b128 v[182:185], v249 offset:37888
	ds_read_b128 v[186:189], v249 offset:38912
	ds_read_b128 v[190:193], v249 offset:39936
	global_load_lds_dwordx4 v[194:195], off
	v_lshl_add_u64 v[194:195], s[26:27], 0, v[214:215]
	s_mov_b32 m0, s54
	s_nop 0
	global_load_lds_dwordx4 v[194:195], off
	s_waitcnt vmcnt(18)
	s_cmp_eq_u32 s100, 0
	s_cbranch_scc1 .Lthird_wait_relaxed_6
	s_waitcnt vmcnt(8)
; #define PG8_STAGE(bufoff, gbase, voff) do { _Pragma("unroll") for (int _i = 0; _i < 2; ++_i) \
;         __builtin_amdgcn_global_load_lds((const unsigned*)((const char*)(gbase) + (voff)[_i]), (PG8_LAS unsigned*)(lds + (bufoff) + ldsw + _i * 8192), 16, 0, 0); } while (0)
; #define PG8_LDA(dst, b, h) do { _Pragma("unroll") for (int m = 0; m < 4; ++m) _Pragma("unroll") for (int k = 0; k < 2; ++k) dst[m][k] = *(const PG8_LAS bf16x8*)(lds + PG8_SA(b, h) + aoff + m * 2048 + k * 1024); } while (0)
; #define PG8_MMA(ai, bj, At, Bt) do { __builtin_amdgcn_s_setprio(1); _Pragma("unroll") for (int m = 0; m < 4; ++m) _Pragma("unroll") for (int n = 0; n < 2; ++n) _Pragma("unroll") for (int k = 0; k < 2; ++k) \
;         acc[ai][bj][m][n] = __builtin_amdgcn_mfma_f32_16x16x32_bf16(Bt[n][k], At[m][k], acc[ai][bj][m][n], 0, 0, 0); __builtin_amdgcn_s_setprio(0); } while (0)
; #define PG8_WAIT_V(n) asm volatile("s_waitcnt vmcnt(" #n ")" ::: "memory")
; #define PG8_WAIT_L(n) asm volatile("s_waitcnt lgkmcnt(" #n ")" ::: "memory")
; #define PG8_BAR __builtin_amdgcn_s_barrier()
; #define PG8_SCHED __builtin_amdgcn_sched_barrier(0)
; template <class Epi, class Sched, bool ALIGN_EPI = false, bool SP2 = false>
; __device__ __forceinline__ void gemm_phase(PG8_LAS unsigned char* lds, const Gemm g, const Sched& S, const Epi& E, const int wave_id) {
;     ...
;             PG8_WAIT_V(8); PG8_WAIT_L(0); PG8_BAR; PG8_MMA(0, 0, At, B0); PG8_MMA(0, 1, At, B1); PG8_BAR; PG8_SCHED;
;             PG8_LDA(At, 1, 1); PG8_STAGE(PG8_SB(1, 0), b3, voffB); PG8_STAGE(PG8_SB(1, 1), b3 + hstep, voffB); PG8_STAGE(PG8_SA(1, 0), a3, voffA);
;             PG8_WAIT_V(8); PG8_WAIT_L(0); PG8_BAR; PG8_MMA(1, 0, At, B0); PG8_MMA(1, 1, At, B1); PG8_BAR; PG8_SCHED;
.Lthird_wait_relaxed_6:
	s_waitcnt lgkmcnt(0)
	s_setprio 1
	s_barrier
	v_mfma_f32_16x16x32_bf16 v[126:129], v[130:133], v[162:165], v[126:129]
	v_mfma_f32_16x16x32_bf16 v[122:125], v[138:141], v[162:165], v[122:125]
	v_mfma_f32_16x16x32_bf16 v[118:121], v[130:133], v[170:173], v[118:121]
	v_mfma_f32_16x16x32_bf16 v[114:117], v[138:141], v[170:173], v[114:117]
	v_mfma_f32_16x16x32_bf16 v[94:97], v[130:133], v[178:181], v[94:97]
	v_mfma_f32_16x16x32_bf16 v[90:93], v[138:141], v[178:181], v[90:93]
	v_mfma_f32_16x16x32_bf16 v[86:89], v[130:133], v[186:189], v[86:89]
	v_mfma_f32_16x16x32_bf16 v[82:85], v[138:141], v[186:189], v[82:85]
	v_mfma_f32_16x16x32_bf16 v[126:129], v[134:137], v[166:169], v[126:129]
	v_mfma_f32_16x16x32_bf16 v[122:125], v[142:145], v[166:169], v[122:125]
	v_mfma_f32_16x16x32_bf16 v[118:121], v[134:137], v[174:177], v[118:121]
	v_mfma_f32_16x16x32_bf16 v[114:117], v[142:145], v[174:177], v[114:117]
	v_mfma_f32_16x16x32_bf16 v[94:97], v[134:137], v[182:185], v[94:97]
	v_mfma_f32_16x16x32_bf16 v[90:93], v[142:145], v[182:185], v[90:93]
	v_mfma_f32_16x16x32_bf16 v[86:89], v[134:137], v[190:193], v[86:89]
	v_mfma_f32_16x16x32_bf16 v[82:85], v[142:145], v[190:193], v[82:85]
	v_mfma_f32_16x16x32_bf16 v[110:113], v[146:149], v[162:165], v[110:113]
	v_mfma_f32_16x16x32_bf16 v[106:109], v[154:157], v[162:165], v[106:109]
	v_mfma_f32_16x16x32_bf16 v[102:105], v[146:149], v[170:173], v[102:105]
	v_mfma_f32_16x16x32_bf16 v[98:101], v[154:157], v[170:173], v[98:101]
	v_mfma_f32_16x16x32_bf16 v[78:81], v[146:149], v[178:181], v[78:81]
	v_mfma_f32_16x16x32_bf16 v[74:77], v[154:157], v[178:181], v[74:77]
	v_mfma_f32_16x16x32_bf16 v[70:73], v[146:149], v[186:189], v[70:73]
	v_mfma_f32_16x16x32_bf16 v[66:69], v[154:157], v[186:189], v[66:69]
	v_mfma_f32_16x16x32_bf16 v[110:113], v[150:153], v[166:169], v[110:113]
	v_mfma_f32_16x16x32_bf16 v[106:109], v[158:161], v[166:169], v[106:109]
	v_mfma_f32_16x16x32_bf16 v[102:105], v[150:153], v[174:177], v[102:105]
	v_mfma_f32_16x16x32_bf16 v[98:101], v[158:161], v[174:177], v[98:101]
	v_mfma_f32_16x16x32_bf16 v[78:81], v[150:153], v[182:185], v[78:81]
	v_mfma_f32_16x16x32_bf16 v[74:77], v[158:161], v[182:185], v[74:77]
	v_mfma_f32_16x16x32_bf16 v[70:73], v[150:153], v[190:193], v[70:73]
	v_mfma_f32_16x16x32_bf16 v[66:69], v[158:161], v[190:193], v[66:69]
	s_setprio 0
	s_barrier
	s_add_i32 s26, s28, s40
	v_lshl_add_u64 v[194:195], v[232:233], 0, s[64:65]
	s_mov_b32 m0, s26
	ds_read_b128 v[162:165], v249 offset:49152
	ds_read_b128 v[166:169], v249 offset:50176
	ds_read_b128 v[170:173], v249 offset:51200
	ds_read_b128 v[174:177], v249 offset:52224
	ds_read_b128 v[178:181], v249 offset:53248
	ds_read_b128 v[182:185], v249 offset:54272
	ds_read_b128 v[186:189], v249 offset:55296
	ds_read_b128 v[190:193], v249 offset:56320
	global_load_lds_dwordx4 v[194:195], off
	s_add_i32 m0, s26, 0x2000
	s_add_u32 s24, s24, 0x40080
	v_lshl_add_u64 v[194:195], v[230:231], 0, s[64:65]
	s_addc_u32 s25, s25, 0
	s_add_i32 s26, s29, s40
	global_load_lds_dwordx4 v[194:195], off
	v_lshl_add_u64 v[194:195], s[24:25], 0, v[212:213]
	s_mov_b32 m0, s26
	s_nop 0
	global_load_lds_dwordx4 v[194:195], off
	v_lshl_add_u64 v[194:195], s[24:25], 0, v[216:217]
	s_add_i32 m0, s26, 0x2000
	s_nop 0
	global_load_lds_dwordx4 v[194:195], off
	v_lshl_add_u64 v[194:195], v[226:227], 0, s[64:65]
	s_mov_b32 m0, s57
	s_nop 0
	global_load_lds_dwordx4 v[194:195], off
	v_lshl_add_u64 v[194:195], v[228:229], 0, s[64:65]
	s_mov_b32 m0, s62
	s_nop 0
	global_load_lds_dwordx4 v[194:195], off
	s_waitcnt vmcnt(8)
	s_waitcnt lgkmcnt(0)
	s_setprio 1
	s_barrier
	v_mfma_f32_16x16x32_bf16 v[62:65], v[130:133], v[162:165], v[62:65]
	v_mfma_f32_16x16x32_bf16 v[58:61], v[138:141], v[162:165], v[58:61]
	v_mfma_f32_16x16x32_bf16 v[54:57], v[130:133], v[170:173], v[54:57]
	v_mfma_f32_16x16x32_bf16 v[50:53], v[138:141], v[170:173], v[50:53]
	v_mfma_f32_16x16x32_bf16 v[30:33], v[130:133], v[178:181], v[30:33]
	v_mfma_f32_16x16x32_bf16 v[26:29], v[138:141], v[178:181], v[26:29]
	v_mfma_f32_16x16x32_bf16 v[22:25], v[130:133], v[186:189], v[22:25]
	v_mfma_f32_16x16x32_bf16 v[18:21], v[138:141], v[186:189], v[18:21]
	v_mfma_f32_16x16x32_bf16 v[62:65], v[134:137], v[166:169], v[62:65]
	v_mfma_f32_16x16x32_bf16 v[58:61], v[142:145], v[166:169], v[58:61]
	v_mfma_f32_16x16x32_bf16 v[54:57], v[134:137], v[174:177], v[54:57]
	v_mfma_f32_16x16x32_bf16 v[50:53], v[142:145], v[174:177], v[50:53]
	v_mfma_f32_16x16x32_bf16 v[30:33], v[134:137], v[182:185], v[30:33]
	v_mfma_f32_16x16x32_bf16 v[26:29], v[142:145], v[182:185], v[26:29]
	v_mfma_f32_16x16x32_bf16 v[22:25], v[134:137], v[190:193], v[22:25]
	v_mfma_f32_16x16x32_bf16 v[18:21], v[142:145], v[190:193], v[18:21]
	v_mfma_f32_16x16x32_bf16 v[46:49], v[146:149], v[162:165], v[46:49]
	v_mfma_f32_16x16x32_bf16 v[42:45], v[154:157], v[162:165], v[42:45]
	v_mfma_f32_16x16x32_bf16 v[38:41], v[146:149], v[170:173], v[38:41]
	v_mfma_f32_16x16x32_bf16 v[34:37], v[154:157], v[170:173], v[34:37]
	v_mfma_f32_16x16x32_bf16 v[14:17], v[146:149], v[178:181], v[14:17]
	v_mfma_f32_16x16x32_bf16 v[10:13], v[154:157], v[178:181], v[10:13]
	v_mfma_f32_16x16x32_bf16 v[6:9], v[146:149], v[186:189], v[6:9]
	v_mfma_f32_16x16x32_bf16 v[2:5], v[154:157], v[186:189], v[2:5]
	v_mfma_f32_16x16x32_bf16 v[46:49], v[150:153], v[166:169], v[46:49]
	v_mfma_f32_16x16x32_bf16 v[42:45], v[158:161], v[166:169], v[42:45]
	v_mfma_f32_16x16x32_bf16 v[38:41], v[150:153], v[174:177], v[38:41]
	v_mfma_f32_16x16x32_bf16 v[34:37], v[158:161], v[174:177], v[34:37]
	v_mfma_f32_16x16x32_bf16 v[14:17], v[150:153], v[182:185], v[14:17]
	v_mfma_f32_16x16x32_bf16 v[10:13], v[158:161], v[182:185], v[10:13]
	v_mfma_f32_16x16x32_bf16 v[6:9], v[150:153], v[190:193], v[6:9]
	v_mfma_f32_16x16x32_bf16 v[2:5], v[158:161], v[190:193], v[2:5]
	s_setprio 0
	s_barrier
	s_add_i32 s76, s76, 2
	s_add_u32 s22, s22, 0x100
	s_addc_u32 s23, s23, 0
	s_cmp_gt_u32 s76, 13
	s_cbranch_scc1 .LBB0_162

; #define PG8_STAGE(bufoff, gbase, voff) do { _Pragma("unroll") for (int _i = 0; _i < 2; ++_i) \
;         __builtin_amdgcn_global_load_lds((const unsigned*)((const char*)(gbase) + (voff)[_i]), (PG8_LAS unsigned*)(lds + (bufoff) + ldsw + _i * 8192), 16, 0, 0); } while (0)
; #define PG8_LDA(dst, b, h) do { _Pragma("unroll") for (int m = 0; m < 4; ++m) _Pragma("unroll") for (int k = 0; k < 2; ++k) dst[m][k] = *(const PG8_LAS bf16x8*)(lds + PG8_SA(b, h) + aoff + m * 2048 + k * 1024); } while (0)
; #define PG8_LDB(dst, b, h) do { _Pragma("unroll") for (int n = 0; n < 2; ++n) _Pragma("unroll") for (int k = 0; k < 2; ++k) dst[n][k] = *(const PG8_LAS bf16x8*)(lds + PG8_SB(b, h) + boff + n * 2048 + k * 1024); } while (0)
; #define PG8_WAIT_V(n) asm volatile("s_waitcnt vmcnt(" #n ")" ::: "memory")
; #define PG8_WAIT_VN(n) asm volatile("s_waitcnt vmcnt(%0)" :: "n"(n) : "memory")
; #define PG8_WAIT_L(n) asm volatile("s_waitcnt lgkmcnt(" #n ")" ::: "memory")
; #define PG8_BAR __builtin_amdgcn_s_barrier()
; #define PG8_SCHED __builtin_amdgcn_sched_barrier(0)
; template <class Epi, class Sched, bool ALIGN_EPI = false, bool SP2 = false>
; __device__ __forceinline__ void gemm_phase(PG8_LAS unsigned char* lds, const Gemm g, const Sched& S, const Epi& E, const int wave_id) {
;     ...
;             const char* a1 = cA + (size_t)(t + 1) * kstep;
;             const char* a2 = last ? nA : cA + (size_t)(t + 2) * kstep; const char* b2 = last ? nB : cB + (size_t)(t + 2) * kstep;
;             const char* a3 = a2 + kstep; const char* b3 = b2 + kstep;
;             if (last && has_next) S.a_ready(nxt);
;             if constexpr (SP2) {
;             int tz_ = __builtin_amdgcn_readfirstlane(t | (ui > 0 ? 0 : 1)); asm volatile("" : "+s"(tz_));
;             const bool strict = !(Epi::NS > 0 && tz_ == 0);
;             PG8_LDB(B0, 0, 0); PG8_LDB(B1, 0, 1); PG8_SCHED; PG8_LDA(At, 0, 0); PG8_STAGE(PG8_SA(1, 1), a1 + hstep, voffA);
;             PG8_WAIT_VN(8 + Epi::NS); if (strict) PG8_WAIT_V(8); PG8_WAIT_L(0); PG8_BAR; PG8_MMA(0, 0, At, B0); PG8_MMA(0, 1, At, B1); PG8_BAR; PG8_SCHED;
;             PG8_LDA(At, 0, 1); PG8_STAGE(PG8_SB(0, 0), b2, voffB); PG8_STAGE(PG8_SB(0, 1), b2 + hstep, voffB); PG8_STAGE(PG8_SA(0, 0), a2, voffA);
;             PG8_WAIT_VN(8 + Epi::NS); if (strict) PG8_WAIT_V(8); PG8_WAIT_L(0); PG8_BAR; PG8_MMA(1, 0, At, B0); PG8_MMA(1, 1, At, B1); PG8_BAR; PG8_SCHED;
.LBB0_160:
	s_add_u32 s24, s20, s22
	s_addc_u32 s25, s21, s23
	s_add_u32 s24, s24, 0x100
	s_addc_u32 s25, s25, 0
	s_add_u32 s53, s74, s22
	s_addc_u32 s78, s75, s23
	s_cmpk_eq_i32 s22, 0x700
	s_cselect_b32 s27, s13, s25
	s_cselect_b32 s26, s68, s24
	s_cselect_b32 s25, s11, s78
	s_cselect_b32 s24, s69, s53
	s_waitcnt lgkmcnt(0)
	s_setprio 1
	s_barrier
	v_mfma_f32_16x16x32_bf16 v[126:129], v[146:149], v[186:189], v[126:129]
	v_mfma_f32_16x16x32_bf16 v[122:125], v[154:157], v[186:189], v[122:125]
	v_mfma_f32_16x16x32_bf16 v[118:121], v[146:149], v[178:181], v[118:121]
	v_mfma_f32_16x16x32_bf16 v[114:117], v[154:157], v[178:181], v[114:117]
	v_mfma_f32_16x16x32_bf16 v[94:97], v[146:149], v[170:173], v[94:97]
	v_mfma_f32_16x16x32_bf16 v[90:93], v[154:157], v[170:173], v[90:93]
	v_mfma_f32_16x16x32_bf16 v[86:89], v[146:149], v[162:165], v[86:89]
	v_mfma_f32_16x16x32_bf16 v[82:85], v[154:157], v[162:165], v[82:85]
	v_mfma_f32_16x16x32_bf16 v[126:129], v[150:153], v[190:193], v[126:129]
	v_mfma_f32_16x16x32_bf16 v[122:125], v[158:161], v[190:193], v[122:125]
	v_mfma_f32_16x16x32_bf16 v[118:121], v[150:153], v[182:185], v[118:121]
	v_mfma_f32_16x16x32_bf16 v[114:117], v[158:161], v[182:185], v[114:117]
	v_mfma_f32_16x16x32_bf16 v[94:97], v[150:153], v[174:177], v[94:97]
	v_mfma_f32_16x16x32_bf16 v[90:93], v[158:161], v[174:177], v[90:93]
	v_mfma_f32_16x16x32_bf16 v[86:89], v[150:153], v[166:169], v[86:89]
	v_mfma_f32_16x16x32_bf16 v[82:85], v[158:161], v[166:169], v[82:85]
	v_mfma_f32_16x16x32_bf16 v[110:113], v[130:133], v[186:189], v[110:113]
	v_mfma_f32_16x16x32_bf16 v[106:109], v[138:141], v[186:189], v[106:109]
	v_mfma_f32_16x16x32_bf16 v[102:105], v[130:133], v[178:181], v[102:105]
	v_mfma_f32_16x16x32_bf16 v[98:101], v[138:141], v[178:181], v[98:101]
	v_mfma_f32_16x16x32_bf16 v[78:81], v[130:133], v[170:173], v[78:81]
	v_mfma_f32_16x16x32_bf16 v[74:77], v[138:141], v[170:173], v[74:77]
	v_mfma_f32_16x16x32_bf16 v[70:73], v[130:133], v[162:165], v[70:73]
	v_mfma_f32_16x16x32_bf16 v[66:69], v[138:141], v[162:165], v[66:69]
	v_mfma_f32_16x16x32_bf16 v[110:113], v[134:137], v[190:193], v[110:113]
	v_mfma_f32_16x16x32_bf16 v[106:109], v[142:145], v[190:193], v[106:109]
	v_mfma_f32_16x16x32_bf16 v[102:105], v[134:137], v[182:185], v[102:105]
	v_mfma_f32_16x16x32_bf16 v[98:101], v[142:145], v[182:185], v[98:101]
	v_mfma_f32_16x16x32_bf16 v[78:81], v[134:137], v[174:177], v[78:81]
	v_mfma_f32_16x16x32_bf16 v[74:77], v[142:145], v[174:177], v[74:77]
	v_mfma_f32_16x16x32_bf16 v[70:73], v[134:137], v[166:169], v[70:73]
	v_mfma_f32_16x16x32_bf16 v[66:69], v[142:145], v[166:169], v[66:69]
	s_setprio 0
	s_barrier
	s_mov_b32 m0, s42
	v_lshl_add_u64 v[232:233], s[24:25], 0, v[212:213]
	s_add_u32 s90, s24, 0x40000
	ds_read_b128 v[186:189], v249 offset:16384
	ds_read_b128 v[190:193], v249 offset:17408
	ds_read_b128 v[178:181], v249 offset:18432
	ds_read_b128 v[182:185], v249 offset:19456
	ds_read_b128 v[170:173], v249 offset:20480
	ds_read_b128 v[174:177], v249 offset:21504
	ds_read_b128 v[162:165], v249 offset:22528
	ds_read_b128 v[166:169], v249 offset:23552
	global_load_lds_dwordx4 v[232:233], off
	v_lshl_add_u64 v[230:231], s[24:25], 0, v[216:217]
	s_mov_b32 m0, s43
	s_addc_u32 s91, s25, 0
	global_load_lds_dwordx4 v[230:231], off
	v_lshl_add_u64 v[194:195], s[90:91], 0, v[212:213]
	s_mov_b32 m0, s49
	v_lshl_add_u64 v[226:227], s[26:27], 0, v[210:211]
	global_load_lds_dwordx4 v[194:195], off
	v_lshl_add_u64 v[194:195], s[90:91], 0, v[216:217]
	s_mov_b32 m0, s50
	v_lshl_add_u64 v[228:229], s[26:27], 0, v[214:215]
	global_load_lds_dwordx4 v[194:195], off
	s_mov_b32 m0, s41
	s_andn2_b64 vcc, exec, s[28:29]
	global_load_lds_dwordx4 v[226:227], off
	s_mov_b32 m0, s51
	s_nop 0
	global_load_lds_dwordx4 v[228:229], off
	s_waitcnt vmcnt(16)
	s_cbranch_vccnz .LBB0_157
	s_waitcnt vmcnt(8)
	s_branch .LBB0_157

; #define PG8_STAGE(bufoff, gbase, voff) do { _Pragma("unroll") for (int _i = 0; _i < 2; ++_i) \
;         __builtin_amdgcn_global_load_lds((const unsigned*)((const char*)(gbase) + (voff)[_i]), (PG8_LAS unsigned*)(lds + (bufoff) + ldsw + _i * 8192), 16, 0, 0); } while (0)
; #define PG8_LDA(dst, b, h) do { _Pragma("unroll") for (int m = 0; m < 4; ++m) _Pragma("unroll") for (int k = 0; k < 2; ++k) dst[m][k] = *(const PG8_LAS bf16x8*)(lds + PG8_SA(b, h) + aoff + m * 2048 + k * 1024); } while (0)
; #define PG8_LDB(dst, b, h) do { _Pragma("unroll") for (int n = 0; n < 2; ++n) _Pragma("unroll") for (int k = 0; k < 2; ++k) dst[n][k] = *(const PG8_LAS bf16x8*)(lds + PG8_SB(b, h) + boff + n * 2048 + k * 1024); } while (0)
; #define PG8_MMA(ai, bj, At, Bt) do { __builtin_amdgcn_s_setprio(1); _Pragma("unroll") for (int m = 0; m < 4; ++m) _Pragma("unroll") for (int n = 0; n < 2; ++n) _Pragma("unroll") for (int k = 0; k < 2; ++k) \
;         acc[ai][bj][m][n] = __builtin_amdgcn_mfma_f32_16x16x32_bf16(Bt[n][k], At[m][k], acc[ai][bj][m][n], 0, 0, 0); __builtin_amdgcn_s_setprio(0); } while (0)
; #define PG8_WAIT_V(n) asm volatile("s_waitcnt vmcnt(" #n ")" ::: "memory")
; #define PG8_WAIT_VN(n) asm volatile("s_waitcnt vmcnt(%0)" :: "n"(n) : "memory")
; #define PG8_WAIT_L(n) asm volatile("s_waitcnt lgkmcnt(" #n ")" ::: "memory")
; #define PG8_BAR __builtin_amdgcn_s_barrier()
; #define PG8_SCHED __builtin_amdgcn_sched_barrier(0)
; template <class Epi, class Sched, bool ALIGN_EPI = false, bool SP2 = false>
; __device__ __forceinline__ void gemm_phase(PG8_LAS unsigned char* lds, const Gemm g, const Sched& S, const Epi& E, const int wave_id) {
;     ...
;             PG8_WAIT_VN(8 + Epi::NS); if (strict) PG8_WAIT_V(8); PG8_WAIT_L(0); PG8_BAR; PG8_MMA(1, 0, At, B0); PG8_MMA(1, 1, At, B1); PG8_BAR; PG8_SCHED;
;             PG8_LDB(B0, 1, 0); PG8_LDB(B1, 1, 1); PG8_SCHED; PG8_LDA(At, 1, 0); PG8_STAGE(PG8_SA(0, 1), a2 + hstep, voffA);
;             PG8_WAIT_V(8); PG8_WAIT_L(0); PG8_BAR; PG8_MMA(0, 0, At, B0); PG8_MMA(0, 1, At, B1); PG8_BAR; PG8_SCHED;
.LBB0_235:
	s_waitcnt lgkmcnt(0)
	s_setprio 1
	s_barrier
	v_mfma_f32_16x16x32_bf16 v[62:65], v[146:149], v[186:189], v[62:65]
	v_mfma_f32_16x16x32_bf16 v[58:61], v[154:157], v[186:189], v[58:61]
	v_mfma_f32_16x16x32_bf16 v[46:49], v[146:149], v[178:181], v[46:49]
	v_mfma_f32_16x16x32_bf16 v[42:45], v[154:157], v[178:181], v[42:45]
	v_mfma_f32_16x16x32_bf16 v[30:33], v[146:149], v[170:173], v[30:33]
	v_mfma_f32_16x16x32_bf16 v[26:29], v[154:157], v[170:173], v[26:29]
	v_mfma_f32_16x16x32_bf16 v[14:17], v[146:149], v[162:165], v[14:17]
	v_mfma_f32_16x16x32_bf16 v[10:13], v[154:157], v[162:165], v[10:13]
	v_mfma_f32_16x16x32_bf16 v[62:65], v[150:153], v[190:193], v[62:65]
	v_mfma_f32_16x16x32_bf16 v[58:61], v[158:161], v[190:193], v[58:61]
	v_mfma_f32_16x16x32_bf16 v[46:49], v[150:153], v[182:185], v[46:49]
	v_mfma_f32_16x16x32_bf16 v[42:45], v[158:161], v[182:185], v[42:45]
	v_mfma_f32_16x16x32_bf16 v[30:33], v[150:153], v[174:177], v[30:33]
	v_mfma_f32_16x16x32_bf16 v[26:29], v[158:161], v[174:177], v[26:29]
	v_mfma_f32_16x16x32_bf16 v[14:17], v[150:153], v[166:169], v[14:17]
	v_mfma_f32_16x16x32_bf16 v[10:13], v[158:161], v[166:169], v[10:13]
	v_mfma_f32_16x16x32_bf16 v[54:57], v[130:133], v[186:189], v[54:57]
	v_mfma_f32_16x16x32_bf16 v[50:53], v[138:141], v[186:189], v[50:53]
	v_mfma_f32_16x16x32_bf16 v[38:41], v[130:133], v[178:181], v[38:41]
	v_mfma_f32_16x16x32_bf16 v[34:37], v[138:141], v[178:181], v[34:37]
	v_mfma_f32_16x16x32_bf16 v[22:25], v[130:133], v[170:173], v[22:25]
	v_mfma_f32_16x16x32_bf16 v[18:21], v[138:141], v[170:173], v[18:21]
	v_mfma_f32_16x16x32_bf16 v[6:9], v[130:133], v[162:165], v[6:9]
	v_mfma_f32_16x16x32_bf16 v[2:5], v[138:141], v[162:165], v[2:5]
	v_mfma_f32_16x16x32_bf16 v[54:57], v[134:137], v[190:193], v[54:57]
	v_mfma_f32_16x16x32_bf16 v[50:53], v[142:145], v[190:193], v[50:53]
	v_mfma_f32_16x16x32_bf16 v[38:41], v[134:137], v[182:185], v[38:41]
	v_mfma_f32_16x16x32_bf16 v[34:37], v[142:145], v[182:185], v[34:37]
	v_mfma_f32_16x16x32_bf16 v[22:25], v[134:137], v[174:177], v[22:25]
	v_mfma_f32_16x16x32_bf16 v[18:21], v[142:145], v[174:177], v[18:21]
	v_mfma_f32_16x16x32_bf16 v[6:9], v[134:137], v[166:169], v[6:9]
	v_mfma_f32_16x16x32_bf16 v[2:5], v[142:145], v[166:169], v[2:5]
	s_setprio 0
	s_barrier
	s_add_i32 s20, 0, 0x18000
	s_add_i32 s21, 0, 0x1c000
	v_add_u32_e32 v142, s20, v246
	v_add_u32_e32 v158, s21, v246
	ds_read_b128 v[130:133], v142
	ds_read_b128 v[134:137], v142 offset:1024
	ds_read_b128 v[138:141], v142 offset:2048
	ds_read_b128 v[142:145], v142 offset:3072
	ds_read_b128 v[146:149], v158
	ds_read_b128 v[150:153], v158 offset:1024
	ds_read_b128 v[154:157], v158 offset:2048
	ds_read_b128 v[158:161], v158 offset:3072
	s_add_u32 s18, s18, 0xb0000
	s_addc_u32 s19, s19, 0
	s_mov_b32 m0, s39
	v_lshl_add_u64 v[194:195], s[18:19], 0, v[210:211]
	ds_read_b128 v[162:165], v247 offset:32768
	ds_read_b128 v[166:169], v247 offset:33792
	ds_read_b128 v[170:173], v247 offset:34816
	ds_read_b128 v[174:177], v247 offset:35840
	ds_read_b128 v[178:181], v247 offset:36864
	ds_read_b128 v[182:185], v247 offset:37888
	ds_read_b128 v[186:189], v247 offset:38912
	ds_read_b128 v[190:193], v247 offset:39936
	global_load_lds_dwordx4 v[194:195], off
	v_lshl_add_u64 v[194:195], s[18:19], 0, v[214:215]
	s_mov_b32 m0, s40
	s_nop 0
	global_load_lds_dwordx4 v[194:195], off
	s_waitcnt vmcnt(26)
	s_cmp_eq_u32 s100, 0
	s_cbranch_scc1 .Lthird_wait_relaxed_5
	s_waitcnt vmcnt(8)
; #define PG8_STAGE(bufoff, gbase, voff) do { _Pragma("unroll") for (int _i = 0; _i < 2; ++_i) \
;         __builtin_amdgcn_global_load_lds((const unsigned*)((const char*)(gbase) + (voff)[_i]), (PG8_LAS unsigned*)(lds + (bufoff) + ldsw + _i * 8192), 16, 0, 0); } while (0)
; #define PG8_LDA(dst, b, h) do { _Pragma("unroll") for (int m = 0; m < 4; ++m) _Pragma("unroll") for (int k = 0; k < 2; ++k) dst[m][k] = *(const PG8_LAS bf16x8*)(lds + PG8_SA(b, h) + aoff + m * 2048 + k * 1024); } while (0)
; #define PG8_MMA(ai, bj, At, Bt) do { __builtin_amdgcn_s_setprio(1); _Pragma("unroll") for (int m = 0; m < 4; ++m) _Pragma("unroll") for (int n = 0; n < 2; ++n) _Pragma("unroll") for (int k = 0; k < 2; ++k) \
;         acc[ai][bj][m][n] = __builtin_amdgcn_mfma_f32_16x16x32_bf16(Bt[n][k], At[m][k], acc[ai][bj][m][n], 0, 0, 0); __builtin_amdgcn_s_setprio(0); } while (0)
; #define PG8_WAIT_V(n) asm volatile("s_waitcnt vmcnt(" #n ")" ::: "memory")
; #define PG8_WAIT_L(n) asm volatile("s_waitcnt lgkmcnt(" #n ")" ::: "memory")
; #define PG8_BAR __builtin_amdgcn_s_barrier()
; #define PG8_SCHED __builtin_amdgcn_sched_barrier(0)
; template <class Epi, class Sched, bool ALIGN_EPI = false, bool SP2 = false>
; __device__ __forceinline__ void gemm_phase(PG8_LAS unsigned char* lds, const Gemm g, const Sched& S, const Epi& E, const int wave_id) {
;     ...
;             PG8_WAIT_V(8); PG8_WAIT_L(0); PG8_BAR; PG8_MMA(0, 0, At, B0); PG8_MMA(0, 1, At, B1); PG8_BAR; PG8_SCHED;
;             PG8_LDA(At, 1, 1); PG8_STAGE(PG8_SB(1, 0), b3, voffB); PG8_STAGE(PG8_SB(1, 1), b3 + hstep, voffB); PG8_STAGE(PG8_SA(1, 0), a3, voffA);
;             PG8_WAIT_V(8); PG8_WAIT_L(0); PG8_BAR; PG8_MMA(1, 0, At, B0); PG8_MMA(1, 1, At, B1); PG8_BAR; PG8_SCHED;
.Lthird_wait_relaxed_5:
	s_waitcnt lgkmcnt(0)
	s_setprio 1
	s_barrier
	v_mfma_f32_16x16x32_bf16 v[126:129], v[130:133], v[162:165], v[126:129]
	v_mfma_f32_16x16x32_bf16 v[122:125], v[138:141], v[162:165], v[122:125]
	v_mfma_f32_16x16x32_bf16 v[110:113], v[130:133], v[170:173], v[110:113]
	v_mfma_f32_16x16x32_bf16 v[106:109], v[138:141], v[170:173], v[106:109]
	v_mfma_f32_16x16x32_bf16 v[94:97], v[130:133], v[178:181], v[94:97]
	v_mfma_f32_16x16x32_bf16 v[90:93], v[138:141], v[178:181], v[90:93]
	v_mfma_f32_16x16x32_bf16 v[78:81], v[130:133], v[186:189], v[78:81]
	v_mfma_f32_16x16x32_bf16 v[74:77], v[138:141], v[186:189], v[74:77]
	v_mfma_f32_16x16x32_bf16 v[126:129], v[134:137], v[166:169], v[126:129]
	v_mfma_f32_16x16x32_bf16 v[122:125], v[142:145], v[166:169], v[122:125]
	v_mfma_f32_16x16x32_bf16 v[110:113], v[134:137], v[174:177], v[110:113]
	v_mfma_f32_16x16x32_bf16 v[106:109], v[142:145], v[174:177], v[106:109]
	v_mfma_f32_16x16x32_bf16 v[94:97], v[134:137], v[182:185], v[94:97]
	v_mfma_f32_16x16x32_bf16 v[90:93], v[142:145], v[182:185], v[90:93]
	v_mfma_f32_16x16x32_bf16 v[78:81], v[134:137], v[190:193], v[78:81]
	v_mfma_f32_16x16x32_bf16 v[74:77], v[142:145], v[190:193], v[74:77]
	v_mfma_f32_16x16x32_bf16 v[118:121], v[146:149], v[162:165], v[118:121]
	v_mfma_f32_16x16x32_bf16 v[114:117], v[154:157], v[162:165], v[114:117]
	v_mfma_f32_16x16x32_bf16 v[102:105], v[146:149], v[170:173], v[102:105]
	v_mfma_f32_16x16x32_bf16 v[98:101], v[154:157], v[170:173], v[98:101]
	v_mfma_f32_16x16x32_bf16 v[86:89], v[146:149], v[178:181], v[86:89]
	v_mfma_f32_16x16x32_bf16 v[82:85], v[154:157], v[178:181], v[82:85]
	v_mfma_f32_16x16x32_bf16 v[70:73], v[146:149], v[186:189], v[70:73]
	v_mfma_f32_16x16x32_bf16 v[66:69], v[154:157], v[186:189], v[66:69]
	v_mfma_f32_16x16x32_bf16 v[118:121], v[150:153], v[166:169], v[118:121]
	v_mfma_f32_16x16x32_bf16 v[114:117], v[158:161], v[166:169], v[114:117]
	v_mfma_f32_16x16x32_bf16 v[102:105], v[150:153], v[174:177], v[102:105]
	v_mfma_f32_16x16x32_bf16 v[98:101], v[158:161], v[174:177], v[98:101]
	v_mfma_f32_16x16x32_bf16 v[86:89], v[150:153], v[182:185], v[86:89]
	v_mfma_f32_16x16x32_bf16 v[82:85], v[158:161], v[182:185], v[82:85]
	v_mfma_f32_16x16x32_bf16 v[70:73], v[150:153], v[190:193], v[70:73]
	v_mfma_f32_16x16x32_bf16 v[66:69], v[158:161], v[190:193], v[66:69]
	s_setprio 0
	s_barrier
	s_add_i32 s18, s20, s30
	v_lshl_add_u64 v[194:195], v[232:233], 0, s[64:65]
	s_mov_b32 m0, s18
	ds_read_b128 v[162:165], v247 offset:49152
	ds_read_b128 v[166:169], v247 offset:50176
	ds_read_b128 v[170:173], v247 offset:51200
	ds_read_b128 v[174:177], v247 offset:52224
	ds_read_b128 v[178:181], v247 offset:53248
	ds_read_b128 v[182:185], v247 offset:54272
	ds_read_b128 v[186:189], v247 offset:55296
	ds_read_b128 v[190:193], v247 offset:56320
	global_load_lds_dwordx4 v[194:195], off
	s_add_i32 m0, s18, 0x2000
	s_add_u32 s16, s16, 0xb0080
	v_lshl_add_u64 v[194:195], v[230:231], 0, s[64:65]
	s_addc_u32 s17, s17, 0
	s_add_i32 s18, s21, s30
	global_load_lds_dwordx4 v[194:195], off
	v_lshl_add_u64 v[194:195], s[16:17], 0, v[212:213]
	s_mov_b32 m0, s18
	s_nop 0
	global_load_lds_dwordx4 v[194:195], off
	v_lshl_add_u64 v[194:195], s[16:17], 0, v[216:217]
	s_add_i32 m0, s18, 0x2000
	s_nop 0
	global_load_lds_dwordx4 v[194:195], off
	v_lshl_add_u64 v[194:195], v[226:227], 0, s[64:65]
	s_mov_b32 m0, s42
	s_nop 0
	global_load_lds_dwordx4 v[194:195], off
	v_lshl_add_u64 v[194:195], v[228:229], 0, s[64:65]
	s_mov_b32 m0, s43
	s_nop 0
	global_load_lds_dwordx4 v[194:195], off
	s_waitcnt vmcnt(8)
	s_waitcnt lgkmcnt(0)
	s_setprio 1
	s_barrier
	v_mfma_f32_16x16x32_bf16 v[62:65], v[130:133], v[162:165], v[62:65]
	v_mfma_f32_16x16x32_bf16 v[58:61], v[138:141], v[162:165], v[58:61]
	v_mfma_f32_16x16x32_bf16 v[46:49], v[130:133], v[170:173], v[46:49]
	v_mfma_f32_16x16x32_bf16 v[42:45], v[138:141], v[170:173], v[42:45]
	v_mfma_f32_16x16x32_bf16 v[30:33], v[130:133], v[178:181], v[30:33]
	v_mfma_f32_16x16x32_bf16 v[26:29], v[138:141], v[178:181], v[26:29]
	v_mfma_f32_16x16x32_bf16 v[14:17], v[130:133], v[186:189], v[14:17]
	v_mfma_f32_16x16x32_bf16 v[10:13], v[138:141], v[186:189], v[10:13]
	v_mfma_f32_16x16x32_bf16 v[62:65], v[134:137], v[166:169], v[62:65]
	v_mfma_f32_16x16x32_bf16 v[58:61], v[142:145], v[166:169], v[58:61]
	v_mfma_f32_16x16x32_bf16 v[46:49], v[134:137], v[174:177], v[46:49]
	v_mfma_f32_16x16x32_bf16 v[42:45], v[142:145], v[174:177], v[42:45]
	v_mfma_f32_16x16x32_bf16 v[30:33], v[134:137], v[182:185], v[30:33]
	v_mfma_f32_16x16x32_bf16 v[26:29], v[142:145], v[182:185], v[26:29]
	v_mfma_f32_16x16x32_bf16 v[14:17], v[134:137], v[190:193], v[14:17]
	v_mfma_f32_16x16x32_bf16 v[10:13], v[142:145], v[190:193], v[10:13]
	v_mfma_f32_16x16x32_bf16 v[54:57], v[146:149], v[162:165], v[54:57]
	v_mfma_f32_16x16x32_bf16 v[50:53], v[154:157], v[162:165], v[50:53]
	v_mfma_f32_16x16x32_bf16 v[38:41], v[146:149], v[170:173], v[38:41]
	v_mfma_f32_16x16x32_bf16 v[34:37], v[154:157], v[170:173], v[34:37]
	v_mfma_f32_16x16x32_bf16 v[22:25], v[146:149], v[178:181], v[22:25]
	v_mfma_f32_16x16x32_bf16 v[18:21], v[154:157], v[178:181], v[18:21]
	v_mfma_f32_16x16x32_bf16 v[6:9], v[146:149], v[186:189], v[6:9]
	v_mfma_f32_16x16x32_bf16 v[2:5], v[154:157], v[186:189], v[2:5]
	v_mfma_f32_16x16x32_bf16 v[54:57], v[150:153], v[166:169], v[54:57]
	v_mfma_f32_16x16x32_bf16 v[50:53], v[158:161], v[166:169], v[50:53]
	v_mfma_f32_16x16x32_bf16 v[38:41], v[150:153], v[174:177], v[38:41]
	v_mfma_f32_16x16x32_bf16 v[34:37], v[158:161], v[174:177], v[34:37]
	v_mfma_f32_16x16x32_bf16 v[22:25], v[150:153], v[182:185], v[22:25]
	v_mfma_f32_16x16x32_bf16 v[18:21], v[158:161], v[182:185], v[18:21]
	v_mfma_f32_16x16x32_bf16 v[6:9], v[150:153], v[190:193], v[6:9]
	v_mfma_f32_16x16x32_bf16 v[2:5], v[158:161], v[190:193], v[2:5]
	s_setprio 0
	s_barrier
	s_add_i32 s63, s63, 2
	s_add_u32 s14, s14, 0x100
	s_addc_u32 s15, s15, 0
	s_cmp_gt_u32 s63, 41
	s_cbranch_scc1 .LBB0_240

; #define PG8_STAGE(bufoff, gbase, voff) do { _Pragma("unroll") for (int _i = 0; _i < 2; ++_i) \
;         __builtin_amdgcn_global_load_lds((const unsigned*)((const char*)(gbase) + (voff)[_i]), (PG8_LAS unsigned*)(lds + (bufoff) + ldsw + _i * 8192), 16, 0, 0); } while (0)
; #define PG8_LDA(dst, b, h) do { _Pragma("unroll") for (int m = 0; m < 4; ++m) _Pragma("unroll") for (int k = 0; k < 2; ++k) dst[m][k] = *(const PG8_LAS bf16x8*)(lds + PG8_SA(b, h) + aoff + m * 2048 + k * 1024); } while (0)
; #define PG8_LDB(dst, b, h) do { _Pragma("unroll") for (int n = 0; n < 2; ++n) _Pragma("unroll") for (int k = 0; k < 2; ++k) dst[n][k] = *(const PG8_LAS bf16x8*)(lds + PG8_SB(b, h) + boff + n * 2048 + k * 1024); } while (0)
; #define PG8_WAIT_V(n) asm volatile("s_waitcnt vmcnt(" #n ")" ::: "memory")
; #define PG8_WAIT_VN(n) asm volatile("s_waitcnt vmcnt(%0)" :: "n"(n) : "memory")
; #define PG8_WAIT_L(n) asm volatile("s_waitcnt lgkmcnt(" #n ")" ::: "memory")
; #define PG8_BAR __builtin_amdgcn_s_barrier()
; #define PG8_SCHED __builtin_amdgcn_sched_barrier(0)
; template <class Epi, class Sched, bool ALIGN_EPI = false, bool SP2 = false>
; __device__ __forceinline__ void gemm_phase(PG8_LAS unsigned char* lds, const Gemm g, const Sched& S, const Epi& E, const int wave_id) {
;     ...
;             const char* a1 = cA + (size_t)(t + 1) * kstep;
;             const char* a2 = last ? nA : cA + (size_t)(t + 2) * kstep; const char* b2 = last ? nB : cB + (size_t)(t + 2) * kstep;
;             const char* a3 = a2 + kstep; const char* b3 = b2 + kstep;
;             if (last && has_next) S.a_ready(nxt);
;             if constexpr (SP2) {
;             int tz_ = __builtin_amdgcn_readfirstlane(t | (ui > 0 ? 0 : 1)); asm volatile("" : "+s"(tz_));
;             const bool strict = !(Epi::NS > 0 && tz_ == 0);
;             PG8_LDB(B0, 0, 0); PG8_LDB(B1, 0, 1); PG8_SCHED; PG8_LDA(At, 0, 0); PG8_STAGE(PG8_SA(1, 1), a1 + hstep, voffA);
;             PG8_WAIT_VN(8 + Epi::NS); if (strict) PG8_WAIT_V(8); PG8_WAIT_L(0); PG8_BAR; PG8_MMA(0, 0, At, B0); PG8_MMA(0, 1, At, B1); PG8_BAR; PG8_SCHED;
;             PG8_LDA(At, 0, 1); PG8_STAGE(PG8_SB(0, 0), b2, voffB); PG8_STAGE(PG8_SB(0, 1), b2 + hstep, voffB); PG8_STAGE(PG8_SA(0, 0), a2, voffA);
;             PG8_WAIT_VN(8 + Epi::NS); if (strict) PG8_WAIT_V(8); PG8_WAIT_L(0); PG8_BAR; PG8_MMA(1, 0, At, B0); PG8_MMA(1, 1, At, B1); PG8_BAR; PG8_SCHED;
.LBB0_238:
	s_add_u32 s16, s12, s14
	s_addc_u32 s17, s13, s15
	s_add_u32 s16, s16, 0x100
	s_addc_u32 s17, s17, 0
	s_add_u32 s53, s57, s14
	s_addc_u32 s67, s62, s15
	s_cmpk_eq_i32 s14, 0x1500
	s_cselect_b32 s19, s7, s17
	s_cselect_b32 s18, s6, s16
	s_cselect_b32 s17, s11, s67
	s_cselect_b32 s16, s10, s53
	s_waitcnt lgkmcnt(0)
	s_setprio 1
	s_barrier
	v_mfma_f32_16x16x32_bf16 v[126:129], v[146:149], v[186:189], v[126:129]
	v_mfma_f32_16x16x32_bf16 v[122:125], v[154:157], v[186:189], v[122:125]
	v_mfma_f32_16x16x32_bf16 v[110:113], v[146:149], v[178:181], v[110:113]
	v_mfma_f32_16x16x32_bf16 v[106:109], v[154:157], v[178:181], v[106:109]
	v_mfma_f32_16x16x32_bf16 v[94:97], v[146:149], v[170:173], v[94:97]
	v_mfma_f32_16x16x32_bf16 v[90:93], v[154:157], v[170:173], v[90:93]
	v_mfma_f32_16x16x32_bf16 v[78:81], v[146:149], v[162:165], v[78:81]
	v_mfma_f32_16x16x32_bf16 v[74:77], v[154:157], v[162:165], v[74:77]
	v_mfma_f32_16x16x32_bf16 v[126:129], v[150:153], v[190:193], v[126:129]
	v_mfma_f32_16x16x32_bf16 v[122:125], v[158:161], v[190:193], v[122:125]
	v_mfma_f32_16x16x32_bf16 v[110:113], v[150:153], v[182:185], v[110:113]
	v_mfma_f32_16x16x32_bf16 v[106:109], v[158:161], v[182:185], v[106:109]
	v_mfma_f32_16x16x32_bf16 v[94:97], v[150:153], v[174:177], v[94:97]
	v_mfma_f32_16x16x32_bf16 v[90:93], v[158:161], v[174:177], v[90:93]
	v_mfma_f32_16x16x32_bf16 v[78:81], v[150:153], v[166:169], v[78:81]
	v_mfma_f32_16x16x32_bf16 v[74:77], v[158:161], v[166:169], v[74:77]
	v_mfma_f32_16x16x32_bf16 v[118:121], v[130:133], v[186:189], v[118:121]
	v_mfma_f32_16x16x32_bf16 v[114:117], v[138:141], v[186:189], v[114:117]
	v_mfma_f32_16x16x32_bf16 v[102:105], v[130:133], v[178:181], v[102:105]
	v_mfma_f32_16x16x32_bf16 v[98:101], v[138:141], v[178:181], v[98:101]
	v_mfma_f32_16x16x32_bf16 v[86:89], v[130:133], v[170:173], v[86:89]
	v_mfma_f32_16x16x32_bf16 v[82:85], v[138:141], v[170:173], v[82:85]
	v_mfma_f32_16x16x32_bf16 v[70:73], v[130:133], v[162:165], v[70:73]
	v_mfma_f32_16x16x32_bf16 v[66:69], v[138:141], v[162:165], v[66:69]
	v_mfma_f32_16x16x32_bf16 v[118:121], v[134:137], v[190:193], v[118:121]
	v_mfma_f32_16x16x32_bf16 v[114:117], v[142:145], v[190:193], v[114:117]
	v_mfma_f32_16x16x32_bf16 v[102:105], v[134:137], v[182:185], v[102:105]
	v_mfma_f32_16x16x32_bf16 v[98:101], v[142:145], v[182:185], v[98:101]
	v_mfma_f32_16x16x32_bf16 v[86:89], v[134:137], v[174:177], v[86:89]
	v_mfma_f32_16x16x32_bf16 v[82:85], v[142:145], v[174:177], v[82:85]
	v_mfma_f32_16x16x32_bf16 v[70:73], v[134:137], v[166:169], v[70:73]
	v_mfma_f32_16x16x32_bf16 v[66:69], v[142:145], v[166:169], v[66:69]
	s_setprio 0
	s_barrier
	s_mov_b32 m0, s34
	v_lshl_add_u64 v[232:233], s[16:17], 0, v[212:213]
	s_add_u32 s68, s16, 0xb0000
	ds_read_b128 v[186:189], v247 offset:16384
	ds_read_b128 v[190:193], v247 offset:17408
	ds_read_b128 v[178:181], v247 offset:18432
	ds_read_b128 v[182:185], v247 offset:19456
	ds_read_b128 v[170:173], v247 offset:20480
	ds_read_b128 v[174:177], v247 offset:21504
	ds_read_b128 v[162:165], v247 offset:22528
	ds_read_b128 v[166:169], v247 offset:23552
	global_load_lds_dwordx4 v[232:233], off
	v_lshl_add_u64 v[230:231], s[16:17], 0, v[216:217]
	s_mov_b32 m0, s35
	s_addc_u32 s69, s17, 0
	global_load_lds_dwordx4 v[230:231], off
	v_lshl_add_u64 v[194:195], s[68:69], 0, v[212:213]
	s_mov_b32 m0, s36
	v_lshl_add_u64 v[226:227], s[18:19], 0, v[210:211]
	global_load_lds_dwordx4 v[194:195], off
	v_lshl_add_u64 v[194:195], s[68:69], 0, v[216:217]
	s_mov_b32 m0, s37
	v_lshl_add_u64 v[228:229], s[18:19], 0, v[214:215]
	global_load_lds_dwordx4 v[194:195], off
	s_mov_b32 m0, s31
	s_andn2_b64 vcc, exec, s[20:21]
	global_load_lds_dwordx4 v[226:227], off
	s_mov_b32 m0, s38
	s_nop 0
	global_load_lds_dwordx4 v[228:229], off
	s_waitcnt vmcnt(24)
	s_cbranch_vccnz .LBB0_235
	s_waitcnt vmcnt(8)
	s_branch .LBB0_235

; #define PG8_STAGE(bufoff, gbase, voff) do { _Pragma("unroll") for (int _i = 0; _i < 2; ++_i) \
;         __builtin_amdgcn_global_load_lds((const unsigned*)((const char*)(gbase) + (voff)[_i]), (PG8_LAS unsigned*)(lds + (bufoff) + ldsw + _i * 8192), 16, 0, 0); } while (0)
; #define PG8_LDA(dst, b, h) do { _Pragma("unroll") for (int m = 0; m < 4; ++m) _Pragma("unroll") for (int k = 0; k < 2; ++k) dst[m][k] = *(const PG8_LAS bf16x8*)(lds + PG8_SA(b, h) + aoff + m * 2048 + k * 1024); } while (0)
; #define PG8_LDB(dst, b, h) do { _Pragma("unroll") for (int n = 0; n < 2; ++n) _Pragma("unroll") for (int k = 0; k < 2; ++k) dst[n][k] = *(const PG8_LAS bf16x8*)(lds + PG8_SB(b, h) + boff + n * 2048 + k * 1024); } while (0)
; #define PG8_MMA(ai, bj, At, Bt) do { __builtin_amdgcn_s_setprio(1); _Pragma("unroll") for (int m = 0; m < 4; ++m) _Pragma("unroll") for (int n = 0; n < 2; ++n) _Pragma("unroll") for (int k = 0; k < 2; ++k) \
;         acc[ai][bj][m][n] = __builtin_amdgcn_mfma_f32_16x16x32_bf16(Bt[n][k], At[m][k], acc[ai][bj][m][n], 0, 0, 0); __builtin_amdgcn_s_setprio(0); } while (0)
; #define PG8_WAIT_V(n) asm volatile("s_waitcnt vmcnt(" #n ")" ::: "memory")
; #define PG8_WAIT_VN(n) asm volatile("s_waitcnt vmcnt(%0)" :: "n"(n) : "memory")
; #define PG8_WAIT_L(n) asm volatile("s_waitcnt lgkmcnt(" #n ")" ::: "memory")
; #define PG8_BAR __builtin_amdgcn_s_barrier()
; #define PG8_SCHED __builtin_amdgcn_sched_barrier(0)
; template <class Epi, class Sched, bool ALIGN_EPI = false, bool SP2 = false>
; __device__ __forceinline__ void gemm_phase(PG8_LAS unsigned char* lds, const Gemm g, const Sched& S, const Epi& E, const int wave_id) {
;     ...
;             PG8_WAIT_VN(8 + Epi::NS); if (strict) PG8_WAIT_V(8); PG8_WAIT_L(0); PG8_BAR; PG8_MMA(1, 0, At, B0); PG8_MMA(1, 1, At, B1); PG8_BAR; PG8_SCHED;
;             PG8_LDB(B0, 1, 0); PG8_LDB(B1, 1, 1); PG8_SCHED; PG8_LDA(At, 1, 0); PG8_STAGE(PG8_SA(0, 1), a2 + hstep, voffA);
;             PG8_WAIT_V(8); PG8_WAIT_L(0); PG8_BAR; PG8_MMA(0, 0, At, B0); PG8_MMA(0, 1, At, B1); PG8_BAR; PG8_SCHED;
.LBB0_304:
	s_waitcnt lgkmcnt(0)
	s_setprio 1
	s_barrier
	v_mfma_f32_16x16x32_bf16 v[62:65], v[146:149], v[186:189], v[62:65]
	v_mfma_f32_16x16x32_bf16 v[58:61], v[154:157], v[186:189], v[58:61]
	v_mfma_f32_16x16x32_bf16 v[54:57], v[146:149], v[178:181], v[54:57]
	v_mfma_f32_16x16x32_bf16 v[50:53], v[154:157], v[178:181], v[50:53]
	v_mfma_f32_16x16x32_bf16 v[42:45], v[146:149], v[170:173], v[42:45]
	v_mfma_f32_16x16x32_bf16 v[34:37], v[154:157], v[170:173], v[34:37]
	v_mfma_f32_16x16x32_bf16 v[26:29], v[146:149], v[162:165], v[26:29]
	v_mfma_f32_16x16x32_bf16 v[18:21], v[154:157], v[162:165], v[18:21]
	v_mfma_f32_16x16x32_bf16 v[62:65], v[150:153], v[190:193], v[62:65]
	v_mfma_f32_16x16x32_bf16 v[58:61], v[158:161], v[190:193], v[58:61]
	v_mfma_f32_16x16x32_bf16 v[54:57], v[150:153], v[182:185], v[54:57]
	v_mfma_f32_16x16x32_bf16 v[50:53], v[158:161], v[182:185], v[50:53]
	v_mfma_f32_16x16x32_bf16 v[42:45], v[150:153], v[174:177], v[42:45]
	v_mfma_f32_16x16x32_bf16 v[34:37], v[158:161], v[174:177], v[34:37]
	v_mfma_f32_16x16x32_bf16 v[26:29], v[150:153], v[166:169], v[26:29]
	v_mfma_f32_16x16x32_bf16 v[18:21], v[158:161], v[166:169], v[18:21]
	v_mfma_f32_16x16x32_bf16 v[46:49], v[130:133], v[186:189], v[46:49]
	v_mfma_f32_16x16x32_bf16 v[38:41], v[138:141], v[186:189], v[38:41]
	v_mfma_f32_16x16x32_bf16 v[30:33], v[130:133], v[178:181], v[30:33]
	v_mfma_f32_16x16x32_bf16 v[22:25], v[138:141], v[178:181], v[22:25]
	v_mfma_f32_16x16x32_bf16 v[14:17], v[130:133], v[170:173], v[14:17]
	v_mfma_f32_16x16x32_bf16 v[10:13], v[138:141], v[170:173], v[10:13]
	v_mfma_f32_16x16x32_bf16 v[6:9], v[130:133], v[162:165], v[6:9]
	v_mfma_f32_16x16x32_bf16 v[2:5], v[138:141], v[162:165], v[2:5]
	v_mfma_f32_16x16x32_bf16 v[46:49], v[134:137], v[190:193], v[46:49]
	v_mfma_f32_16x16x32_bf16 v[38:41], v[142:145], v[190:193], v[38:41]
	v_mfma_f32_16x16x32_bf16 v[30:33], v[134:137], v[182:185], v[30:33]
	v_mfma_f32_16x16x32_bf16 v[22:25], v[142:145], v[182:185], v[22:25]
	v_mfma_f32_16x16x32_bf16 v[14:17], v[134:137], v[174:177], v[14:17]
	v_mfma_f32_16x16x32_bf16 v[10:13], v[142:145], v[174:177], v[10:13]
	v_mfma_f32_16x16x32_bf16 v[6:9], v[134:137], v[166:169], v[6:9]
	v_mfma_f32_16x16x32_bf16 v[2:5], v[142:145], v[166:169], v[2:5]
	s_setprio 0
	s_barrier
	s_add_i32 s16, 0, 0x18000
	s_add_i32 s17, 0, 0x1c000
	v_add_u32_e32 v142, s16, v231
	v_add_u32_e32 v158, s17, v231
	ds_read_b128 v[130:133], v142
	ds_read_b128 v[134:137], v142 offset:1024
	ds_read_b128 v[138:141], v142 offset:2048
	ds_read_b128 v[142:145], v142 offset:3072
	ds_read_b128 v[146:149], v158
	ds_read_b128 v[150:153], v158 offset:1024
	ds_read_b128 v[154:157], v158 offset:2048
	ds_read_b128 v[158:161], v158 offset:3072
	s_add_u32 s14, s14, 0xb0000
	s_addc_u32 s15, s15, 0
	s_mov_b32 m0, s29
	v_lshl_add_u64 v[194:195], s[14:15], 0, v[216:217]
	ds_read_b128 v[162:165], v232 offset:32768
	ds_read_b128 v[166:169], v232 offset:33792
	ds_read_b128 v[170:173], v232 offset:34816
	ds_read_b128 v[174:177], v232 offset:35840
	ds_read_b128 v[178:181], v232 offset:36864
	ds_read_b128 v[182:185], v232 offset:37888
	ds_read_b128 v[186:189], v232 offset:38912
	ds_read_b128 v[190:193], v232 offset:39936
	global_load_lds_dwordx4 v[194:195], off
	v_lshl_add_u64 v[194:195], s[14:15], 0, v[212:213]
	s_mov_b32 m0, s30
	s_nop 0
	global_load_lds_dwordx4 v[194:195], off
	s_waitcnt vmcnt(8)
	s_waitcnt lgkmcnt(0)
	s_setprio 1
	s_barrier
	v_mfma_f32_16x16x32_bf16 v[126:129], v[130:133], v[162:165], v[126:129]
	v_mfma_f32_16x16x32_bf16 v[122:125], v[138:141], v[162:165], v[122:125]
	v_mfma_f32_16x16x32_bf16 v[118:121], v[130:133], v[170:173], v[118:121]
	v_mfma_f32_16x16x32_bf16 v[114:117], v[138:141], v[170:173], v[114:117]
	v_mfma_f32_16x16x32_bf16 v[110:113], v[130:133], v[178:181], v[110:113]
	v_mfma_f32_16x16x32_bf16 v[102:105], v[138:141], v[178:181], v[102:105]
	v_mfma_f32_16x16x32_bf16 v[94:97], v[130:133], v[186:189], v[94:97]
	v_mfma_f32_16x16x32_bf16 v[86:89], v[138:141], v[186:189], v[86:89]
	v_mfma_f32_16x16x32_bf16 v[126:129], v[134:137], v[166:169], v[126:129]
	v_mfma_f32_16x16x32_bf16 v[122:125], v[142:145], v[166:169], v[122:125]
	v_mfma_f32_16x16x32_bf16 v[118:121], v[134:137], v[174:177], v[118:121]
	v_mfma_f32_16x16x32_bf16 v[114:117], v[142:145], v[174:177], v[114:117]
	v_mfma_f32_16x16x32_bf16 v[110:113], v[134:137], v[182:185], v[110:113]
	v_mfma_f32_16x16x32_bf16 v[102:105], v[142:145], v[182:185], v[102:105]
	v_mfma_f32_16x16x32_bf16 v[94:97], v[134:137], v[190:193], v[94:97]
	v_mfma_f32_16x16x32_bf16 v[86:89], v[142:145], v[190:193], v[86:89]
	v_mfma_f32_16x16x32_bf16 v[106:109], v[146:149], v[162:165], v[106:109]
	v_mfma_f32_16x16x32_bf16 v[98:101], v[154:157], v[162:165], v[98:101]
	v_mfma_f32_16x16x32_bf16 v[90:93], v[146:149], v[170:173], v[90:93]
	v_mfma_f32_16x16x32_bf16 v[82:85], v[154:157], v[170:173], v[82:85]
	v_mfma_f32_16x16x32_bf16 v[78:81], v[146:149], v[178:181], v[78:81]
	v_mfma_f32_16x16x32_bf16 v[74:77], v[154:157], v[178:181], v[74:77]
	v_mfma_f32_16x16x32_bf16 v[70:73], v[146:149], v[186:189], v[70:73]
	v_mfma_f32_16x16x32_bf16 v[66:69], v[154:157], v[186:189], v[66:69]
	v_mfma_f32_16x16x32_bf16 v[106:109], v[150:153], v[166:169], v[106:109]
	v_mfma_f32_16x16x32_bf16 v[98:101], v[158:161], v[166:169], v[98:101]
	v_mfma_f32_16x16x32_bf16 v[90:93], v[150:153], v[174:177], v[90:93]
	v_mfma_f32_16x16x32_bf16 v[82:85], v[158:161], v[174:177], v[82:85]
	v_mfma_f32_16x16x32_bf16 v[78:81], v[150:153], v[182:185], v[78:81]
	v_mfma_f32_16x16x32_bf16 v[74:77], v[158:161], v[182:185], v[74:77]
	v_mfma_f32_16x16x32_bf16 v[70:73], v[150:153], v[190:193], v[70:73]
	v_mfma_f32_16x16x32_bf16 v[66:69], v[158:161], v[190:193], v[66:69]
	s_setprio 0
	s_barrier
; #define PG8_STAGE(bufoff, gbase, voff) do { _Pragma("unroll") for (int _i = 0; _i < 2; ++_i) \
;         __builtin_amdgcn_global_load_lds((const unsigned*)((const char*)(gbase) + (voff)[_i]), (PG8_LAS unsigned*)(lds + (bufoff) + ldsw + _i * 8192), 16, 0, 0); } while (0)
; #define PG8_LDA(dst, b, h) do { _Pragma("unroll") for (int m = 0; m < 4; ++m) _Pragma("unroll") for (int k = 0; k < 2; ++k) dst[m][k] = *(const PG8_LAS bf16x8*)(lds + PG8_SA(b, h) + aoff + m * 2048 + k * 1024); } while (0)
; #define PG8_MMA(ai, bj, At, Bt) do { __builtin_amdgcn_s_setprio(1); _Pragma("unroll") for (int m = 0; m < 4; ++m) _Pragma("unroll") for (int n = 0; n < 2; ++n) _Pragma("unroll") for (int k = 0; k < 2; ++k) \
;         acc[ai][bj][m][n] = __builtin_amdgcn_mfma_f32_16x16x32_bf16(Bt[n][k], At[m][k], acc[ai][bj][m][n], 0, 0, 0); __builtin_amdgcn_s_setprio(0); } while (0)
; #define PG8_WAIT_V(n) asm volatile("s_waitcnt vmcnt(" #n ")" ::: "memory")
; #define PG8_WAIT_L(n) asm volatile("s_waitcnt lgkmcnt(" #n ")" ::: "memory")
; #define PG8_BAR __builtin_amdgcn_s_barrier()
; #define PG8_SCHED __builtin_amdgcn_sched_barrier(0)
; template <class Epi, class Sched, bool ALIGN_EPI = false, bool SP2 = false>
; __device__ __forceinline__ void gemm_phase(PG8_LAS unsigned char* lds, const Gemm g, const Sched& S, const Epi& E, const int wave_id) {
;     ...
;             PG8_LDA(At, 1, 1); PG8_STAGE(PG8_SB(1, 0), b3, voffB); PG8_STAGE(PG8_SB(1, 1), b3 + hstep, voffB); PG8_STAGE(PG8_SA(1, 0), a3, voffA);
;             PG8_WAIT_V(8); PG8_WAIT_L(0); PG8_BAR; PG8_MMA(1, 0, At, B0); PG8_MMA(1, 1, At, B1); PG8_BAR; PG8_SCHED;
	s_add_i32 s14, s16, s21
	v_lshl_add_u64 v[194:195], v[228:229], 0, s[64:65]
	s_mov_b32 m0, s14
	ds_read_b128 v[162:165], v232 offset:49152
	ds_read_b128 v[166:169], v232 offset:50176
	ds_read_b128 v[170:173], v232 offset:51200
	ds_read_b128 v[174:177], v232 offset:52224
	ds_read_b128 v[178:181], v232 offset:53248
	ds_read_b128 v[182:185], v232 offset:54272
	ds_read_b128 v[186:189], v232 offset:55296
	ds_read_b128 v[190:193], v232 offset:56320
	global_load_lds_dwordx4 v[194:195], off
	s_add_i32 m0, s14, 0x2000
	s_add_u32 s12, s12, 0xb0080
	v_lshl_add_u64 v[194:195], v[226:227], 0, s[64:65]
	s_addc_u32 s13, s13, 0
	s_add_i32 s14, s17, s21
	global_load_lds_dwordx4 v[194:195], off
	v_lshl_add_u64 v[194:195], s[12:13], 0, v[214:215]
	s_mov_b32 m0, s14
	s_nop 0
	global_load_lds_dwordx4 v[194:195], off
	v_lshl_add_u64 v[194:195], s[12:13], 0, v[210:211]
	s_add_i32 m0, s14, 0x2000
	s_nop 0
	global_load_lds_dwordx4 v[194:195], off
	v_lshl_add_u64 v[194:195], v[222:223], 0, s[64:65]
	s_mov_b32 m0, s31
	s_nop 0
	global_load_lds_dwordx4 v[194:195], off
	v_lshl_add_u64 v[194:195], v[224:225], 0, s[64:65]
	s_mov_b32 m0, s34
	s_nop 0
	global_load_lds_dwordx4 v[194:195], off
	s_waitcnt vmcnt(8)
	s_waitcnt lgkmcnt(0)
	s_setprio 1
	s_barrier
	v_mfma_f32_16x16x32_bf16 v[62:65], v[130:133], v[162:165], v[62:65]
	v_mfma_f32_16x16x32_bf16 v[58:61], v[138:141], v[162:165], v[58:61]
	v_mfma_f32_16x16x32_bf16 v[54:57], v[130:133], v[170:173], v[54:57]
	v_mfma_f32_16x16x32_bf16 v[50:53], v[138:141], v[170:173], v[50:53]
	v_mfma_f32_16x16x32_bf16 v[42:45], v[130:133], v[178:181], v[42:45]
	v_mfma_f32_16x16x32_bf16 v[34:37], v[138:141], v[178:181], v[34:37]
	v_mfma_f32_16x16x32_bf16 v[26:29], v[130:133], v[186:189], v[26:29]
	v_mfma_f32_16x16x32_bf16 v[18:21], v[138:141], v[186:189], v[18:21]
	v_mfma_f32_16x16x32_bf16 v[62:65], v[134:137], v[166:169], v[62:65]
	v_mfma_f32_16x16x32_bf16 v[58:61], v[142:145], v[166:169], v[58:61]
	v_mfma_f32_16x16x32_bf16 v[54:57], v[134:137], v[174:177], v[54:57]
	v_mfma_f32_16x16x32_bf16 v[50:53], v[142:145], v[174:177], v[50:53]
	v_mfma_f32_16x16x32_bf16 v[42:45], v[134:137], v[182:185], v[42:45]
	v_mfma_f32_16x16x32_bf16 v[34:37], v[142:145], v[182:185], v[34:37]
	v_mfma_f32_16x16x32_bf16 v[26:29], v[134:137], v[190:193], v[26:29]
	v_mfma_f32_16x16x32_bf16 v[18:21], v[142:145], v[190:193], v[18:21]
	v_mfma_f32_16x16x32_bf16 v[46:49], v[146:149], v[162:165], v[46:49]
	v_mfma_f32_16x16x32_bf16 v[38:41], v[154:157], v[162:165], v[38:41]
	v_mfma_f32_16x16x32_bf16 v[30:33], v[146:149], v[170:173], v[30:33]
	v_mfma_f32_16x16x32_bf16 v[22:25], v[154:157], v[170:173], v[22:25]
	v_mfma_f32_16x16x32_bf16 v[14:17], v[146:149], v[178:181], v[14:17]
	v_mfma_f32_16x16x32_bf16 v[10:13], v[154:157], v[178:181], v[10:13]
	v_mfma_f32_16x16x32_bf16 v[6:9], v[146:149], v[186:189], v[6:9]
	v_mfma_f32_16x16x32_bf16 v[2:5], v[154:157], v[186:189], v[2:5]
	v_mfma_f32_16x16x32_bf16 v[46:49], v[150:153], v[166:169], v[46:49]
	v_mfma_f32_16x16x32_bf16 v[38:41], v[158:161], v[166:169], v[38:41]
	v_mfma_f32_16x16x32_bf16 v[30:33], v[150:153], v[174:177], v[30:33]
	v_mfma_f32_16x16x32_bf16 v[22:25], v[158:161], v[174:177], v[22:25]
	v_mfma_f32_16x16x32_bf16 v[14:17], v[150:153], v[182:185], v[14:17]
	v_mfma_f32_16x16x32_bf16 v[10:13], v[158:161], v[182:185], v[10:13]
	v_mfma_f32_16x16x32_bf16 v[6:9], v[150:153], v[190:193], v[6:9]
	v_mfma_f32_16x16x32_bf16 v[2:5], v[158:161], v[190:193], v[2:5]
	s_setprio 0
	s_barrier
	s_add_u32 s10, s10, 0x100
	s_addc_u32 s11, s11, 0
	s_cmp_gt_u32 s39, 19
	v_readlane_b32 s40, v254, 55
	s_cbranch_scc1 .LBB0_309

; #define PG8_STAGE(bufoff, gbase, voff) do { _Pragma("unroll") for (int _i = 0; _i < 2; ++_i) \
;         __builtin_amdgcn_global_load_lds((const unsigned*)((const char*)(gbase) + (voff)[_i]), (PG8_LAS unsigned*)(lds + (bufoff) + ldsw + _i * 8192), 16, 0, 0); } while (0)
; #define PG8_LDA(dst, b, h) do { _Pragma("unroll") for (int m = 0; m < 4; ++m) _Pragma("unroll") for (int k = 0; k < 2; ++k) dst[m][k] = *(const PG8_LAS bf16x8*)(lds + PG8_SA(b, h) + aoff + m * 2048 + k * 1024); } while (0)
; #define PG8_LDB(dst, b, h) do { _Pragma("unroll") for (int n = 0; n < 2; ++n) _Pragma("unroll") for (int k = 0; k < 2; ++k) dst[n][k] = *(const PG8_LAS bf16x8*)(lds + PG8_SB(b, h) + boff + n * 2048 + k * 1024); } while (0)
; #define PG8_WAIT_V(n) asm volatile("s_waitcnt vmcnt(" #n ")" ::: "memory")
; #define PG8_WAIT_VN(n) asm volatile("s_waitcnt vmcnt(%0)" :: "n"(n) : "memory")
; #define PG8_WAIT_L(n) asm volatile("s_waitcnt lgkmcnt(" #n ")" ::: "memory")
; #define PG8_BAR __builtin_amdgcn_s_barrier()
; #define PG8_SCHED __builtin_amdgcn_sched_barrier(0)
; template <class Epi, class Sched, bool ALIGN_EPI = false, bool SP2 = false>
; __device__ __forceinline__ void gemm_phase(PG8_LAS unsigned char* lds, const Gemm g, const Sched& S, const Epi& E, const int wave_id) {
;     ...
;             const char* a1 = cA + (size_t)(t + 1) * kstep;
;             const char* a2 = last ? nA : cA + (size_t)(t + 2) * kstep; const char* b2 = last ? nB : cB + (size_t)(t + 2) * kstep;
;             const char* a3 = a2 + kstep; const char* b3 = b2 + kstep;
;             if (last && has_next) S.a_ready(nxt);
;             if constexpr (SP2) {
;             int tz_ = __builtin_amdgcn_readfirstlane(t | (ui > 0 ? 0 : 1)); asm volatile("" : "+s"(tz_));
;             const bool strict = !(Epi::NS > 0 && tz_ == 0);
;             PG8_LDB(B0, 0, 0); PG8_LDB(B1, 0, 1); PG8_SCHED; PG8_LDA(At, 0, 0); PG8_STAGE(PG8_SA(1, 1), a1 + hstep, voffA);
;             PG8_WAIT_VN(8 + Epi::NS); if (strict) PG8_WAIT_V(8); PG8_WAIT_L(0); PG8_BAR; PG8_MMA(0, 0, At, B0); PG8_MMA(0, 1, At, B1); PG8_BAR; PG8_SCHED;
;             PG8_LDA(At, 0, 1); PG8_STAGE(PG8_SB(0, 0), b2, voffB); PG8_STAGE(PG8_SB(0, 1), b2 + hstep, voffB); PG8_STAGE(PG8_SA(0, 0), a2, voffA);
;             PG8_WAIT_VN(8 + Epi::NS); if (strict) PG8_WAIT_V(8); PG8_WAIT_L(0); PG8_BAR; PG8_MMA(1, 0, At, B0); PG8_MMA(1, 1, At, B1); PG8_BAR; PG8_SCHED;
.LBB0_307:
	s_add_u32 s12, s37, s10
	s_addc_u32 s13, s38, s11
	s_add_u32 s12, s12, 0x26300100
	s_addc_u32 s13, s13, 0
	s_add_u32 s40, s35, s10
	s_addc_u32 s41, s36, s11
	s_cmpk_eq_i32 s10, 0xa00
	s_cselect_b32 s15, s9, s13
	s_cselect_b32 s14, s8, s12
	s_cselect_b32 s13, s7, s41
	s_cselect_b32 s12, s6, s40
	s_waitcnt lgkmcnt(0)
	s_setprio 1
	s_barrier
	v_mfma_f32_16x16x32_bf16 v[126:129], v[146:149], v[186:189], v[126:129]
	v_mfma_f32_16x16x32_bf16 v[122:125], v[154:157], v[186:189], v[122:125]
	v_mfma_f32_16x16x32_bf16 v[118:121], v[146:149], v[178:181], v[118:121]
	v_mfma_f32_16x16x32_bf16 v[114:117], v[154:157], v[178:181], v[114:117]
	v_mfma_f32_16x16x32_bf16 v[110:113], v[146:149], v[170:173], v[110:113]
	v_mfma_f32_16x16x32_bf16 v[102:105], v[154:157], v[170:173], v[102:105]
	v_mfma_f32_16x16x32_bf16 v[94:97], v[146:149], v[162:165], v[94:97]
	v_mfma_f32_16x16x32_bf16 v[86:89], v[154:157], v[162:165], v[86:89]
	v_mfma_f32_16x16x32_bf16 v[126:129], v[150:153], v[190:193], v[126:129]
	v_mfma_f32_16x16x32_bf16 v[122:125], v[158:161], v[190:193], v[122:125]
	v_mfma_f32_16x16x32_bf16 v[118:121], v[150:153], v[182:185], v[118:121]
	v_mfma_f32_16x16x32_bf16 v[114:117], v[158:161], v[182:185], v[114:117]
	v_mfma_f32_16x16x32_bf16 v[110:113], v[150:153], v[174:177], v[110:113]
	v_mfma_f32_16x16x32_bf16 v[102:105], v[158:161], v[174:177], v[102:105]
	v_mfma_f32_16x16x32_bf16 v[94:97], v[150:153], v[166:169], v[94:97]
	v_mfma_f32_16x16x32_bf16 v[86:89], v[158:161], v[166:169], v[86:89]
	v_mfma_f32_16x16x32_bf16 v[106:109], v[130:133], v[186:189], v[106:109]
	v_mfma_f32_16x16x32_bf16 v[98:101], v[138:141], v[186:189], v[98:101]
	v_mfma_f32_16x16x32_bf16 v[90:93], v[130:133], v[178:181], v[90:93]
	v_mfma_f32_16x16x32_bf16 v[82:85], v[138:141], v[178:181], v[82:85]
	v_mfma_f32_16x16x32_bf16 v[78:81], v[130:133], v[170:173], v[78:81]
	v_mfma_f32_16x16x32_bf16 v[74:77], v[138:141], v[170:173], v[74:77]
	v_mfma_f32_16x16x32_bf16 v[70:73], v[130:133], v[162:165], v[70:73]
	v_mfma_f32_16x16x32_bf16 v[66:69], v[138:141], v[162:165], v[66:69]
	v_mfma_f32_16x16x32_bf16 v[106:109], v[134:137], v[190:193], v[106:109]
	v_mfma_f32_16x16x32_bf16 v[98:101], v[142:145], v[190:193], v[98:101]
	v_mfma_f32_16x16x32_bf16 v[90:93], v[134:137], v[182:185], v[90:93]
	v_mfma_f32_16x16x32_bf16 v[82:85], v[142:145], v[182:185], v[82:85]
	v_mfma_f32_16x16x32_bf16 v[78:81], v[134:137], v[174:177], v[78:81]
	v_mfma_f32_16x16x32_bf16 v[74:77], v[142:145], v[174:177], v[74:77]
	v_mfma_f32_16x16x32_bf16 v[70:73], v[134:137], v[166:169], v[70:73]
	v_mfma_f32_16x16x32_bf16 v[66:69], v[142:145], v[166:169], v[66:69]
	s_setprio 0
	s_barrier
	s_mov_b32 m0, s23
	v_lshl_add_u64 v[228:229], s[12:13], 0, v[214:215]
	s_add_u32 s40, s12, 0xb0000
	ds_read_b128 v[186:189], v232 offset:16384
	ds_read_b128 v[190:193], v232 offset:17408
	ds_read_b128 v[178:181], v232 offset:18432
	ds_read_b128 v[182:185], v232 offset:19456
	ds_read_b128 v[170:173], v232 offset:20480
	ds_read_b128 v[174:177], v232 offset:21504
	ds_read_b128 v[162:165], v232 offset:22528
	ds_read_b128 v[166:169], v232 offset:23552
	global_load_lds_dwordx4 v[228:229], off
	v_lshl_add_u64 v[226:227], s[12:13], 0, v[210:211]
	s_mov_b32 m0, s24
	s_addc_u32 s41, s13, 0
	global_load_lds_dwordx4 v[226:227], off
	v_lshl_add_u64 v[194:195], s[40:41], 0, v[214:215]
	s_mov_b32 m0, s25
	v_lshl_add_u64 v[222:223], s[14:15], 0, v[216:217]
	global_load_lds_dwordx4 v[194:195], off
	v_lshl_add_u64 v[194:195], s[40:41], 0, v[210:211]
	s_mov_b32 m0, s26
	v_lshl_add_u64 v[224:225], s[14:15], 0, v[212:213]
	global_load_lds_dwordx4 v[194:195], off
	s_mov_b32 m0, s22
	s_andn2_b64 vcc, exec, s[16:17]
	global_load_lds_dwordx4 v[222:223], off
	s_mov_b32 m0, s28
	s_nop 0
	global_load_lds_dwordx4 v[224:225], off
	s_waitcnt vmcnt(24)
	s_cbranch_vccnz .LBB0_304
	s_waitcnt vmcnt(8)
	s_branch .LBB0_304

; #define PG8_STAGE(bufoff, gbase, voff) do { _Pragma("unroll") for (int _i = 0; _i < 2; ++_i) \
;         __builtin_amdgcn_global_load_lds((const unsigned*)((const char*)(gbase) + (voff)[_i]), (PG8_LAS unsigned*)(lds + (bufoff) + ldsw + _i * 8192), 16, 0, 0); } while (0)
; #define PG8_LDA(dst, b, h) do { _Pragma("unroll") for (int m = 0; m < 4; ++m) _Pragma("unroll") for (int k = 0; k < 2; ++k) dst[m][k] = *(const PG8_LAS bf16x8*)(lds + PG8_SA(b, h) + aoff + m * 2048 + k * 1024); } while (0)
; #define PG8_LDB(dst, b, h) do { _Pragma("unroll") for (int n = 0; n < 2; ++n) _Pragma("unroll") for (int k = 0; k < 2; ++k) dst[n][k] = *(const PG8_LAS bf16x8*)(lds + PG8_SB(b, h) + boff + n * 2048 + k * 1024); } while (0)
; #define PG8_MMA(ai, bj, At, Bt) do { __builtin_amdgcn_s_setprio(1); _Pragma("unroll") for (int m = 0; m < 4; ++m) _Pragma("unroll") for (int n = 0; n < 2; ++n) _Pragma("unroll") for (int k = 0; k < 2; ++k) \
;         acc[ai][bj][m][n] = __builtin_amdgcn_mfma_f32_16x16x32_bf16(Bt[n][k], At[m][k], acc[ai][bj][m][n], 0, 0, 0); __builtin_amdgcn_s_setprio(0); } while (0)
; #define PG8_WAIT_V(n) asm volatile("s_waitcnt vmcnt(" #n ")" ::: "memory")
; #define PG8_WAIT_VN(n) asm volatile("s_waitcnt vmcnt(%0)" :: "n"(n) : "memory")
; #define PG8_WAIT_L(n) asm volatile("s_waitcnt lgkmcnt(" #n ")" ::: "memory")
; #define PG8_BAR __builtin_amdgcn_s_barrier()
; #define PG8_SCHED __builtin_amdgcn_sched_barrier(0)
; template <class Epi, class Sched, bool ALIGN_EPI = false, bool SP2 = false>
; __device__ __forceinline__ void gemm_phase(PG8_LAS unsigned char* lds, const Gemm g, const Sched& S, const Epi& E, const int wave_id) {
;     ...
;             PG8_WAIT_VN(8 + Epi::NS); if (strict) PG8_WAIT_V(8); PG8_WAIT_L(0); PG8_BAR; PG8_MMA(1, 0, At, B0); PG8_MMA(1, 1, At, B1); PG8_BAR; PG8_SCHED;
;             PG8_LDB(B0, 1, 0); PG8_LDB(B1, 1, 1); PG8_SCHED; PG8_LDA(At, 1, 0); PG8_STAGE(PG8_SA(0, 1), a2 + hstep, voffA);
;             PG8_WAIT_V(8); PG8_WAIT_L(0); PG8_BAR; PG8_MMA(0, 0, At, B0); PG8_MMA(0, 1, At, B1); PG8_BAR; PG8_SCHED;
.LBB0_420:
	s_waitcnt lgkmcnt(0)
	s_setprio 1
	s_barrier
	v_mfma_f32_16x16x32_bf16 v[62:65], v[146:149], v[186:189], v[62:65]
	v_mfma_f32_16x16x32_bf16 v[58:61], v[154:157], v[186:189], v[58:61]
	v_mfma_f32_16x16x32_bf16 v[46:49], v[146:149], v[178:181], v[46:49]
	v_mfma_f32_16x16x32_bf16 v[42:45], v[154:157], v[178:181], v[42:45]
	v_mfma_f32_16x16x32_bf16 v[30:33], v[146:149], v[170:173], v[30:33]
	v_mfma_f32_16x16x32_bf16 v[26:29], v[154:157], v[170:173], v[26:29]
	v_mfma_f32_16x16x32_bf16 v[14:17], v[146:149], v[162:165], v[14:17]
	v_mfma_f32_16x16x32_bf16 v[10:13], v[154:157], v[162:165], v[10:13]
	v_mfma_f32_16x16x32_bf16 v[62:65], v[150:153], v[190:193], v[62:65]
	v_mfma_f32_16x16x32_bf16 v[58:61], v[158:161], v[190:193], v[58:61]
	v_mfma_f32_16x16x32_bf16 v[46:49], v[150:153], v[182:185], v[46:49]
	v_mfma_f32_16x16x32_bf16 v[42:45], v[158:161], v[182:185], v[42:45]
	v_mfma_f32_16x16x32_bf16 v[30:33], v[150:153], v[174:177], v[30:33]
	v_mfma_f32_16x16x32_bf16 v[26:29], v[158:161], v[174:177], v[26:29]
	v_mfma_f32_16x16x32_bf16 v[14:17], v[150:153], v[166:169], v[14:17]
	v_mfma_f32_16x16x32_bf16 v[10:13], v[158:161], v[166:169], v[10:13]
	v_mfma_f32_16x16x32_bf16 v[54:57], v[130:133], v[186:189], v[54:57]
	v_mfma_f32_16x16x32_bf16 v[50:53], v[138:141], v[186:189], v[50:53]
	v_mfma_f32_16x16x32_bf16 v[38:41], v[130:133], v[178:181], v[38:41]
	v_mfma_f32_16x16x32_bf16 v[34:37], v[138:141], v[178:181], v[34:37]
	v_mfma_f32_16x16x32_bf16 v[22:25], v[130:133], v[170:173], v[22:25]
	v_mfma_f32_16x16x32_bf16 v[18:21], v[138:141], v[170:173], v[18:21]
	v_mfma_f32_16x16x32_bf16 v[6:9], v[130:133], v[162:165], v[6:9]
	v_mfma_f32_16x16x32_bf16 v[2:5], v[138:141], v[162:165], v[2:5]
	v_mfma_f32_16x16x32_bf16 v[54:57], v[134:137], v[190:193], v[54:57]
	v_mfma_f32_16x16x32_bf16 v[50:53], v[142:145], v[190:193], v[50:53]
	v_mfma_f32_16x16x32_bf16 v[38:41], v[134:137], v[182:185], v[38:41]
	v_mfma_f32_16x16x32_bf16 v[34:37], v[142:145], v[182:185], v[34:37]
	v_mfma_f32_16x16x32_bf16 v[22:25], v[134:137], v[174:177], v[22:25]
	v_mfma_f32_16x16x32_bf16 v[18:21], v[142:145], v[174:177], v[18:21]
	v_mfma_f32_16x16x32_bf16 v[6:9], v[134:137], v[166:169], v[6:9]
	v_mfma_f32_16x16x32_bf16 v[2:5], v[142:145], v[166:169], v[2:5]
	s_setprio 0
	s_barrier
	s_add_i32 s34, 0, 0x18000
	s_add_i32 s35, 0, 0x1c000
	v_add_u32_e32 v142, s34, v246
	v_add_u32_e32 v158, s35, v246
	ds_read_b128 v[130:133], v142
	ds_read_b128 v[134:137], v142 offset:1024
	ds_read_b128 v[138:141], v142 offset:2048
	ds_read_b128 v[142:145], v142 offset:3072
	ds_read_b128 v[146:149], v158
	ds_read_b128 v[150:153], v158 offset:1024
	ds_read_b128 v[154:157], v158 offset:2048
	ds_read_b128 v[158:161], v158 offset:3072
	s_add_u32 s14, s14, 0x40000
	s_addc_u32 s15, s15, 0
	s_mov_b32 m0, s3
	v_lshl_add_u64 v[194:195], s[14:15], 0, v[210:211]
	ds_read_b128 v[162:165], v247 offset:32768
	ds_read_b128 v[166:169], v247 offset:33792
	ds_read_b128 v[170:173], v247 offset:34816
	ds_read_b128 v[174:177], v247 offset:35840
	ds_read_b128 v[178:181], v247 offset:36864
	ds_read_b128 v[182:185], v247 offset:37888
	ds_read_b128 v[186:189], v247 offset:38912
	ds_read_b128 v[190:193], v247 offset:39936
	global_load_lds_dwordx4 v[194:195], off
	v_lshl_add_u64 v[194:195], s[14:15], 0, v[214:215]
	s_mov_b32 m0, s4
	s_nop 0
	global_load_lds_dwordx4 v[194:195], off
	s_waitcnt vmcnt(26)
	s_cmp_eq_u32 s100, 0
	s_cbranch_scc1 .Lthird_wait_relaxed_4
	s_waitcnt vmcnt(8)
; #define PG8_STAGE(bufoff, gbase, voff) do { _Pragma("unroll") for (int _i = 0; _i < 2; ++_i) \
;         __builtin_amdgcn_global_load_lds((const unsigned*)((const char*)(gbase) + (voff)[_i]), (PG8_LAS unsigned*)(lds + (bufoff) + ldsw + _i * 8192), 16, 0, 0); } while (0)
; #define PG8_LDA(dst, b, h) do { _Pragma("unroll") for (int m = 0; m < 4; ++m) _Pragma("unroll") for (int k = 0; k < 2; ++k) dst[m][k] = *(const PG8_LAS bf16x8*)(lds + PG8_SA(b, h) + aoff + m * 2048 + k * 1024); } while (0)
; #define PG8_MMA(ai, bj, At, Bt) do { __builtin_amdgcn_s_setprio(1); _Pragma("unroll") for (int m = 0; m < 4; ++m) _Pragma("unroll") for (int n = 0; n < 2; ++n) _Pragma("unroll") for (int k = 0; k < 2; ++k) \
;         acc[ai][bj][m][n] = __builtin_amdgcn_mfma_f32_16x16x32_bf16(Bt[n][k], At[m][k], acc[ai][bj][m][n], 0, 0, 0); __builtin_amdgcn_s_setprio(0); } while (0)
; #define PG8_WAIT_V(n) asm volatile("s_waitcnt vmcnt(" #n ")" ::: "memory")
; #define PG8_WAIT_L(n) asm volatile("s_waitcnt lgkmcnt(" #n ")" ::: "memory")
; #define PG8_BAR __builtin_amdgcn_s_barrier()
; #define PG8_SCHED __builtin_amdgcn_sched_barrier(0)
; template <class Epi, class Sched, bool ALIGN_EPI = false, bool SP2 = false>
; __device__ __forceinline__ void gemm_phase(PG8_LAS unsigned char* lds, const Gemm g, const Sched& S, const Epi& E, const int wave_id) {
;     ...
;             PG8_WAIT_V(8); PG8_WAIT_L(0); PG8_BAR; PG8_MMA(0, 0, At, B0); PG8_MMA(0, 1, At, B1); PG8_BAR; PG8_SCHED;
;             PG8_LDA(At, 1, 1); PG8_STAGE(PG8_SB(1, 0), b3, voffB); PG8_STAGE(PG8_SB(1, 1), b3 + hstep, voffB); PG8_STAGE(PG8_SA(1, 0), a3, voffA);
;             PG8_WAIT_V(8); PG8_WAIT_L(0); PG8_BAR; PG8_MMA(1, 0, At, B0); PG8_MMA(1, 1, At, B1); PG8_BAR; PG8_SCHED;
.Lthird_wait_relaxed_4:
	s_waitcnt lgkmcnt(0)
	s_setprio 1
	s_barrier
	v_mfma_f32_16x16x32_bf16 v[126:129], v[130:133], v[162:165], v[126:129]
	v_mfma_f32_16x16x32_bf16 v[122:125], v[138:141], v[162:165], v[122:125]
	v_mfma_f32_16x16x32_bf16 v[110:113], v[130:133], v[170:173], v[110:113]
	v_mfma_f32_16x16x32_bf16 v[106:109], v[138:141], v[170:173], v[106:109]
	v_mfma_f32_16x16x32_bf16 v[94:97], v[130:133], v[178:181], v[94:97]
	v_mfma_f32_16x16x32_bf16 v[90:93], v[138:141], v[178:181], v[90:93]
	v_mfma_f32_16x16x32_bf16 v[78:81], v[130:133], v[186:189], v[78:81]
	v_mfma_f32_16x16x32_bf16 v[74:77], v[138:141], v[186:189], v[74:77]
	v_mfma_f32_16x16x32_bf16 v[126:129], v[134:137], v[166:169], v[126:129]
	v_mfma_f32_16x16x32_bf16 v[122:125], v[142:145], v[166:169], v[122:125]
	v_mfma_f32_16x16x32_bf16 v[110:113], v[134:137], v[174:177], v[110:113]
	v_mfma_f32_16x16x32_bf16 v[106:109], v[142:145], v[174:177], v[106:109]
	v_mfma_f32_16x16x32_bf16 v[94:97], v[134:137], v[182:185], v[94:97]
	v_mfma_f32_16x16x32_bf16 v[90:93], v[142:145], v[182:185], v[90:93]
	v_mfma_f32_16x16x32_bf16 v[78:81], v[134:137], v[190:193], v[78:81]
	v_mfma_f32_16x16x32_bf16 v[74:77], v[142:145], v[190:193], v[74:77]
	v_mfma_f32_16x16x32_bf16 v[118:121], v[146:149], v[162:165], v[118:121]
	v_mfma_f32_16x16x32_bf16 v[114:117], v[154:157], v[162:165], v[114:117]
	v_mfma_f32_16x16x32_bf16 v[102:105], v[146:149], v[170:173], v[102:105]
	v_mfma_f32_16x16x32_bf16 v[98:101], v[154:157], v[170:173], v[98:101]
	v_mfma_f32_16x16x32_bf16 v[86:89], v[146:149], v[178:181], v[86:89]
	v_mfma_f32_16x16x32_bf16 v[82:85], v[154:157], v[178:181], v[82:85]
	v_mfma_f32_16x16x32_bf16 v[70:73], v[146:149], v[186:189], v[70:73]
	v_mfma_f32_16x16x32_bf16 v[66:69], v[154:157], v[186:189], v[66:69]
	v_mfma_f32_16x16x32_bf16 v[118:121], v[150:153], v[166:169], v[118:121]
	v_mfma_f32_16x16x32_bf16 v[114:117], v[158:161], v[166:169], v[114:117]
	v_mfma_f32_16x16x32_bf16 v[102:105], v[150:153], v[174:177], v[102:105]
	v_mfma_f32_16x16x32_bf16 v[98:101], v[158:161], v[174:177], v[98:101]
	v_mfma_f32_16x16x32_bf16 v[86:89], v[150:153], v[182:185], v[86:89]
	v_mfma_f32_16x16x32_bf16 v[82:85], v[158:161], v[182:185], v[82:85]
	v_mfma_f32_16x16x32_bf16 v[70:73], v[150:153], v[190:193], v[70:73]
	v_mfma_f32_16x16x32_bf16 v[66:69], v[158:161], v[190:193], v[66:69]
	s_setprio 0
	s_barrier
	s_add_i32 s14, s34, s90
	v_lshl_add_u64 v[194:195], v[232:233], 0, s[64:65]
	s_mov_b32 m0, s14
	ds_read_b128 v[162:165], v247 offset:49152
	ds_read_b128 v[166:169], v247 offset:50176
	ds_read_b128 v[170:173], v247 offset:51200
	ds_read_b128 v[174:177], v247 offset:52224
	ds_read_b128 v[178:181], v247 offset:53248
	ds_read_b128 v[182:185], v247 offset:54272
	ds_read_b128 v[186:189], v247 offset:55296
	ds_read_b128 v[190:193], v247 offset:56320
	global_load_lds_dwordx4 v[194:195], off
	s_add_i32 m0, s14, 0x2000
	s_add_u32 s12, s12, 0x40080
	v_lshl_add_u64 v[194:195], v[230:231], 0, s[64:65]
	s_addc_u32 s13, s13, 0
	s_add_i32 s14, s35, s90
	global_load_lds_dwordx4 v[194:195], off
	v_lshl_add_u64 v[194:195], s[12:13], 0, v[212:213]
	s_mov_b32 m0, s14
	s_nop 0
	global_load_lds_dwordx4 v[194:195], off
	v_lshl_add_u64 v[194:195], s[12:13], 0, v[216:217]
	s_add_i32 m0, s14, 0x2000
	s_nop 0
	global_load_lds_dwordx4 v[194:195], off
	v_lshl_add_u64 v[194:195], v[226:227], 0, s[64:65]
	s_mov_b32 m0, s63
	s_nop 0
	global_load_lds_dwordx4 v[194:195], off
	v_lshl_add_u64 v[194:195], v[228:229], 0, s[64:65]
	s_mov_b32 m0, s68
	s_nop 0
	global_load_lds_dwordx4 v[194:195], off
	s_waitcnt vmcnt(8)
	s_waitcnt lgkmcnt(0)
	s_setprio 1
	s_barrier
	v_mfma_f32_16x16x32_bf16 v[62:65], v[130:133], v[162:165], v[62:65]
	v_mfma_f32_16x16x32_bf16 v[58:61], v[138:141], v[162:165], v[58:61]
	v_mfma_f32_16x16x32_bf16 v[46:49], v[130:133], v[170:173], v[46:49]
	v_mfma_f32_16x16x32_bf16 v[42:45], v[138:141], v[170:173], v[42:45]
	v_mfma_f32_16x16x32_bf16 v[30:33], v[130:133], v[178:181], v[30:33]
	v_mfma_f32_16x16x32_bf16 v[26:29], v[138:141], v[178:181], v[26:29]
	v_mfma_f32_16x16x32_bf16 v[14:17], v[130:133], v[186:189], v[14:17]
	v_mfma_f32_16x16x32_bf16 v[10:13], v[138:141], v[186:189], v[10:13]
	v_mfma_f32_16x16x32_bf16 v[62:65], v[134:137], v[166:169], v[62:65]
	v_mfma_f32_16x16x32_bf16 v[58:61], v[142:145], v[166:169], v[58:61]
	v_mfma_f32_16x16x32_bf16 v[46:49], v[134:137], v[174:177], v[46:49]
	v_mfma_f32_16x16x32_bf16 v[42:45], v[142:145], v[174:177], v[42:45]
	v_mfma_f32_16x16x32_bf16 v[30:33], v[134:137], v[182:185], v[30:33]
	v_mfma_f32_16x16x32_bf16 v[26:29], v[142:145], v[182:185], v[26:29]
	v_mfma_f32_16x16x32_bf16 v[14:17], v[134:137], v[190:193], v[14:17]
	v_mfma_f32_16x16x32_bf16 v[10:13], v[142:145], v[190:193], v[10:13]
	v_mfma_f32_16x16x32_bf16 v[54:57], v[146:149], v[162:165], v[54:57]
	v_mfma_f32_16x16x32_bf16 v[50:53], v[154:157], v[162:165], v[50:53]
	v_mfma_f32_16x16x32_bf16 v[38:41], v[146:149], v[170:173], v[38:41]
	v_mfma_f32_16x16x32_bf16 v[34:37], v[154:157], v[170:173], v[34:37]
	v_mfma_f32_16x16x32_bf16 v[22:25], v[146:149], v[178:181], v[22:25]
	v_mfma_f32_16x16x32_bf16 v[18:21], v[154:157], v[178:181], v[18:21]
	v_mfma_f32_16x16x32_bf16 v[6:9], v[146:149], v[186:189], v[6:9]
	v_mfma_f32_16x16x32_bf16 v[2:5], v[154:157], v[186:189], v[2:5]
	v_mfma_f32_16x16x32_bf16 v[54:57], v[150:153], v[166:169], v[54:57]
	v_mfma_f32_16x16x32_bf16 v[50:53], v[158:161], v[166:169], v[50:53]
	v_mfma_f32_16x16x32_bf16 v[38:41], v[150:153], v[174:177], v[38:41]
	v_mfma_f32_16x16x32_bf16 v[34:37], v[158:161], v[174:177], v[34:37]
	v_mfma_f32_16x16x32_bf16 v[22:25], v[150:153], v[182:185], v[22:25]
	v_mfma_f32_16x16x32_bf16 v[18:21], v[158:161], v[182:185], v[18:21]
	v_mfma_f32_16x16x32_bf16 v[6:9], v[150:153], v[190:193], v[6:9]
	v_mfma_f32_16x16x32_bf16 v[2:5], v[158:161], v[190:193], v[2:5]
	s_setprio 0
	s_barrier
	s_add_i32 s40, s40, 2
	s_add_u32 s10, s10, 0x100
	s_addc_u32 s11, s11, 0
	s_cmp_gt_u32 s40, 13
	s_cbranch_scc1 .LBB0_425

; #define PG8_STAGE(bufoff, gbase, voff) do { _Pragma("unroll") for (int _i = 0; _i < 2; ++_i) \
;         __builtin_amdgcn_global_load_lds((const unsigned*)((const char*)(gbase) + (voff)[_i]), (PG8_LAS unsigned*)(lds + (bufoff) + ldsw + _i * 8192), 16, 0, 0); } while (0)
; #define PG8_LDA(dst, b, h) do { _Pragma("unroll") for (int m = 0; m < 4; ++m) _Pragma("unroll") for (int k = 0; k < 2; ++k) dst[m][k] = *(const PG8_LAS bf16x8*)(lds + PG8_SA(b, h) + aoff + m * 2048 + k * 1024); } while (0)
; #define PG8_LDB(dst, b, h) do { _Pragma("unroll") for (int n = 0; n < 2; ++n) _Pragma("unroll") for (int k = 0; k < 2; ++k) dst[n][k] = *(const PG8_LAS bf16x8*)(lds + PG8_SB(b, h) + boff + n * 2048 + k * 1024); } while (0)
; #define PG8_WAIT_V(n) asm volatile("s_waitcnt vmcnt(" #n ")" ::: "memory")
; #define PG8_WAIT_VN(n) asm volatile("s_waitcnt vmcnt(%0)" :: "n"(n) : "memory")
; #define PG8_WAIT_L(n) asm volatile("s_waitcnt lgkmcnt(" #n ")" ::: "memory")
; #define PG8_BAR __builtin_amdgcn_s_barrier()
; #define PG8_SCHED __builtin_amdgcn_sched_barrier(0)
; template <class Epi, class Sched, bool ALIGN_EPI = false, bool SP2 = false>
; __device__ __forceinline__ void gemm_phase(PG8_LAS unsigned char* lds, const Gemm g, const Sched& S, const Epi& E, const int wave_id) {
;     ...
;             const char* a1 = cA + (size_t)(t + 1) * kstep;
;             const char* a2 = last ? nA : cA + (size_t)(t + 2) * kstep; const char* b2 = last ? nB : cB + (size_t)(t + 2) * kstep;
;             const char* a3 = a2 + kstep; const char* b3 = b2 + kstep;
;             if (last && has_next) S.a_ready(nxt);
;             if constexpr (SP2) {
;             int tz_ = __builtin_amdgcn_readfirstlane(t | (ui > 0 ? 0 : 1)); asm volatile("" : "+s"(tz_));
;             const bool strict = !(Epi::NS > 0 && tz_ == 0);
;             PG8_LDB(B0, 0, 0); PG8_LDB(B1, 0, 1); PG8_SCHED; PG8_LDA(At, 0, 0); PG8_STAGE(PG8_SA(1, 1), a1 + hstep, voffA);
;             PG8_WAIT_VN(8 + Epi::NS); if (strict) PG8_WAIT_V(8); PG8_WAIT_L(0); PG8_BAR; PG8_MMA(0, 0, At, B0); PG8_MMA(0, 1, At, B1); PG8_BAR; PG8_SCHED;
;             PG8_LDA(At, 0, 1); PG8_STAGE(PG8_SB(0, 0), b2, voffB); PG8_STAGE(PG8_SB(0, 1), b2 + hstep, voffB); PG8_STAGE(PG8_SA(0, 0), a2, voffA);
;             PG8_WAIT_VN(8 + Epi::NS); if (strict) PG8_WAIT_V(8); PG8_WAIT_L(0); PG8_BAR; PG8_MMA(1, 0, At, B0); PG8_MMA(1, 1, At, B1); PG8_BAR; PG8_SCHED;
.LBB0_423:
	s_add_u32 s12, s8, s10
	s_addc_u32 s13, s9, s11
	s_add_u32 s12, s12, 0x100
	s_addc_u32 s13, s13, 0
	s_add_u32 s41, s36, s10
	s_addc_u32 s42, s37, s11
	s_cmpk_eq_i32 s10, 0x700
	s_cselect_b32 s15, s23, s13
	s_cselect_b32 s14, s29, s12
	s_cselect_b32 s13, s21, s42
	s_cselect_b32 s12, s31, s41
	s_waitcnt lgkmcnt(0)
	s_setprio 1
	s_barrier
	v_mfma_f32_16x16x32_bf16 v[126:129], v[146:149], v[186:189], v[126:129]
	v_mfma_f32_16x16x32_bf16 v[122:125], v[154:157], v[186:189], v[122:125]
	v_mfma_f32_16x16x32_bf16 v[110:113], v[146:149], v[178:181], v[110:113]
	v_mfma_f32_16x16x32_bf16 v[106:109], v[154:157], v[178:181], v[106:109]
	v_mfma_f32_16x16x32_bf16 v[94:97], v[146:149], v[170:173], v[94:97]
	v_mfma_f32_16x16x32_bf16 v[90:93], v[154:157], v[170:173], v[90:93]
	v_mfma_f32_16x16x32_bf16 v[78:81], v[146:149], v[162:165], v[78:81]
	v_mfma_f32_16x16x32_bf16 v[74:77], v[154:157], v[162:165], v[74:77]
	v_mfma_f32_16x16x32_bf16 v[126:129], v[150:153], v[190:193], v[126:129]
	v_mfma_f32_16x16x32_bf16 v[122:125], v[158:161], v[190:193], v[122:125]
	v_mfma_f32_16x16x32_bf16 v[110:113], v[150:153], v[182:185], v[110:113]
	v_mfma_f32_16x16x32_bf16 v[106:109], v[158:161], v[182:185], v[106:109]
	v_mfma_f32_16x16x32_bf16 v[94:97], v[150:153], v[174:177], v[94:97]
	v_mfma_f32_16x16x32_bf16 v[90:93], v[158:161], v[174:177], v[90:93]
	v_mfma_f32_16x16x32_bf16 v[78:81], v[150:153], v[166:169], v[78:81]
	v_mfma_f32_16x16x32_bf16 v[74:77], v[158:161], v[166:169], v[74:77]
	v_mfma_f32_16x16x32_bf16 v[118:121], v[130:133], v[186:189], v[118:121]
	v_mfma_f32_16x16x32_bf16 v[114:117], v[138:141], v[186:189], v[114:117]
	v_mfma_f32_16x16x32_bf16 v[102:105], v[130:133], v[178:181], v[102:105]
	v_mfma_f32_16x16x32_bf16 v[98:101], v[138:141], v[178:181], v[98:101]
	v_mfma_f32_16x16x32_bf16 v[86:89], v[130:133], v[170:173], v[86:89]
	v_mfma_f32_16x16x32_bf16 v[82:85], v[138:141], v[170:173], v[82:85]
	v_mfma_f32_16x16x32_bf16 v[70:73], v[130:133], v[162:165], v[70:73]
	v_mfma_f32_16x16x32_bf16 v[66:69], v[138:141], v[162:165], v[66:69]
	v_mfma_f32_16x16x32_bf16 v[118:121], v[134:137], v[190:193], v[118:121]
	v_mfma_f32_16x16x32_bf16 v[114:117], v[142:145], v[190:193], v[114:117]
	v_mfma_f32_16x16x32_bf16 v[102:105], v[134:137], v[182:185], v[102:105]
	v_mfma_f32_16x16x32_bf16 v[98:101], v[142:145], v[182:185], v[98:101]
	v_mfma_f32_16x16x32_bf16 v[86:89], v[134:137], v[174:177], v[86:89]
	v_mfma_f32_16x16x32_bf16 v[82:85], v[142:145], v[174:177], v[82:85]
	v_mfma_f32_16x16x32_bf16 v[70:73], v[134:137], v[166:169], v[70:73]
	v_mfma_f32_16x16x32_bf16 v[66:69], v[142:145], v[166:169], v[66:69]
	s_setprio 0
	s_barrier
	s_mov_b32 m0, s94
	v_lshl_add_u64 v[232:233], s[12:13], 0, v[212:213]
	s_add_u32 s42, s12, 0x40000
	ds_read_b128 v[186:189], v247 offset:16384
	ds_read_b128 v[190:193], v247 offset:17408
	ds_read_b128 v[178:181], v247 offset:18432
	ds_read_b128 v[182:185], v247 offset:19456
	ds_read_b128 v[170:173], v247 offset:20480
	ds_read_b128 v[174:177], v247 offset:21504
	ds_read_b128 v[162:165], v247 offset:22528
	ds_read_b128 v[166:169], v247 offset:23552
	global_load_lds_dwordx4 v[232:233], off
	v_lshl_add_u64 v[230:231], s[12:13], 0, v[216:217]
	s_mov_b32 m0, s95
	s_addc_u32 s43, s13, 0
	global_load_lds_dwordx4 v[230:231], off
	v_lshl_add_u64 v[194:195], s[42:43], 0, v[212:213]
	s_mov_b32 m0, s38
	v_lshl_add_u64 v[226:227], s[14:15], 0, v[210:211]
	global_load_lds_dwordx4 v[194:195], off
	v_lshl_add_u64 v[194:195], s[42:43], 0, v[216:217]
	s_mov_b32 m0, s39
	v_lshl_add_u64 v[228:229], s[14:15], 0, v[214:215]
	global_load_lds_dwordx4 v[194:195], off
	s_mov_b32 m0, s91
	s_andn2_b64 vcc, exec, s[34:35]
	global_load_lds_dwordx4 v[226:227], off
	s_mov_b32 m0, s2
	s_nop 0
	global_load_lds_dwordx4 v[228:229], off
	s_waitcnt vmcnt(24)
	s_cbranch_vccnz .LBB0_420
	s_waitcnt vmcnt(8)
	s_branch .LBB0_420

; #define PG8_STAGE(bufoff, gbase, voff) do { _Pragma("unroll") for (int _i = 0; _i < 2; ++_i) \
;         __builtin_amdgcn_global_load_lds((const unsigned*)((const char*)(gbase) + (voff)[_i]), (PG8_LAS unsigned*)(lds + (bufoff) + ldsw + _i * 8192), 16, 0, 0); } while (0)
; #define PG8_LDA(dst, b, h) do { _Pragma("unroll") for (int m = 0; m < 4; ++m) _Pragma("unroll") for (int k = 0; k < 2; ++k) dst[m][k] = *(const PG8_LAS bf16x8*)(lds + PG8_SA(b, h) + aoff + m * 2048 + k * 1024); } while (0)
; #define PG8_LDB(dst, b, h) do { _Pragma("unroll") for (int n = 0; n < 2; ++n) _Pragma("unroll") for (int k = 0; k < 2; ++k) dst[n][k] = *(const PG8_LAS bf16x8*)(lds + PG8_SB(b, h) + boff + n * 2048 + k * 1024); } while (0)
; #define PG8_MMA(ai, bj, At, Bt) do { __builtin_amdgcn_s_setprio(1); _Pragma("unroll") for (int m = 0; m < 4; ++m) _Pragma("unroll") for (int n = 0; n < 2; ++n) _Pragma("unroll") for (int k = 0; k < 2; ++k) \
;         acc[ai][bj][m][n] = __builtin_amdgcn_mfma_f32_16x16x32_bf16(Bt[n][k], At[m][k], acc[ai][bj][m][n], 0, 0, 0); __builtin_amdgcn_s_setprio(0); } while (0)
; #define PG8_WAIT_V(n) asm volatile("s_waitcnt vmcnt(" #n ")" ::: "memory")
; #define PG8_WAIT_VN(n) asm volatile("s_waitcnt vmcnt(%0)" :: "n"(n) : "memory")
; #define PG8_WAIT_L(n) asm volatile("s_waitcnt lgkmcnt(" #n ")" ::: "memory")
; #define PG8_BAR __builtin_amdgcn_s_barrier()
; #define PG8_SCHED __builtin_amdgcn_sched_barrier(0)
; template <class Epi, class Sched, bool ALIGN_EPI = false, bool SP2 = false>
; __device__ __forceinline__ void gemm_phase(PG8_LAS unsigned char* lds, const Gemm g, const Sched& S, const Epi& E, const int wave_id) {
;     ...
;             PG8_WAIT_VN(8 + Epi::NS); if (strict) PG8_WAIT_V(8); PG8_WAIT_L(0); PG8_BAR; PG8_MMA(1, 0, At, B0); PG8_MMA(1, 1, At, B1); PG8_BAR; PG8_SCHED;
;             PG8_LDB(B0, 1, 0); PG8_LDB(B1, 1, 1); PG8_SCHED; PG8_LDA(At, 1, 0); PG8_STAGE(PG8_SA(0, 1), a2 + hstep, voffA);
;             PG8_WAIT_V(8); PG8_WAIT_L(0); PG8_BAR; PG8_MMA(0, 0, At, B0); PG8_MMA(0, 1, At, B1); PG8_BAR; PG8_SCHED;
.LBB0_1504:
	s_waitcnt lgkmcnt(0)
	s_setprio 1
	s_barrier
	v_mfma_f32_16x16x32_bf16 v[62:65], v[146:149], v[186:189], v[62:65]
	v_mfma_f32_16x16x32_bf16 v[58:61], v[154:157], v[186:189], v[58:61]
	v_mfma_f32_16x16x32_bf16 v[46:49], v[146:149], v[178:181], v[46:49]
	v_mfma_f32_16x16x32_bf16 v[42:45], v[154:157], v[178:181], v[42:45]
	v_mfma_f32_16x16x32_bf16 v[30:33], v[146:149], v[170:173], v[30:33]
	v_mfma_f32_16x16x32_bf16 v[26:29], v[154:157], v[170:173], v[26:29]
	v_mfma_f32_16x16x32_bf16 v[14:17], v[146:149], v[162:165], v[14:17]
	v_mfma_f32_16x16x32_bf16 v[10:13], v[154:157], v[162:165], v[10:13]
	v_mfma_f32_16x16x32_bf16 v[62:65], v[150:153], v[190:193], v[62:65]
	v_mfma_f32_16x16x32_bf16 v[58:61], v[158:161], v[190:193], v[58:61]
	v_mfma_f32_16x16x32_bf16 v[46:49], v[150:153], v[182:185], v[46:49]
	v_mfma_f32_16x16x32_bf16 v[42:45], v[158:161], v[182:185], v[42:45]
	v_mfma_f32_16x16x32_bf16 v[30:33], v[150:153], v[174:177], v[30:33]
	v_mfma_f32_16x16x32_bf16 v[26:29], v[158:161], v[174:177], v[26:29]
	v_mfma_f32_16x16x32_bf16 v[14:17], v[150:153], v[166:169], v[14:17]
	v_mfma_f32_16x16x32_bf16 v[10:13], v[158:161], v[166:169], v[10:13]
	v_mfma_f32_16x16x32_bf16 v[54:57], v[130:133], v[186:189], v[54:57]
	v_mfma_f32_16x16x32_bf16 v[50:53], v[138:141], v[186:189], v[50:53]
	v_mfma_f32_16x16x32_bf16 v[38:41], v[130:133], v[178:181], v[38:41]
	v_mfma_f32_16x16x32_bf16 v[34:37], v[138:141], v[178:181], v[34:37]
	v_mfma_f32_16x16x32_bf16 v[22:25], v[130:133], v[170:173], v[22:25]
	v_mfma_f32_16x16x32_bf16 v[18:21], v[138:141], v[170:173], v[18:21]
	v_mfma_f32_16x16x32_bf16 v[6:9], v[130:133], v[162:165], v[6:9]
	v_mfma_f32_16x16x32_bf16 v[2:5], v[138:141], v[162:165], v[2:5]
	v_mfma_f32_16x16x32_bf16 v[54:57], v[134:137], v[190:193], v[54:57]
	v_mfma_f32_16x16x32_bf16 v[50:53], v[142:145], v[190:193], v[50:53]
	v_mfma_f32_16x16x32_bf16 v[38:41], v[134:137], v[182:185], v[38:41]
	v_mfma_f32_16x16x32_bf16 v[34:37], v[142:145], v[182:185], v[34:37]
	v_mfma_f32_16x16x32_bf16 v[22:25], v[134:137], v[174:177], v[22:25]
	v_mfma_f32_16x16x32_bf16 v[18:21], v[142:145], v[174:177], v[18:21]
	v_mfma_f32_16x16x32_bf16 v[6:9], v[134:137], v[166:169], v[6:9]
	v_mfma_f32_16x16x32_bf16 v[2:5], v[142:145], v[166:169], v[2:5]
	s_setprio 0
	s_barrier
	s_add_i32 s20, 0, 0x18000
	s_add_i32 s21, 0, 0x1c000
	v_add_u32_e32 v142, s20, v1
	v_add_u32_e32 v158, s21, v1
	ds_read_b128 v[130:133], v142
	ds_read_b128 v[134:137], v142 offset:1024
	ds_read_b128 v[138:141], v142 offset:2048
	ds_read_b128 v[142:145], v142 offset:3072
	ds_read_b128 v[146:149], v158
	ds_read_b128 v[150:153], v158 offset:1024
	ds_read_b128 v[154:157], v158 offset:2048
	ds_read_b128 v[158:161], v158 offset:3072
	s_add_u32 s18, s18, 0x40000
	s_addc_u32 s19, s19, 0
	s_mov_b32 m0, s35
	v_lshl_add_u64 v[194:195], s[18:19], 0, v[216:217]
	ds_read_b128 v[162:165], v232 offset:32768
	ds_read_b128 v[166:169], v232 offset:33792
	ds_read_b128 v[170:173], v232 offset:34816
	ds_read_b128 v[174:177], v232 offset:35840
	ds_read_b128 v[178:181], v232 offset:36864
	ds_read_b128 v[182:185], v232 offset:37888
	ds_read_b128 v[186:189], v232 offset:38912
	ds_read_b128 v[190:193], v232 offset:39936
	global_load_lds_dwordx4 v[194:195], off
	v_lshl_add_u64 v[194:195], s[18:19], 0, v[212:213]
	s_mov_b32 m0, s36
	s_nop 0
	global_load_lds_dwordx4 v[194:195], off
	s_waitcnt vmcnt(8)
	s_waitcnt lgkmcnt(0)
	s_setprio 1
	s_barrier
	v_mfma_f32_16x16x32_bf16 v[126:129], v[130:133], v[162:165], v[126:129]
	v_mfma_f32_16x16x32_bf16 v[122:125], v[138:141], v[162:165], v[122:125]
	v_mfma_f32_16x16x32_bf16 v[110:113], v[130:133], v[170:173], v[110:113]
	v_mfma_f32_16x16x32_bf16 v[106:109], v[138:141], v[170:173], v[106:109]
	v_mfma_f32_16x16x32_bf16 v[94:97], v[130:133], v[178:181], v[94:97]
	v_mfma_f32_16x16x32_bf16 v[90:93], v[138:141], v[178:181], v[90:93]
	v_mfma_f32_16x16x32_bf16 v[78:81], v[130:133], v[186:189], v[78:81]
	v_mfma_f32_16x16x32_bf16 v[74:77], v[138:141], v[186:189], v[74:77]
	v_mfma_f32_16x16x32_bf16 v[126:129], v[134:137], v[166:169], v[126:129]
	v_mfma_f32_16x16x32_bf16 v[122:125], v[142:145], v[166:169], v[122:125]
	v_mfma_f32_16x16x32_bf16 v[110:113], v[134:137], v[174:177], v[110:113]
	v_mfma_f32_16x16x32_bf16 v[106:109], v[142:145], v[174:177], v[106:109]
	v_mfma_f32_16x16x32_bf16 v[94:97], v[134:137], v[182:185], v[94:97]
	v_mfma_f32_16x16x32_bf16 v[90:93], v[142:145], v[182:185], v[90:93]
	v_mfma_f32_16x16x32_bf16 v[78:81], v[134:137], v[190:193], v[78:81]
	v_mfma_f32_16x16x32_bf16 v[74:77], v[142:145], v[190:193], v[74:77]
	v_mfma_f32_16x16x32_bf16 v[118:121], v[146:149], v[162:165], v[118:121]
	v_mfma_f32_16x16x32_bf16 v[114:117], v[154:157], v[162:165], v[114:117]
	v_mfma_f32_16x16x32_bf16 v[102:105], v[146:149], v[170:173], v[102:105]
	v_mfma_f32_16x16x32_bf16 v[98:101], v[154:157], v[170:173], v[98:101]
	v_mfma_f32_16x16x32_bf16 v[86:89], v[146:149], v[178:181], v[86:89]
	v_mfma_f32_16x16x32_bf16 v[82:85], v[154:157], v[178:181], v[82:85]
	v_mfma_f32_16x16x32_bf16 v[70:73], v[146:149], v[186:189], v[70:73]
	v_mfma_f32_16x16x32_bf16 v[66:69], v[154:157], v[186:189], v[66:69]
	v_mfma_f32_16x16x32_bf16 v[118:121], v[150:153], v[166:169], v[118:121]
	v_mfma_f32_16x16x32_bf16 v[114:117], v[158:161], v[166:169], v[114:117]
	v_mfma_f32_16x16x32_bf16 v[102:105], v[150:153], v[174:177], v[102:105]
	v_mfma_f32_16x16x32_bf16 v[98:101], v[158:161], v[174:177], v[98:101]
	v_mfma_f32_16x16x32_bf16 v[86:89], v[150:153], v[182:185], v[86:89]
	v_mfma_f32_16x16x32_bf16 v[82:85], v[158:161], v[182:185], v[82:85]
	v_mfma_f32_16x16x32_bf16 v[70:73], v[150:153], v[190:193], v[70:73]
	v_mfma_f32_16x16x32_bf16 v[66:69], v[158:161], v[190:193], v[66:69]
	s_setprio 0
	s_barrier
; #define PG8_STAGE(bufoff, gbase, voff) do { _Pragma("unroll") for (int _i = 0; _i < 2; ++_i) \
;         __builtin_amdgcn_global_load_lds((const unsigned*)((const char*)(gbase) + (voff)[_i]), (PG8_LAS unsigned*)(lds + (bufoff) + ldsw + _i * 8192), 16, 0, 0); } while (0)
; #define PG8_LDA(dst, b, h) do { _Pragma("unroll") for (int m = 0; m < 4; ++m) _Pragma("unroll") for (int k = 0; k < 2; ++k) dst[m][k] = *(const PG8_LAS bf16x8*)(lds + PG8_SA(b, h) + aoff + m * 2048 + k * 1024); } while (0)
; #define PG8_MMA(ai, bj, At, Bt) do { __builtin_amdgcn_s_setprio(1); _Pragma("unroll") for (int m = 0; m < 4; ++m) _Pragma("unroll") for (int n = 0; n < 2; ++n) _Pragma("unroll") for (int k = 0; k < 2; ++k) \
;         acc[ai][bj][m][n] = __builtin_amdgcn_mfma_f32_16x16x32_bf16(Bt[n][k], At[m][k], acc[ai][bj][m][n], 0, 0, 0); __builtin_amdgcn_s_setprio(0); } while (0)
; #define PG8_WAIT_V(n) asm volatile("s_waitcnt vmcnt(" #n ")" ::: "memory")
; #define PG8_WAIT_L(n) asm volatile("s_waitcnt lgkmcnt(" #n ")" ::: "memory")
; #define PG8_BAR __builtin_amdgcn_s_barrier()
; #define PG8_SCHED __builtin_amdgcn_sched_barrier(0)
; template <class Epi, class Sched, bool ALIGN_EPI = false, bool SP2 = false>
; __device__ __forceinline__ void gemm_phase(PG8_LAS unsigned char* lds, const Gemm g, const Sched& S, const Epi& E, const int wave_id) {
;     ...
;             PG8_LDA(At, 1, 1); PG8_STAGE(PG8_SB(1, 0), b3, voffB); PG8_STAGE(PG8_SB(1, 1), b3 + hstep, voffB); PG8_STAGE(PG8_SA(1, 0), a3, voffA);
;             PG8_WAIT_V(8); PG8_WAIT_L(0); PG8_BAR; PG8_MMA(1, 0, At, B0); PG8_MMA(1, 1, At, B1); PG8_BAR; PG8_SCHED;
	s_add_i32 s18, s20, s24
	v_lshl_add_u64 v[194:195], v[228:229], 0, s[64:65]
	s_mov_b32 m0, s18
	ds_read_b128 v[162:165], v232 offset:49152
	ds_read_b128 v[166:169], v232 offset:50176
	ds_read_b128 v[170:173], v232 offset:51200
	ds_read_b128 v[174:177], v232 offset:52224
	ds_read_b128 v[178:181], v232 offset:53248
	ds_read_b128 v[182:185], v232 offset:54272
	ds_read_b128 v[186:189], v232 offset:55296
	ds_read_b128 v[190:193], v232 offset:56320
	global_load_lds_dwordx4 v[194:195], off
	s_add_i32 m0, s18, 0x2000
	s_add_u32 s16, s16, 0x40080
	v_lshl_add_u64 v[194:195], v[226:227], 0, s[64:65]
	s_addc_u32 s17, s17, 0
	s_add_i32 s18, s21, s24
	global_load_lds_dwordx4 v[194:195], off
	v_lshl_add_u64 v[194:195], s[16:17], 0, v[214:215]
	s_mov_b32 m0, s18
	s_nop 0
	global_load_lds_dwordx4 v[194:195], off
	v_lshl_add_u64 v[194:195], s[16:17], 0, v[210:211]
	s_add_i32 m0, s18, 0x2000
	s_nop 0
	global_load_lds_dwordx4 v[194:195], off
	v_lshl_add_u64 v[194:195], v[222:223], 0, s[64:65]
	s_mov_b32 m0, s37
	s_nop 0
	global_load_lds_dwordx4 v[194:195], off
	v_lshl_add_u64 v[194:195], v[224:225], 0, s[64:65]
	s_mov_b32 m0, s38
	s_nop 0
	global_load_lds_dwordx4 v[194:195], off
	s_waitcnt vmcnt(8)
	s_waitcnt lgkmcnt(0)
	s_setprio 1
	s_barrier
	v_mfma_f32_16x16x32_bf16 v[62:65], v[130:133], v[162:165], v[62:65]
	v_mfma_f32_16x16x32_bf16 v[58:61], v[138:141], v[162:165], v[58:61]
	v_mfma_f32_16x16x32_bf16 v[46:49], v[130:133], v[170:173], v[46:49]
	v_mfma_f32_16x16x32_bf16 v[42:45], v[138:141], v[170:173], v[42:45]
	v_mfma_f32_16x16x32_bf16 v[30:33], v[130:133], v[178:181], v[30:33]
	v_mfma_f32_16x16x32_bf16 v[26:29], v[138:141], v[178:181], v[26:29]
	v_mfma_f32_16x16x32_bf16 v[14:17], v[130:133], v[186:189], v[14:17]
	v_mfma_f32_16x16x32_bf16 v[10:13], v[138:141], v[186:189], v[10:13]
	v_mfma_f32_16x16x32_bf16 v[62:65], v[134:137], v[166:169], v[62:65]
	v_mfma_f32_16x16x32_bf16 v[58:61], v[142:145], v[166:169], v[58:61]
	v_mfma_f32_16x16x32_bf16 v[46:49], v[134:137], v[174:177], v[46:49]
	v_mfma_f32_16x16x32_bf16 v[42:45], v[142:145], v[174:177], v[42:45]
	v_mfma_f32_16x16x32_bf16 v[30:33], v[134:137], v[182:185], v[30:33]
	v_mfma_f32_16x16x32_bf16 v[26:29], v[142:145], v[182:185], v[26:29]
	v_mfma_f32_16x16x32_bf16 v[14:17], v[134:137], v[190:193], v[14:17]
	v_mfma_f32_16x16x32_bf16 v[10:13], v[142:145], v[190:193], v[10:13]
	v_mfma_f32_16x16x32_bf16 v[54:57], v[146:149], v[162:165], v[54:57]
	v_mfma_f32_16x16x32_bf16 v[50:53], v[154:157], v[162:165], v[50:53]
	v_mfma_f32_16x16x32_bf16 v[38:41], v[146:149], v[170:173], v[38:41]
	v_mfma_f32_16x16x32_bf16 v[34:37], v[154:157], v[170:173], v[34:37]
	v_mfma_f32_16x16x32_bf16 v[22:25], v[146:149], v[178:181], v[22:25]
	v_mfma_f32_16x16x32_bf16 v[18:21], v[154:157], v[178:181], v[18:21]
	v_mfma_f32_16x16x32_bf16 v[6:9], v[146:149], v[186:189], v[6:9]
	v_mfma_f32_16x16x32_bf16 v[2:5], v[154:157], v[186:189], v[2:5]
	v_mfma_f32_16x16x32_bf16 v[54:57], v[150:153], v[166:169], v[54:57]
	v_mfma_f32_16x16x32_bf16 v[50:53], v[158:161], v[166:169], v[50:53]
	v_mfma_f32_16x16x32_bf16 v[38:41], v[150:153], v[174:177], v[38:41]
	v_mfma_f32_16x16x32_bf16 v[34:37], v[158:161], v[174:177], v[34:37]
	v_mfma_f32_16x16x32_bf16 v[22:25], v[150:153], v[182:185], v[22:25]
	v_mfma_f32_16x16x32_bf16 v[18:21], v[158:161], v[182:185], v[18:21]
	v_mfma_f32_16x16x32_bf16 v[6:9], v[150:153], v[190:193], v[6:9]
	v_mfma_f32_16x16x32_bf16 v[2:5], v[158:161], v[190:193], v[2:5]
	s_setprio 0
	s_barrier
	s_add_u32 s12, s12, 0x100
	s_addc_u32 s13, s13, 0
	s_cmp_gt_u32 s43, 13
	s_cbranch_scc1 .LBB0_1526

; #define PG8_STAGE(bufoff, gbase, voff) do { _Pragma("unroll") for (int _i = 0; _i < 2; ++_i) \
;         __builtin_amdgcn_global_load_lds((const unsigned*)((const char*)(gbase) + (voff)[_i]), (PG8_LAS unsigned*)(lds + (bufoff) + ldsw + _i * 8192), 16, 0, 0); } while (0)
; #define PG8_LDA(dst, b, h) do { _Pragma("unroll") for (int m = 0; m < 4; ++m) _Pragma("unroll") for (int k = 0; k < 2; ++k) dst[m][k] = *(const PG8_LAS bf16x8*)(lds + PG8_SA(b, h) + aoff + m * 2048 + k * 1024); } while (0)
; #define PG8_LDB(dst, b, h) do { _Pragma("unroll") for (int n = 0; n < 2; ++n) _Pragma("unroll") for (int k = 0; k < 2; ++k) dst[n][k] = *(const PG8_LAS bf16x8*)(lds + PG8_SB(b, h) + boff + n * 2048 + k * 1024); } while (0)
; #define PG8_WAIT_V(n) asm volatile("s_waitcnt vmcnt(" #n ")" ::: "memory")
; #define PG8_WAIT_VN(n) asm volatile("s_waitcnt vmcnt(%0)" :: "n"(n) : "memory")
; #define PG8_WAIT_L(n) asm volatile("s_waitcnt lgkmcnt(" #n ")" ::: "memory")
; #define PG8_BAR __builtin_amdgcn_s_barrier()
; #define PG8_SCHED __builtin_amdgcn_sched_barrier(0)
; template <class Epi, class Sched, bool ALIGN_EPI = false, bool SP2 = false>
; __device__ __forceinline__ void gemm_phase(PG8_LAS unsigned char* lds, const Gemm g, const Sched& S, const Epi& E, const int wave_id) {
;     ...
;             const char* a1 = cA + (size_t)(t + 1) * kstep;
;             const char* a2 = last ? nA : cA + (size_t)(t + 2) * kstep; const char* b2 = last ? nB : cB + (size_t)(t + 2) * kstep;
;             const char* a3 = a2 + kstep; const char* b3 = b2 + kstep;
;             if (last && has_next) S.a_ready(nxt);
;             if constexpr (SP2) {
;             int tz_ = __builtin_amdgcn_readfirstlane(t | (ui > 0 ? 0 : 1)); asm volatile("" : "+s"(tz_));
;             const bool strict = !(Epi::NS > 0 && tz_ == 0);
;             PG8_LDB(B0, 0, 0); PG8_LDB(B1, 0, 1); PG8_SCHED; PG8_LDA(At, 0, 0); PG8_STAGE(PG8_SA(1, 1), a1 + hstep, voffA);
;             PG8_WAIT_VN(8 + Epi::NS); if (strict) PG8_WAIT_V(8); PG8_WAIT_L(0); PG8_BAR; PG8_MMA(0, 0, At, B0); PG8_MMA(0, 1, At, B1); PG8_BAR; PG8_SCHED;
;             PG8_LDA(At, 0, 1); PG8_STAGE(PG8_SB(0, 0), b2, voffB); PG8_STAGE(PG8_SB(0, 1), b2 + hstep, voffB); PG8_STAGE(PG8_SA(0, 0), a2, voffA);
;             PG8_WAIT_VN(8 + Epi::NS); if (strict) PG8_WAIT_V(8); PG8_WAIT_L(0); PG8_BAR; PG8_MMA(1, 0, At, B0); PG8_MMA(1, 1, At, B1); PG8_BAR; PG8_SCHED;
.LBB0_1507:
	s_add_u32 s16, s41, s12
	s_addc_u32 s17, s42, s13
	s_add_u32 s16, s16, 0x8f2c0100
	s_addc_u32 s17, s17, 0
	s_add_u32 s49, s39, s12
	s_addc_u32 s50, s40, s13
	s_cmpk_eq_i32 s12, 0x700
	s_cselect_b32 s19, s11, s17
	s_cselect_b32 s18, s10, s16
	s_cselect_b32 s17, s9, s50
	s_cselect_b32 s16, s8, s49
	s_waitcnt lgkmcnt(0)
	s_setprio 1
	s_barrier
	v_mfma_f32_16x16x32_bf16 v[126:129], v[146:149], v[186:189], v[126:129]
	v_mfma_f32_16x16x32_bf16 v[122:125], v[154:157], v[186:189], v[122:125]
	v_mfma_f32_16x16x32_bf16 v[110:113], v[146:149], v[178:181], v[110:113]
	v_mfma_f32_16x16x32_bf16 v[106:109], v[154:157], v[178:181], v[106:109]
	v_mfma_f32_16x16x32_bf16 v[94:97], v[146:149], v[170:173], v[94:97]
	v_mfma_f32_16x16x32_bf16 v[90:93], v[154:157], v[170:173], v[90:93]
	v_mfma_f32_16x16x32_bf16 v[78:81], v[146:149], v[162:165], v[78:81]
	v_mfma_f32_16x16x32_bf16 v[74:77], v[154:157], v[162:165], v[74:77]
	v_mfma_f32_16x16x32_bf16 v[126:129], v[150:153], v[190:193], v[126:129]
	v_mfma_f32_16x16x32_bf16 v[122:125], v[158:161], v[190:193], v[122:125]
	v_mfma_f32_16x16x32_bf16 v[110:113], v[150:153], v[182:185], v[110:113]
	v_mfma_f32_16x16x32_bf16 v[106:109], v[158:161], v[182:185], v[106:109]
	v_mfma_f32_16x16x32_bf16 v[94:97], v[150:153], v[174:177], v[94:97]
	v_mfma_f32_16x16x32_bf16 v[90:93], v[158:161], v[174:177], v[90:93]
	v_mfma_f32_16x16x32_bf16 v[78:81], v[150:153], v[166:169], v[78:81]
	v_mfma_f32_16x16x32_bf16 v[74:77], v[158:161], v[166:169], v[74:77]
	v_mfma_f32_16x16x32_bf16 v[118:121], v[130:133], v[186:189], v[118:121]
	v_mfma_f32_16x16x32_bf16 v[114:117], v[138:141], v[186:189], v[114:117]
	v_mfma_f32_16x16x32_bf16 v[102:105], v[130:133], v[178:181], v[102:105]
	v_mfma_f32_16x16x32_bf16 v[98:101], v[138:141], v[178:181], v[98:101]
	v_mfma_f32_16x16x32_bf16 v[86:89], v[130:133], v[170:173], v[86:89]
	v_mfma_f32_16x16x32_bf16 v[82:85], v[138:141], v[170:173], v[82:85]
	v_mfma_f32_16x16x32_bf16 v[70:73], v[130:133], v[162:165], v[70:73]
	v_mfma_f32_16x16x32_bf16 v[66:69], v[138:141], v[162:165], v[66:69]
	v_mfma_f32_16x16x32_bf16 v[118:121], v[134:137], v[190:193], v[118:121]
	v_mfma_f32_16x16x32_bf16 v[114:117], v[142:145], v[190:193], v[114:117]
	v_mfma_f32_16x16x32_bf16 v[102:105], v[134:137], v[182:185], v[102:105]
	v_mfma_f32_16x16x32_bf16 v[98:101], v[142:145], v[182:185], v[98:101]
	v_mfma_f32_16x16x32_bf16 v[86:89], v[134:137], v[174:177], v[86:89]
	v_mfma_f32_16x16x32_bf16 v[82:85], v[142:145], v[174:177], v[82:85]
	v_mfma_f32_16x16x32_bf16 v[70:73], v[134:137], v[166:169], v[70:73]
	v_mfma_f32_16x16x32_bf16 v[66:69], v[142:145], v[166:169], v[66:69]
	s_setprio 0
	s_barrier
	s_mov_b32 m0, s26
	v_lshl_add_u64 v[228:229], s[16:17], 0, v[214:215]
	s_add_u32 s50, s16, 0x40000
	ds_read_b128 v[186:189], v232 offset:16384
	ds_read_b128 v[190:193], v232 offset:17408
	ds_read_b128 v[178:181], v232 offset:18432
	ds_read_b128 v[182:185], v232 offset:19456
	ds_read_b128 v[170:173], v232 offset:20480
	ds_read_b128 v[174:177], v232 offset:21504
	ds_read_b128 v[162:165], v232 offset:22528
	ds_read_b128 v[166:169], v232 offset:23552
	global_load_lds_dwordx4 v[228:229], off
	v_lshl_add_u64 v[226:227], s[16:17], 0, v[210:211]
	s_mov_b32 m0, s27
	s_addc_u32 s51, s17, 0
	global_load_lds_dwordx4 v[226:227], off
	v_lshl_add_u64 v[194:195], s[50:51], 0, v[214:215]
	s_mov_b32 m0, s29
	v_lshl_add_u64 v[222:223], s[18:19], 0, v[216:217]
	global_load_lds_dwordx4 v[194:195], off
	v_lshl_add_u64 v[194:195], s[50:51], 0, v[210:211]
	s_mov_b32 m0, s30
	v_lshl_add_u64 v[224:225], s[18:19], 0, v[212:213]
	global_load_lds_dwordx4 v[194:195], off
	s_mov_b32 m0, s25
	s_andn2_b64 vcc, exec, s[20:21]
	global_load_lds_dwordx4 v[222:223], off
	s_mov_b32 m0, s34
	s_nop 0
	global_load_lds_dwordx4 v[224:225], off
	s_waitcnt vmcnt(24)
	s_cbranch_vccnz .LBB0_1504
	s_waitcnt vmcnt(8)
	s_branch .LBB0_1504

; #define PG8_STAGE(bufoff, gbase, voff) do { _Pragma("unroll") for (int _i = 0; _i < 2; ++_i) \
;         __builtin_amdgcn_global_load_lds((const unsigned*)((const char*)(gbase) + (voff)[_i]), (PG8_LAS unsigned*)(lds + (bufoff) + ldsw + _i * 8192), 16, 0, 0); } while (0)
; #define PG8_LDA(dst, b, h) do { _Pragma("unroll") for (int m = 0; m < 4; ++m) _Pragma("unroll") for (int k = 0; k < 2; ++k) dst[m][k] = *(const PG8_LAS bf16x8*)(lds + PG8_SA(b, h) + aoff + m * 2048 + k * 1024); } while (0)
; #define PG8_LDB(dst, b, h) do { _Pragma("unroll") for (int n = 0; n < 2; ++n) _Pragma("unroll") for (int k = 0; k < 2; ++k) dst[n][k] = *(const PG8_LAS bf16x8*)(lds + PG8_SB(b, h) + boff + n * 2048 + k * 1024); } while (0)
; #define PG8_WAIT_V(n) asm volatile("s_waitcnt vmcnt(" #n ")" ::: "memory")
; #define PG8_WAIT_VN(n) asm volatile("s_waitcnt vmcnt(%0)" :: "n"(n) : "memory")
; #define PG8_WAIT_L(n) asm volatile("s_waitcnt lgkmcnt(" #n ")" ::: "memory")
; #define PG8_BAR __builtin_amdgcn_s_barrier()
; #define PG8_SCHED __builtin_amdgcn_sched_barrier(0)
; template <class Epi, class Sched, bool ALIGN_EPI = false, bool SP2 = false>
; __device__ __forceinline__ void gemm_phase(PG8_LAS unsigned char* lds, const Gemm g, const Sched& S, const Epi& E, const int wave_id) {
;     ...
;             const char* a1 = cA + (size_t)(t + 1) * kstep;
;             const char* a2 = last ? nA : cA + (size_t)(t + 2) * kstep; const char* b2 = last ? nB : cB + (size_t)(t + 2) * kstep;
;             const char* a3 = a2 + kstep; const char* b3 = b2 + kstep;
;             if (last && has_next) S.a_ready(nxt);
;             if constexpr (SP2) {
;             int tz_ = __builtin_amdgcn_readfirstlane(t | (ui > 0 ? 0 : 1)); asm volatile("" : "+s"(tz_));
;             const bool strict = !(Epi::NS > 0 && tz_ == 0);
;             PG8_LDB(B0, 0, 0); PG8_LDB(B1, 0, 1); PG8_SCHED; PG8_LDA(At, 0, 0); PG8_STAGE(PG8_SA(1, 1), a1 + hstep, voffA);
;             PG8_WAIT_VN(8 + Epi::NS); if (strict) PG8_WAIT_V(8); PG8_WAIT_L(0); PG8_BAR; PG8_MMA(0, 0, At, B0); PG8_MMA(0, 1, At, B1); PG8_BAR; PG8_SCHED;
;             PG8_LDA(At, 0, 1); PG8_STAGE(PG8_SB(0, 0), b2, voffB); PG8_STAGE(PG8_SB(0, 1), b2 + hstep, voffB); PG8_STAGE(PG8_SA(0, 0), a2, voffA);
;             PG8_WAIT_VN(8 + Epi::NS); if (strict) PG8_WAIT_V(8); PG8_WAIT_L(0); PG8_BAR; PG8_MMA(1, 0, At, B0); PG8_MMA(1, 1, At, B1); PG8_BAR; PG8_SCHED;
.LBB0_1537:
	s_add_u32 s12, s8, s10
	s_addc_u32 s13, s9, s11
	s_add_u32 s12, s12, 0x100
	s_addc_u32 s13, s13, 0
	s_add_u32 s53, s67, s10
	s_addc_u32 s76, s68, s11
	s_add_i32 s69, s69, 2
	s_add_i32 s78, 0, 0x10000
	v_add_u32_e32 v147, s69, v146
	s_cmpk_eq_i32 s10, 0x700
	s_cselect_b32 s26, s57, s12
	v_readfirstlane_b32 s12, v147
	s_cselect_b32 s27, s56, s13
	v_add_u32_e32 v147, s78, v163
	s_cselect_b32 s13, s62, s76
	s_cselect_b32 s12, s63, s53
	s_add_i32 s53, 0, 0x14000
	ds_read_b128 v[148:151], v147
	ds_read_b128 v[152:155], v147 offset:1024
	ds_read_b128 v[156:159], v147 offset:2048
	ds_read_b128 v[166:169], v147 offset:3072
	v_add_u32_e32 v147, s53, v163
	ds_read_b128 v[170:173], v147
	ds_read_b128 v[174:177], v147 offset:1024
	ds_read_b128 v[178:181], v147 offset:2048
	ds_read_b128 v[182:185], v147 offset:3072
	v_lshl_add_u64 v[160:161], v[144:145], 0, s[10:11]
	s_add_i32 m0, s17, 0xc000
	ds_read_b128 v[186:189], v164
	ds_read_b128 v[190:193], v164 offset:1024
	ds_read_b128 v[194:197], v164 offset:2048
	ds_read_b128 v[198:201], v164 offset:3072
	ds_read_b128 v[202:205], v164 offset:4096
	ds_read_b128 v[206:209], v164 offset:5120
	ds_read_b128 v[210:213], v164 offset:6144
	ds_read_b128 v[214:217], v164 offset:7168
	global_load_lds_dwordx4 v[160:161], off
	v_lshl_add_u64 v[160:161], v[142:143], 0, s[10:11]
	s_add_i32 m0, s17, 0xe000
	s_nop 0
	global_load_lds_dwordx4 v[160:161], off
	s_waitcnt vmcnt(8)
	s_waitcnt vmcnt(8)
	s_waitcnt lgkmcnt(0)
	s_setprio 1
	s_barrier
	v_mfma_f32_16x16x32_bf16 v[126:129], v[148:151], v[186:189], v[126:129]
	v_mfma_f32_16x16x32_bf16 v[122:125], v[156:159], v[186:189], v[122:125]
	v_mfma_f32_16x16x32_bf16 v[118:121], v[148:151], v[194:197], v[118:121]
	v_mfma_f32_16x16x32_bf16 v[114:117], v[156:159], v[194:197], v[114:117]
	v_mfma_f32_16x16x32_bf16 v[110:113], v[148:151], v[202:205], v[110:113]
	v_mfma_f32_16x16x32_bf16 v[106:109], v[156:159], v[202:205], v[106:109]
	v_mfma_f32_16x16x32_bf16 v[102:105], v[148:151], v[210:213], v[102:105]
	v_mfma_f32_16x16x32_bf16 v[98:101], v[156:159], v[210:213], v[98:101]
	v_mfma_f32_16x16x32_bf16 v[126:129], v[152:155], v[190:193], v[126:129]
	v_mfma_f32_16x16x32_bf16 v[122:125], v[166:169], v[190:193], v[122:125]
	v_mfma_f32_16x16x32_bf16 v[118:121], v[152:155], v[198:201], v[118:121]
	v_mfma_f32_16x16x32_bf16 v[114:117], v[166:169], v[198:201], v[114:117]
	v_mfma_f32_16x16x32_bf16 v[110:113], v[152:155], v[206:209], v[110:113]
	v_mfma_f32_16x16x32_bf16 v[106:109], v[166:169], v[206:209], v[106:109]
	v_mfma_f32_16x16x32_bf16 v[102:105], v[152:155], v[214:217], v[102:105]
	v_mfma_f32_16x16x32_bf16 v[98:101], v[166:169], v[214:217], v[98:101]
	v_mfma_f32_16x16x32_bf16 v[94:97], v[170:173], v[186:189], v[94:97]
	v_mfma_f32_16x16x32_bf16 v[90:93], v[178:181], v[186:189], v[90:93]
	v_mfma_f32_16x16x32_bf16 v[86:89], v[170:173], v[194:197], v[86:89]
	v_mfma_f32_16x16x32_bf16 v[82:85], v[178:181], v[194:197], v[82:85]
	v_mfma_f32_16x16x32_bf16 v[78:81], v[170:173], v[202:205], v[78:81]
	v_mfma_f32_16x16x32_bf16 v[74:77], v[178:181], v[202:205], v[74:77]
	v_mfma_f32_16x16x32_bf16 v[70:73], v[170:173], v[210:213], v[70:73]
	v_mfma_f32_16x16x32_bf16 v[66:69], v[178:181], v[210:213], v[66:69]
	v_mfma_f32_16x16x32_bf16 v[94:97], v[174:177], v[190:193], v[94:97]
	v_mfma_f32_16x16x32_bf16 v[90:93], v[182:185], v[190:193], v[90:93]
	v_mfma_f32_16x16x32_bf16 v[86:89], v[174:177], v[198:201], v[86:89]
	v_mfma_f32_16x16x32_bf16 v[82:85], v[182:185], v[198:201], v[82:85]
	v_mfma_f32_16x16x32_bf16 v[78:81], v[174:177], v[206:209], v[78:81]
	v_mfma_f32_16x16x32_bf16 v[74:77], v[182:185], v[206:209], v[74:77]
	v_mfma_f32_16x16x32_bf16 v[70:73], v[174:177], v[214:217], v[70:73]
	v_mfma_f32_16x16x32_bf16 v[66:69], v[182:185], v[214:217], v[66:69]
	s_setprio 0
	s_barrier
	s_add_i32 s76, s78, s35
	v_lshl_add_u64 v[160:161], s[12:13], 0, v[132:133]
	s_mov_b32 m0, s76
	ds_read_b128 v[186:189], v164 offset:16384
	ds_read_b128 v[190:193], v164 offset:17408
	ds_read_b128 v[194:197], v164 offset:18432
	ds_read_b128 v[198:201], v164 offset:19456
	ds_read_b128 v[202:205], v164 offset:20480
	ds_read_b128 v[206:209], v164 offset:21504
	ds_read_b128 v[210:213], v164 offset:22528
	ds_read_b128 v[214:217], v164 offset:23552
	global_load_lds_dwordx4 v[160:161], off
	s_add_i32 m0, s76, 0x2000
	s_add_u32 s90, s12, 0x40000
	v_lshl_add_u64 v[218:219], s[12:13], 0, v[136:137]
	s_addc_u32 s91, s13, 0
	s_add_i32 s53, s53, s35
	global_load_lds_dwordx4 v[218:219], off
	v_lshl_add_u64 v[220:221], s[90:91], 0, v[132:133]
	s_mov_b32 m0, s53
	v_lshl_add_u64 v[222:223], s[26:27], 0, v[134:135]
	global_load_lds_dwordx4 v[220:221], off
	v_lshl_add_u64 v[220:221], s[90:91], 0, v[136:137]
	s_add_i32 m0, s53, 0x2000
	s_nop 0
	global_load_lds_dwordx4 v[220:221], off
	v_lshl_add_u64 v[220:221], s[26:27], 0, v[130:131]
	s_mov_b32 m0, s17
	s_nop 0
	global_load_lds_dwordx4 v[220:221], off
	s_mov_b32 m0, s37
	s_nop 0
	global_load_lds_dwordx4 v[222:223], off
	s_waitcnt vmcnt(8)
	s_waitcnt vmcnt(8)
	s_waitcnt lgkmcnt(0)
	s_setprio 1
	s_barrier
; #define PG8_STAGE(bufoff, gbase, voff) do { _Pragma("unroll") for (int _i = 0; _i < 2; ++_i) \
;         __builtin_amdgcn_global_load_lds((const unsigned*)((const char*)(gbase) + (voff)[_i]), (PG8_LAS unsigned*)(lds + (bufoff) + ldsw + _i * 8192), 16, 0, 0); } while (0)
; #define PG8_LDA(dst, b, h) do { _Pragma("unroll") for (int m = 0; m < 4; ++m) _Pragma("unroll") for (int k = 0; k < 2; ++k) dst[m][k] = *(const PG8_LAS bf16x8*)(lds + PG8_SA(b, h) + aoff + m * 2048 + k * 1024); } while (0)
; #define PG8_LDB(dst, b, h) do { _Pragma("unroll") for (int n = 0; n < 2; ++n) _Pragma("unroll") for (int k = 0; k < 2; ++k) dst[n][k] = *(const PG8_LAS bf16x8*)(lds + PG8_SB(b, h) + boff + n * 2048 + k * 1024); } while (0)
; #define PG8_MMA(ai, bj, At, Bt) do { __builtin_amdgcn_s_setprio(1); _Pragma("unroll") for (int m = 0; m < 4; ++m) _Pragma("unroll") for (int n = 0; n < 2; ++n) _Pragma("unroll") for (int k = 0; k < 2; ++k) \
;         acc[ai][bj][m][n] = __builtin_amdgcn_mfma_f32_16x16x32_bf16(Bt[n][k], At[m][k], acc[ai][bj][m][n], 0, 0, 0); __builtin_amdgcn_s_setprio(0); } while (0)
; #define PG8_WAIT_V(n) asm volatile("s_waitcnt vmcnt(" #n ")" ::: "memory")
; #define PG8_WAIT_VN(n) asm volatile("s_waitcnt vmcnt(%0)" :: "n"(n) : "memory")
; #define PG8_WAIT_L(n) asm volatile("s_waitcnt lgkmcnt(" #n ")" ::: "memory")
; #define PG8_BAR __builtin_amdgcn_s_barrier()
; #define PG8_SCHED __builtin_amdgcn_sched_barrier(0)
; template <class Epi, class Sched, bool ALIGN_EPI = false, bool SP2 = false>
; __device__ __forceinline__ void gemm_phase(PG8_LAS unsigned char* lds, const Gemm g, const Sched& S, const Epi& E, const int wave_id) {
;     ...
;             PG8_WAIT_VN(8 + Epi::NS); if (strict) PG8_WAIT_V(8); PG8_WAIT_L(0); PG8_BAR; PG8_MMA(1, 0, At, B0); PG8_MMA(1, 1, At, B1); PG8_BAR; PG8_SCHED;
;             PG8_LDB(B0, 1, 0); PG8_LDB(B1, 1, 1); PG8_SCHED; PG8_LDA(At, 1, 0); PG8_STAGE(PG8_SA(0, 1), a2 + hstep, voffA);
;             PG8_WAIT_V(8); PG8_WAIT_L(0); PG8_BAR; PG8_MMA(0, 0, At, B0); PG8_MMA(0, 1, At, B1); PG8_BAR; PG8_SCHED;
	v_mfma_f32_16x16x32_bf16 v[62:65], v[148:151], v[186:189], v[62:65]
	v_mfma_f32_16x16x32_bf16 v[58:61], v[156:159], v[186:189], v[58:61]
	v_mfma_f32_16x16x32_bf16 v[54:57], v[148:151], v[194:197], v[54:57]
	v_mfma_f32_16x16x32_bf16 v[50:53], v[156:159], v[194:197], v[50:53]
	v_mfma_f32_16x16x32_bf16 v[46:49], v[148:151], v[202:205], v[46:49]
	v_mfma_f32_16x16x32_bf16 v[42:45], v[156:159], v[202:205], v[42:45]
	v_mfma_f32_16x16x32_bf16 v[38:41], v[148:151], v[210:213], v[38:41]
	v_mfma_f32_16x16x32_bf16 v[34:37], v[156:159], v[210:213], v[34:37]
	v_mfma_f32_16x16x32_bf16 v[62:65], v[152:155], v[190:193], v[62:65]
	v_mfma_f32_16x16x32_bf16 v[58:61], v[166:169], v[190:193], v[58:61]
	v_mfma_f32_16x16x32_bf16 v[54:57], v[152:155], v[198:201], v[54:57]
	v_mfma_f32_16x16x32_bf16 v[50:53], v[166:169], v[198:201], v[50:53]
	v_mfma_f32_16x16x32_bf16 v[46:49], v[152:155], v[206:209], v[46:49]
	v_mfma_f32_16x16x32_bf16 v[42:45], v[166:169], v[206:209], v[42:45]
	v_mfma_f32_16x16x32_bf16 v[38:41], v[152:155], v[214:217], v[38:41]
	v_mfma_f32_16x16x32_bf16 v[34:37], v[166:169], v[214:217], v[34:37]
	v_mfma_f32_16x16x32_bf16 v[30:33], v[170:173], v[186:189], v[30:33]
	v_mfma_f32_16x16x32_bf16 v[26:29], v[178:181], v[186:189], v[26:29]
	v_mfma_f32_16x16x32_bf16 v[22:25], v[170:173], v[194:197], v[22:25]
	v_mfma_f32_16x16x32_bf16 v[18:21], v[178:181], v[194:197], v[18:21]
	v_mfma_f32_16x16x32_bf16 v[14:17], v[170:173], v[202:205], v[14:17]
	v_mfma_f32_16x16x32_bf16 v[10:13], v[178:181], v[202:205], v[10:13]
	v_mfma_f32_16x16x32_bf16 v[6:9], v[170:173], v[210:213], v[6:9]
	v_mfma_f32_16x16x32_bf16 v[2:5], v[178:181], v[210:213], v[2:5]
	v_mfma_f32_16x16x32_bf16 v[30:33], v[174:177], v[190:193], v[30:33]
	v_mfma_f32_16x16x32_bf16 v[26:29], v[182:185], v[190:193], v[26:29]
	v_mfma_f32_16x16x32_bf16 v[22:25], v[174:177], v[198:201], v[22:25]
	v_mfma_f32_16x16x32_bf16 v[18:21], v[182:185], v[198:201], v[18:21]
	v_mfma_f32_16x16x32_bf16 v[14:17], v[174:177], v[206:209], v[14:17]
	v_mfma_f32_16x16x32_bf16 v[10:13], v[182:185], v[206:209], v[10:13]
	v_mfma_f32_16x16x32_bf16 v[6:9], v[174:177], v[214:217], v[6:9]
	v_mfma_f32_16x16x32_bf16 v[2:5], v[182:185], v[214:217], v[2:5]
	s_setprio 0
	s_barrier
	s_add_i32 s53, 0, 0x18000
	v_add_u32_e32 v147, s53, v163
	s_add_i32 s76, 0, 0x1c000
	ds_read_b128 v[148:151], v147
	ds_read_b128 v[152:155], v147 offset:1024
	ds_read_b128 v[156:159], v147 offset:2048
	ds_read_b128 v[166:169], v147 offset:3072
	v_add_u32_e32 v147, s76, v163
	ds_read_b128 v[170:173], v147
	ds_read_b128 v[174:177], v147 offset:1024
	ds_read_b128 v[178:181], v147 offset:2048
	ds_read_b128 v[182:185], v147 offset:3072
	s_add_u32 s26, s26, 0x40000
	s_addc_u32 s27, s27, 0
	s_mov_b32 m0, s38
	v_lshl_add_u64 v[224:225], s[26:27], 0, v[130:131]
	ds_read_b128 v[186:189], v164 offset:32768
	ds_read_b128 v[190:193], v164 offset:33792
	ds_read_b128 v[194:197], v164 offset:34816
	ds_read_b128 v[198:201], v164 offset:35840
	ds_read_b128 v[202:205], v164 offset:36864
	ds_read_b128 v[206:209], v164 offset:37888
	ds_read_b128 v[210:213], v164 offset:38912
	ds_read_b128 v[214:217], v164 offset:39936
	global_load_lds_dwordx4 v[224:225], off
	v_lshl_add_u64 v[224:225], s[26:27], 0, v[134:135]
	s_mov_b32 m0, s39
	s_nop 0
	global_load_lds_dwordx4 v[224:225], off
	s_waitcnt vmcnt(8)
	s_waitcnt lgkmcnt(0)
	s_setprio 1
	s_barrier
	v_mfma_f32_16x16x32_bf16 v[126:129], v[148:151], v[186:189], v[126:129]
	v_mfma_f32_16x16x32_bf16 v[122:125], v[156:159], v[186:189], v[122:125]
	v_mfma_f32_16x16x32_bf16 v[118:121], v[148:151], v[194:197], v[118:121]
	v_mfma_f32_16x16x32_bf16 v[114:117], v[156:159], v[194:197], v[114:117]
	v_mfma_f32_16x16x32_bf16 v[110:113], v[148:151], v[202:205], v[110:113]
	v_mfma_f32_16x16x32_bf16 v[106:109], v[156:159], v[202:205], v[106:109]
	v_mfma_f32_16x16x32_bf16 v[102:105], v[148:151], v[210:213], v[102:105]
	v_mfma_f32_16x16x32_bf16 v[98:101], v[156:159], v[210:213], v[98:101]
	v_mfma_f32_16x16x32_bf16 v[126:129], v[152:155], v[190:193], v[126:129]
	v_mfma_f32_16x16x32_bf16 v[122:125], v[166:169], v[190:193], v[122:125]
	v_mfma_f32_16x16x32_bf16 v[118:121], v[152:155], v[198:201], v[118:121]
	v_mfma_f32_16x16x32_bf16 v[114:117], v[166:169], v[198:201], v[114:117]
	v_mfma_f32_16x16x32_bf16 v[110:113], v[152:155], v[206:209], v[110:113]
	v_mfma_f32_16x16x32_bf16 v[106:109], v[166:169], v[206:209], v[106:109]
	v_mfma_f32_16x16x32_bf16 v[102:105], v[152:155], v[214:217], v[102:105]
	v_mfma_f32_16x16x32_bf16 v[98:101], v[166:169], v[214:217], v[98:101]
	v_mfma_f32_16x16x32_bf16 v[94:97], v[170:173], v[186:189], v[94:97]
	v_mfma_f32_16x16x32_bf16 v[90:93], v[178:181], v[186:189], v[90:93]
	v_mfma_f32_16x16x32_bf16 v[86:89], v[170:173], v[194:197], v[86:89]
	v_mfma_f32_16x16x32_bf16 v[82:85], v[178:181], v[194:197], v[82:85]
	v_mfma_f32_16x16x32_bf16 v[78:81], v[170:173], v[202:205], v[78:81]
	v_mfma_f32_16x16x32_bf16 v[74:77], v[178:181], v[202:205], v[74:77]
	v_mfma_f32_16x16x32_bf16 v[70:73], v[170:173], v[210:213], v[70:73]
	v_mfma_f32_16x16x32_bf16 v[66:69], v[178:181], v[210:213], v[66:69]
	v_mfma_f32_16x16x32_bf16 v[94:97], v[174:177], v[190:193], v[94:97]
	v_mfma_f32_16x16x32_bf16 v[90:93], v[182:185], v[190:193], v[90:93]
	v_mfma_f32_16x16x32_bf16 v[86:89], v[174:177], v[198:201], v[86:89]
	v_mfma_f32_16x16x32_bf16 v[82:85], v[182:185], v[198:201], v[82:85]
	v_mfma_f32_16x16x32_bf16 v[78:81], v[174:177], v[206:209], v[78:81]
	v_mfma_f32_16x16x32_bf16 v[74:77], v[182:185], v[206:209], v[74:77]
	v_mfma_f32_16x16x32_bf16 v[70:73], v[174:177], v[214:217], v[70:73]
	v_mfma_f32_16x16x32_bf16 v[66:69], v[182:185], v[214:217], v[66:69]
	s_setprio 0
	s_barrier
; #define PG8_STAGE(bufoff, gbase, voff) do { _Pragma("unroll") for (int _i = 0; _i < 2; ++_i) \
;         __builtin_amdgcn_global_load_lds((const unsigned*)((const char*)(gbase) + (voff)[_i]), (PG8_LAS unsigned*)(lds + (bufoff) + ldsw + _i * 8192), 16, 0, 0); } while (0)
; #define PG8_LDA(dst, b, h) do { _Pragma("unroll") for (int m = 0; m < 4; ++m) _Pragma("unroll") for (int k = 0; k < 2; ++k) dst[m][k] = *(const PG8_LAS bf16x8*)(lds + PG8_SA(b, h) + aoff + m * 2048 + k * 1024); } while (0)
; #define PG8_MMA(ai, bj, At, Bt) do { __builtin_amdgcn_s_setprio(1); _Pragma("unroll") for (int m = 0; m < 4; ++m) _Pragma("unroll") for (int n = 0; n < 2; ++n) _Pragma("unroll") for (int k = 0; k < 2; ++k) \
;         acc[ai][bj][m][n] = __builtin_amdgcn_mfma_f32_16x16x32_bf16(Bt[n][k], At[m][k], acc[ai][bj][m][n], 0, 0, 0); __builtin_amdgcn_s_setprio(0); } while (0)
; #define PG8_WAIT_V(n) asm volatile("s_waitcnt vmcnt(" #n ")" ::: "memory")
; #define PG8_WAIT_L(n) asm volatile("s_waitcnt lgkmcnt(" #n ")" ::: "memory")
; #define PG8_BAR __builtin_amdgcn_s_barrier()
; #define PG8_SCHED __builtin_amdgcn_sched_barrier(0)
; template <class Epi, class Sched, bool ALIGN_EPI = false, bool SP2 = false>
; __device__ __forceinline__ void gemm_phase(PG8_LAS unsigned char* lds, const Gemm g, const Sched& S, const Epi& E, const int wave_id) {
;     ...
;             PG8_LDA(At, 1, 1); PG8_STAGE(PG8_SB(1, 0), b3, voffB); PG8_STAGE(PG8_SB(1, 1), b3 + hstep, voffB); PG8_STAGE(PG8_SA(1, 0), a3, voffA);
;             PG8_WAIT_V(8); PG8_WAIT_L(0); PG8_BAR; PG8_MMA(1, 0, At, B0); PG8_MMA(1, 1, At, B1); PG8_BAR; PG8_SCHED;
;     ...
;         if constexpr (ALIGN_EPI) { if (wr == 0) PG8_BAR; }
	s_add_i32 s26, s53, s35
	v_lshl_add_u64 v[160:161], v[160:161], 0, s[64:65]
	s_mov_b32 m0, s26
	ds_read_b128 v[186:189], v164 offset:49152
	ds_read_b128 v[190:193], v164 offset:50176
	ds_read_b128 v[194:197], v164 offset:51200
	ds_read_b128 v[198:201], v164 offset:52224
	ds_read_b128 v[202:205], v164 offset:53248
	ds_read_b128 v[206:209], v164 offset:54272
	ds_read_b128 v[210:213], v164 offset:55296
	ds_read_b128 v[214:217], v164 offset:56320
	global_load_lds_dwordx4 v[160:161], off
	s_add_i32 m0, s26, 0x2000
	s_add_u32 s12, s12, 0x40080
	v_lshl_add_u64 v[160:161], v[218:219], 0, s[64:65]
	s_addc_u32 s13, s13, 0
	s_add_i32 s26, s76, s35
	global_load_lds_dwordx4 v[160:161], off
	v_lshl_add_u64 v[160:161], s[12:13], 0, v[132:133]
	s_mov_b32 m0, s26
	s_nop 0
	global_load_lds_dwordx4 v[160:161], off
	v_lshl_add_u64 v[160:161], s[12:13], 0, v[136:137]
	s_add_i32 m0, s26, 0x2000
	s_nop 0
	global_load_lds_dwordx4 v[160:161], off
	v_lshl_add_u64 v[160:161], v[220:221], 0, s[64:65]
	s_mov_b32 m0, s41
	s_nop 0
	global_load_lds_dwordx4 v[160:161], off
	v_lshl_add_u64 v[160:161], v[222:223], 0, s[64:65]
	s_mov_b32 m0, s42
	s_nop 0
	global_load_lds_dwordx4 v[160:161], off
	s_waitcnt vmcnt(8)
	s_waitcnt lgkmcnt(0)
	s_setprio 1
	s_barrier
	v_mfma_f32_16x16x32_bf16 v[62:65], v[148:151], v[186:189], v[62:65]
	v_mfma_f32_16x16x32_bf16 v[58:61], v[156:159], v[186:189], v[58:61]
	v_mfma_f32_16x16x32_bf16 v[54:57], v[148:151], v[194:197], v[54:57]
	v_mfma_f32_16x16x32_bf16 v[50:53], v[156:159], v[194:197], v[50:53]
	v_mfma_f32_16x16x32_bf16 v[46:49], v[148:151], v[202:205], v[46:49]
	v_mfma_f32_16x16x32_bf16 v[42:45], v[156:159], v[202:205], v[42:45]
	v_mfma_f32_16x16x32_bf16 v[38:41], v[148:151], v[210:213], v[38:41]
	v_mfma_f32_16x16x32_bf16 v[34:37], v[156:159], v[210:213], v[34:37]
	v_mfma_f32_16x16x32_bf16 v[62:65], v[152:155], v[190:193], v[62:65]
	v_mfma_f32_16x16x32_bf16 v[58:61], v[166:169], v[190:193], v[58:61]
	v_mfma_f32_16x16x32_bf16 v[54:57], v[152:155], v[198:201], v[54:57]
	v_mfma_f32_16x16x32_bf16 v[50:53], v[166:169], v[198:201], v[50:53]
	v_mfma_f32_16x16x32_bf16 v[46:49], v[152:155], v[206:209], v[46:49]
	v_mfma_f32_16x16x32_bf16 v[42:45], v[166:169], v[206:209], v[42:45]
	v_mfma_f32_16x16x32_bf16 v[38:41], v[152:155], v[214:217], v[38:41]
	v_mfma_f32_16x16x32_bf16 v[34:37], v[166:169], v[214:217], v[34:37]
	v_mfma_f32_16x16x32_bf16 v[30:33], v[170:173], v[186:189], v[30:33]
	v_mfma_f32_16x16x32_bf16 v[26:29], v[178:181], v[186:189], v[26:29]
	v_mfma_f32_16x16x32_bf16 v[22:25], v[170:173], v[194:197], v[22:25]
	v_mfma_f32_16x16x32_bf16 v[18:21], v[178:181], v[194:197], v[18:21]
	v_mfma_f32_16x16x32_bf16 v[14:17], v[170:173], v[202:205], v[14:17]
	v_mfma_f32_16x16x32_bf16 v[10:13], v[178:181], v[202:205], v[10:13]
	v_mfma_f32_16x16x32_bf16 v[6:9], v[170:173], v[210:213], v[6:9]
	v_mfma_f32_16x16x32_bf16 v[2:5], v[178:181], v[210:213], v[2:5]
	v_mfma_f32_16x16x32_bf16 v[30:33], v[174:177], v[190:193], v[30:33]
	v_mfma_f32_16x16x32_bf16 v[26:29], v[182:185], v[190:193], v[26:29]
	v_mfma_f32_16x16x32_bf16 v[22:25], v[174:177], v[198:201], v[22:25]
	v_mfma_f32_16x16x32_bf16 v[18:21], v[182:185], v[198:201], v[18:21]
	v_mfma_f32_16x16x32_bf16 v[14:17], v[174:177], v[206:209], v[14:17]
	v_mfma_f32_16x16x32_bf16 v[10:13], v[182:185], v[206:209], v[10:13]
	v_mfma_f32_16x16x32_bf16 v[6:9], v[174:177], v[214:217], v[6:9]
	v_mfma_f32_16x16x32_bf16 v[2:5], v[182:185], v[214:217], v[2:5]
	s_setprio 0
	s_barrier
	s_add_u32 s10, s10, 0x100
	s_addc_u32 s11, s11, 0
	s_cmp_gt_u32 s69, 13
	s_cbranch_scc0 .LBB0_1537
	s_and_b64 vcc, exec, s[24:25]
	s_cbranch_vccz .LBB0_1540
	s_barrier

; #define PG8_STAGE(bufoff, gbase, voff) do { _Pragma("unroll") for (int _i = 0; _i < 2; ++_i) \
;         __builtin_amdgcn_global_load_lds((const unsigned*)((const char*)(gbase) + (voff)[_i]), (PG8_LAS unsigned*)(lds + (bufoff) + ldsw + _i * 8192), 16, 0, 0); } while (0)
; #define PG8_LDA(dst, b, h) do { _Pragma("unroll") for (int m = 0; m < 4; ++m) _Pragma("unroll") for (int k = 0; k < 2; ++k) dst[m][k] = *(const PG8_LAS bf16x8*)(lds + PG8_SA(b, h) + aoff + m * 2048 + k * 1024); } while (0)
; #define PG8_LDB(dst, b, h) do { _Pragma("unroll") for (int n = 0; n < 2; ++n) _Pragma("unroll") for (int k = 0; k < 2; ++k) dst[n][k] = *(const PG8_LAS bf16x8*)(lds + PG8_SB(b, h) + boff + n * 2048 + k * 1024); } while (0)
; #define PG8_WAIT_V(n) asm volatile("s_waitcnt vmcnt(" #n ")" ::: "memory")
; #define PG8_WAIT_VN(n) asm volatile("s_waitcnt vmcnt(%0)" :: "n"(n) : "memory")
; #define PG8_WAIT_L(n) asm volatile("s_waitcnt lgkmcnt(" #n ")" ::: "memory")
; #define PG8_BAR __builtin_amdgcn_s_barrier()
; #define PG8_SCHED __builtin_amdgcn_sched_barrier(0)
; template <class Epi, class Sched, bool ALIGN_EPI = false, bool SP2 = false>
; __device__ __forceinline__ void gemm_phase(PG8_LAS unsigned char* lds, const Gemm g, const Sched& S, const Epi& E, const int wave_id) {
;     ...
;             const char* a1 = cA + (size_t)(t + 1) * kstep;
;             const char* a2 = last ? nA : cA + (size_t)(t + 2) * kstep; const char* b2 = last ? nB : cB + (size_t)(t + 2) * kstep;
;             const char* a3 = a2 + kstep; const char* b3 = b2 + kstep;
;             if (last && has_next) S.a_ready(nxt);
;             if constexpr (SP2) {
;             int tz_ = __builtin_amdgcn_readfirstlane(t | (ui > 0 ? 0 : 1)); asm volatile("" : "+s"(tz_));
;             const bool strict = !(Epi::NS > 0 && tz_ == 0);
;             PG8_LDB(B0, 0, 0); PG8_LDB(B1, 0, 1); PG8_SCHED; PG8_LDA(At, 0, 0); PG8_STAGE(PG8_SA(1, 1), a1 + hstep, voffA);
;             PG8_WAIT_VN(8 + Epi::NS); if (strict) PG8_WAIT_V(8); PG8_WAIT_L(0); PG8_BAR; PG8_MMA(0, 0, At, B0); PG8_MMA(0, 1, At, B1); PG8_BAR; PG8_SCHED;
;             PG8_LDA(At, 0, 1); PG8_STAGE(PG8_SB(0, 0), b2, voffB); PG8_STAGE(PG8_SB(0, 1), b2 + hstep, voffB); PG8_STAGE(PG8_SA(0, 0), a2, voffA);
;             PG8_WAIT_VN(8 + Epi::NS); if (strict) PG8_WAIT_V(8); PG8_WAIT_L(0); PG8_BAR; PG8_MMA(1, 0, At, B0); PG8_MMA(1, 1, At, B1); PG8_BAR; PG8_SCHED;
.LBB0_1685:
	s_add_u32 s24, s20, s22
	s_addc_u32 s25, s21, s23
	s_add_u32 s24, s24, 0x100
	s_addc_u32 s25, s25, 0
	s_add_u32 s53, s52, s22
	s_addc_u32 s57, s54, s23
	s_add_i32 s56, s56, 2
	s_add_i32 s62, 0, 0x10000
	v_add_u32_e32 v147, s56, v146
	s_cmpk_eq_i32 s22, 0x700
	s_cselect_b32 s26, s11, s24
	v_readfirstlane_b32 s24, v147
	s_cselect_b32 s27, s9, s25
	v_add_u32_e32 v147, s62, v163
	s_cselect_b32 s25, s13, s57
	s_cselect_b32 s24, s15, s53
	s_add_i32 s53, 0, 0x14000
	ds_read_b128 v[148:151], v147
	ds_read_b128 v[152:155], v147 offset:1024
	ds_read_b128 v[156:159], v147 offset:2048
	ds_read_b128 v[166:169], v147 offset:3072
	v_add_u32_e32 v147, s53, v163
	ds_read_b128 v[170:173], v147
	ds_read_b128 v[174:177], v147 offset:1024
	ds_read_b128 v[178:181], v147 offset:2048
	ds_read_b128 v[182:185], v147 offset:3072
	v_lshl_add_u64 v[160:161], v[144:145], 0, s[22:23]
	s_add_i32 m0, s38, 0xc000
	ds_read_b128 v[186:189], v164
	ds_read_b128 v[190:193], v164 offset:1024
	ds_read_b128 v[194:197], v164 offset:2048
	ds_read_b128 v[198:201], v164 offset:3072
	ds_read_b128 v[202:205], v164 offset:4096
	ds_read_b128 v[206:209], v164 offset:5120
	ds_read_b128 v[210:213], v164 offset:6144
	ds_read_b128 v[214:217], v164 offset:7168
	global_load_lds_dwordx4 v[160:161], off
	v_lshl_add_u64 v[160:161], v[142:143], 0, s[22:23]
	s_add_i32 m0, s38, 0xe000
	s_nop 0
	global_load_lds_dwordx4 v[160:161], off
	s_waitcnt vmcnt(8)
	s_waitcnt vmcnt(8)
	s_waitcnt lgkmcnt(0)
	s_setprio 1
	s_barrier
	v_mfma_f32_16x16x32_bf16 v[126:129], v[148:151], v[186:189], v[126:129]
	v_mfma_f32_16x16x32_bf16 v[122:125], v[156:159], v[186:189], v[122:125]
	v_mfma_f32_16x16x32_bf16 v[118:121], v[148:151], v[194:197], v[118:121]
	v_mfma_f32_16x16x32_bf16 v[114:117], v[156:159], v[194:197], v[114:117]
	v_mfma_f32_16x16x32_bf16 v[110:113], v[148:151], v[202:205], v[110:113]
	v_mfma_f32_16x16x32_bf16 v[106:109], v[156:159], v[202:205], v[106:109]
	v_mfma_f32_16x16x32_bf16 v[102:105], v[148:151], v[210:213], v[102:105]
	v_mfma_f32_16x16x32_bf16 v[98:101], v[156:159], v[210:213], v[98:101]
	v_mfma_f32_16x16x32_bf16 v[126:129], v[152:155], v[190:193], v[126:129]
	v_mfma_f32_16x16x32_bf16 v[122:125], v[166:169], v[190:193], v[122:125]
	v_mfma_f32_16x16x32_bf16 v[118:121], v[152:155], v[198:201], v[118:121]
	v_mfma_f32_16x16x32_bf16 v[114:117], v[166:169], v[198:201], v[114:117]
	v_mfma_f32_16x16x32_bf16 v[110:113], v[152:155], v[206:209], v[110:113]
	v_mfma_f32_16x16x32_bf16 v[106:109], v[166:169], v[206:209], v[106:109]
	v_mfma_f32_16x16x32_bf16 v[102:105], v[152:155], v[214:217], v[102:105]
	v_mfma_f32_16x16x32_bf16 v[98:101], v[166:169], v[214:217], v[98:101]
	v_mfma_f32_16x16x32_bf16 v[94:97], v[170:173], v[186:189], v[94:97]
	v_mfma_f32_16x16x32_bf16 v[90:93], v[178:181], v[186:189], v[90:93]
	v_mfma_f32_16x16x32_bf16 v[86:89], v[170:173], v[194:197], v[86:89]
	v_mfma_f32_16x16x32_bf16 v[82:85], v[178:181], v[194:197], v[82:85]
	v_mfma_f32_16x16x32_bf16 v[78:81], v[170:173], v[202:205], v[78:81]
	v_mfma_f32_16x16x32_bf16 v[74:77], v[178:181], v[202:205], v[74:77]
	v_mfma_f32_16x16x32_bf16 v[70:73], v[170:173], v[210:213], v[70:73]
	v_mfma_f32_16x16x32_bf16 v[66:69], v[178:181], v[210:213], v[66:69]
	v_mfma_f32_16x16x32_bf16 v[94:97], v[174:177], v[190:193], v[94:97]
	v_mfma_f32_16x16x32_bf16 v[90:93], v[182:185], v[190:193], v[90:93]
	v_mfma_f32_16x16x32_bf16 v[86:89], v[174:177], v[198:201], v[86:89]
	v_mfma_f32_16x16x32_bf16 v[82:85], v[182:185], v[198:201], v[82:85]
	v_mfma_f32_16x16x32_bf16 v[78:81], v[174:177], v[206:209], v[78:81]
	v_mfma_f32_16x16x32_bf16 v[74:77], v[182:185], v[206:209], v[74:77]
	v_mfma_f32_16x16x32_bf16 v[70:73], v[174:177], v[214:217], v[70:73]
	v_mfma_f32_16x16x32_bf16 v[66:69], v[182:185], v[214:217], v[66:69]
	s_setprio 0
	s_barrier
	s_add_i32 s57, s62, s37
	v_lshl_add_u64 v[160:161], s[24:25], 0, v[132:133]
	s_mov_b32 m0, s57
	ds_read_b128 v[186:189], v164 offset:16384
	ds_read_b128 v[190:193], v164 offset:17408
	ds_read_b128 v[194:197], v164 offset:18432
	ds_read_b128 v[198:201], v164 offset:19456
	ds_read_b128 v[202:205], v164 offset:20480
	ds_read_b128 v[206:209], v164 offset:21504
	ds_read_b128 v[210:213], v164 offset:22528
	ds_read_b128 v[214:217], v164 offset:23552
	global_load_lds_dwordx4 v[160:161], off
	s_add_i32 m0, s57, 0x2000
	s_add_u32 s62, s24, 0x40000
	v_lshl_add_u64 v[218:219], s[24:25], 0, v[136:137]
	s_addc_u32 s63, s25, 0
	s_add_i32 s53, s53, s37
	global_load_lds_dwordx4 v[218:219], off
	v_lshl_add_u64 v[220:221], s[62:63], 0, v[132:133]
	s_mov_b32 m0, s53
	v_lshl_add_u64 v[222:223], s[26:27], 0, v[134:135]
	global_load_lds_dwordx4 v[220:221], off
	v_lshl_add_u64 v[220:221], s[62:63], 0, v[136:137]
	s_add_i32 m0, s53, 0x2000
	s_nop 0
	global_load_lds_dwordx4 v[220:221], off
	v_lshl_add_u64 v[220:221], s[26:27], 0, v[130:131]
	s_mov_b32 m0, s38
	s_nop 0
	global_load_lds_dwordx4 v[220:221], off
	s_mov_b32 m0, s39
	s_nop 0
	global_load_lds_dwordx4 v[222:223], off
	s_waitcnt vmcnt(8)
	s_waitcnt vmcnt(8)
	s_waitcnt lgkmcnt(0)
	s_setprio 1
	s_barrier
; #define PG8_STAGE(bufoff, gbase, voff) do { _Pragma("unroll") for (int _i = 0; _i < 2; ++_i) \
;         __builtin_amdgcn_global_load_lds((const unsigned*)((const char*)(gbase) + (voff)[_i]), (PG8_LAS unsigned*)(lds + (bufoff) + ldsw + _i * 8192), 16, 0, 0); } while (0)
; #define PG8_LDA(dst, b, h) do { _Pragma("unroll") for (int m = 0; m < 4; ++m) _Pragma("unroll") for (int k = 0; k < 2; ++k) dst[m][k] = *(const PG8_LAS bf16x8*)(lds + PG8_SA(b, h) + aoff + m * 2048 + k * 1024); } while (0)
; #define PG8_LDB(dst, b, h) do { _Pragma("unroll") for (int n = 0; n < 2; ++n) _Pragma("unroll") for (int k = 0; k < 2; ++k) dst[n][k] = *(const PG8_LAS bf16x8*)(lds + PG8_SB(b, h) + boff + n * 2048 + k * 1024); } while (0)
; #define PG8_MMA(ai, bj, At, Bt) do { __builtin_amdgcn_s_setprio(1); _Pragma("unroll") for (int m = 0; m < 4; ++m) _Pragma("unroll") for (int n = 0; n < 2; ++n) _Pragma("unroll") for (int k = 0; k < 2; ++k) \
;         acc[ai][bj][m][n] = __builtin_amdgcn_mfma_f32_16x16x32_bf16(Bt[n][k], At[m][k], acc[ai][bj][m][n], 0, 0, 0); __builtin_amdgcn_s_setprio(0); } while (0)
; #define PG8_WAIT_V(n) asm volatile("s_waitcnt vmcnt(" #n ")" ::: "memory")
; #define PG8_WAIT_VN(n) asm volatile("s_waitcnt vmcnt(%0)" :: "n"(n) : "memory")
; #define PG8_WAIT_L(n) asm volatile("s_waitcnt lgkmcnt(" #n ")" ::: "memory")
; #define PG8_BAR __builtin_amdgcn_s_barrier()
; #define PG8_SCHED __builtin_amdgcn_sched_barrier(0)
; template <class Epi, class Sched, bool ALIGN_EPI = false, bool SP2 = false>
; __device__ __forceinline__ void gemm_phase(PG8_LAS unsigned char* lds, const Gemm g, const Sched& S, const Epi& E, const int wave_id) {
;     ...
;             PG8_WAIT_VN(8 + Epi::NS); if (strict) PG8_WAIT_V(8); PG8_WAIT_L(0); PG8_BAR; PG8_MMA(1, 0, At, B0); PG8_MMA(1, 1, At, B1); PG8_BAR; PG8_SCHED;
;             PG8_LDB(B0, 1, 0); PG8_LDB(B1, 1, 1); PG8_SCHED; PG8_LDA(At, 1, 0); PG8_STAGE(PG8_SA(0, 1), a2 + hstep, voffA);
;             PG8_WAIT_V(8); PG8_WAIT_L(0); PG8_BAR; PG8_MMA(0, 0, At, B0); PG8_MMA(0, 1, At, B1); PG8_BAR; PG8_SCHED;
	v_mfma_f32_16x16x32_bf16 v[62:65], v[148:151], v[186:189], v[62:65]
	v_mfma_f32_16x16x32_bf16 v[58:61], v[156:159], v[186:189], v[58:61]
	v_mfma_f32_16x16x32_bf16 v[54:57], v[148:151], v[194:197], v[54:57]
	v_mfma_f32_16x16x32_bf16 v[50:53], v[156:159], v[194:197], v[50:53]
	v_mfma_f32_16x16x32_bf16 v[46:49], v[148:151], v[202:205], v[46:49]
	v_mfma_f32_16x16x32_bf16 v[42:45], v[156:159], v[202:205], v[42:45]
	v_mfma_f32_16x16x32_bf16 v[38:41], v[148:151], v[210:213], v[38:41]
	v_mfma_f32_16x16x32_bf16 v[34:37], v[156:159], v[210:213], v[34:37]
	v_mfma_f32_16x16x32_bf16 v[62:65], v[152:155], v[190:193], v[62:65]
	v_mfma_f32_16x16x32_bf16 v[58:61], v[166:169], v[190:193], v[58:61]
	v_mfma_f32_16x16x32_bf16 v[54:57], v[152:155], v[198:201], v[54:57]
	v_mfma_f32_16x16x32_bf16 v[50:53], v[166:169], v[198:201], v[50:53]
	v_mfma_f32_16x16x32_bf16 v[46:49], v[152:155], v[206:209], v[46:49]
	v_mfma_f32_16x16x32_bf16 v[42:45], v[166:169], v[206:209], v[42:45]
	v_mfma_f32_16x16x32_bf16 v[38:41], v[152:155], v[214:217], v[38:41]
	v_mfma_f32_16x16x32_bf16 v[34:37], v[166:169], v[214:217], v[34:37]
	v_mfma_f32_16x16x32_bf16 v[30:33], v[170:173], v[186:189], v[30:33]
	v_mfma_f32_16x16x32_bf16 v[26:29], v[178:181], v[186:189], v[26:29]
	v_mfma_f32_16x16x32_bf16 v[22:25], v[170:173], v[194:197], v[22:25]
	v_mfma_f32_16x16x32_bf16 v[18:21], v[178:181], v[194:197], v[18:21]
	v_mfma_f32_16x16x32_bf16 v[14:17], v[170:173], v[202:205], v[14:17]
	v_mfma_f32_16x16x32_bf16 v[10:13], v[178:181], v[202:205], v[10:13]
	v_mfma_f32_16x16x32_bf16 v[6:9], v[170:173], v[210:213], v[6:9]
	v_mfma_f32_16x16x32_bf16 v[2:5], v[178:181], v[210:213], v[2:5]
	v_mfma_f32_16x16x32_bf16 v[30:33], v[174:177], v[190:193], v[30:33]
	v_mfma_f32_16x16x32_bf16 v[26:29], v[182:185], v[190:193], v[26:29]
	v_mfma_f32_16x16x32_bf16 v[22:25], v[174:177], v[198:201], v[22:25]
	v_mfma_f32_16x16x32_bf16 v[18:21], v[182:185], v[198:201], v[18:21]
	v_mfma_f32_16x16x32_bf16 v[14:17], v[174:177], v[206:209], v[14:17]
	v_mfma_f32_16x16x32_bf16 v[10:13], v[182:185], v[206:209], v[10:13]
	v_mfma_f32_16x16x32_bf16 v[6:9], v[174:177], v[214:217], v[6:9]
	v_mfma_f32_16x16x32_bf16 v[2:5], v[182:185], v[214:217], v[2:5]
	s_setprio 0
	s_barrier
	s_add_i32 s53, 0, 0x18000
	v_add_u32_e32 v147, s53, v163
	s_add_i32 s57, 0, 0x1c000
	ds_read_b128 v[148:151], v147
	ds_read_b128 v[152:155], v147 offset:1024
	ds_read_b128 v[156:159], v147 offset:2048
	ds_read_b128 v[166:169], v147 offset:3072
	v_add_u32_e32 v147, s57, v163
	ds_read_b128 v[170:173], v147
	ds_read_b128 v[174:177], v147 offset:1024
	ds_read_b128 v[178:181], v147 offset:2048
	ds_read_b128 v[182:185], v147 offset:3072
	s_add_u32 s26, s26, 0x40000
	s_addc_u32 s27, s27, 0
	s_mov_b32 m0, s40
	v_lshl_add_u64 v[224:225], s[26:27], 0, v[130:131]
	ds_read_b128 v[186:189], v164 offset:32768
	ds_read_b128 v[190:193], v164 offset:33792
	ds_read_b128 v[194:197], v164 offset:34816
	ds_read_b128 v[198:201], v164 offset:35840
	ds_read_b128 v[202:205], v164 offset:36864
	ds_read_b128 v[206:209], v164 offset:37888
	ds_read_b128 v[210:213], v164 offset:38912
	ds_read_b128 v[214:217], v164 offset:39936
	global_load_lds_dwordx4 v[224:225], off
	v_lshl_add_u64 v[224:225], s[26:27], 0, v[134:135]
	s_mov_b32 m0, s41
	s_nop 0
	global_load_lds_dwordx4 v[224:225], off
	s_waitcnt vmcnt(8)
	s_waitcnt lgkmcnt(0)
	s_setprio 1
	s_barrier
	v_mfma_f32_16x16x32_bf16 v[126:129], v[148:151], v[186:189], v[126:129]
	v_mfma_f32_16x16x32_bf16 v[122:125], v[156:159], v[186:189], v[122:125]
	v_mfma_f32_16x16x32_bf16 v[118:121], v[148:151], v[194:197], v[118:121]
	v_mfma_f32_16x16x32_bf16 v[114:117], v[156:159], v[194:197], v[114:117]
	v_mfma_f32_16x16x32_bf16 v[110:113], v[148:151], v[202:205], v[110:113]
	v_mfma_f32_16x16x32_bf16 v[106:109], v[156:159], v[202:205], v[106:109]
	v_mfma_f32_16x16x32_bf16 v[102:105], v[148:151], v[210:213], v[102:105]
	v_mfma_f32_16x16x32_bf16 v[98:101], v[156:159], v[210:213], v[98:101]
	v_mfma_f32_16x16x32_bf16 v[126:129], v[152:155], v[190:193], v[126:129]
	v_mfma_f32_16x16x32_bf16 v[122:125], v[166:169], v[190:193], v[122:125]
	v_mfma_f32_16x16x32_bf16 v[118:121], v[152:155], v[198:201], v[118:121]
	v_mfma_f32_16x16x32_bf16 v[114:117], v[166:169], v[198:201], v[114:117]
	v_mfma_f32_16x16x32_bf16 v[110:113], v[152:155], v[206:209], v[110:113]
	v_mfma_f32_16x16x32_bf16 v[106:109], v[166:169], v[206:209], v[106:109]
	v_mfma_f32_16x16x32_bf16 v[102:105], v[152:155], v[214:217], v[102:105]
	v_mfma_f32_16x16x32_bf16 v[98:101], v[166:169], v[214:217], v[98:101]
	v_mfma_f32_16x16x32_bf16 v[94:97], v[170:173], v[186:189], v[94:97]
	v_mfma_f32_16x16x32_bf16 v[90:93], v[178:181], v[186:189], v[90:93]
	v_mfma_f32_16x16x32_bf16 v[86:89], v[170:173], v[194:197], v[86:89]
	v_mfma_f32_16x16x32_bf16 v[82:85], v[178:181], v[194:197], v[82:85]
	v_mfma_f32_16x16x32_bf16 v[78:81], v[170:173], v[202:205], v[78:81]
	v_mfma_f32_16x16x32_bf16 v[74:77], v[178:181], v[202:205], v[74:77]
	v_mfma_f32_16x16x32_bf16 v[70:73], v[170:173], v[210:213], v[70:73]
	v_mfma_f32_16x16x32_bf16 v[66:69], v[178:181], v[210:213], v[66:69]
	v_mfma_f32_16x16x32_bf16 v[94:97], v[174:177], v[190:193], v[94:97]
	v_mfma_f32_16x16x32_bf16 v[90:93], v[182:185], v[190:193], v[90:93]
	v_mfma_f32_16x16x32_bf16 v[86:89], v[174:177], v[198:201], v[86:89]
	v_mfma_f32_16x16x32_bf16 v[82:85], v[182:185], v[198:201], v[82:85]
	v_mfma_f32_16x16x32_bf16 v[78:81], v[174:177], v[206:209], v[78:81]
	v_mfma_f32_16x16x32_bf16 v[74:77], v[182:185], v[206:209], v[74:77]
	v_mfma_f32_16x16x32_bf16 v[70:73], v[174:177], v[214:217], v[70:73]
	v_mfma_f32_16x16x32_bf16 v[66:69], v[182:185], v[214:217], v[66:69]
	s_setprio 0
	s_barrier
; #define PG8_STAGE(bufoff, gbase, voff) do { _Pragma("unroll") for (int _i = 0; _i < 2; ++_i) \
;         __builtin_amdgcn_global_load_lds((const unsigned*)((const char*)(gbase) + (voff)[_i]), (PG8_LAS unsigned*)(lds + (bufoff) + ldsw + _i * 8192), 16, 0, 0); } while (0)
; #define PG8_LDA(dst, b, h) do { _Pragma("unroll") for (int m = 0; m < 4; ++m) _Pragma("unroll") for (int k = 0; k < 2; ++k) dst[m][k] = *(const PG8_LAS bf16x8*)(lds + PG8_SA(b, h) + aoff + m * 2048 + k * 1024); } while (0)
; #define PG8_MMA(ai, bj, At, Bt) do { __builtin_amdgcn_s_setprio(1); _Pragma("unroll") for (int m = 0; m < 4; ++m) _Pragma("unroll") for (int n = 0; n < 2; ++n) _Pragma("unroll") for (int k = 0; k < 2; ++k) \
;         acc[ai][bj][m][n] = __builtin_amdgcn_mfma_f32_16x16x32_bf16(Bt[n][k], At[m][k], acc[ai][bj][m][n], 0, 0, 0); __builtin_amdgcn_s_setprio(0); } while (0)
; #define PG8_WAIT_V(n) asm volatile("s_waitcnt vmcnt(" #n ")" ::: "memory")
; #define PG8_WAIT_L(n) asm volatile("s_waitcnt lgkmcnt(" #n ")" ::: "memory")
; #define PG8_BAR __builtin_amdgcn_s_barrier()
; #define PG8_SCHED __builtin_amdgcn_sched_barrier(0)
; template <class Epi, class Sched, bool ALIGN_EPI = false, bool SP2 = false>
; __device__ __forceinline__ void gemm_phase(PG8_LAS unsigned char* lds, const Gemm g, const Sched& S, const Epi& E, const int wave_id) {
;     ...
;             PG8_LDA(At, 1, 1); PG8_STAGE(PG8_SB(1, 0), b3, voffB); PG8_STAGE(PG8_SB(1, 1), b3 + hstep, voffB); PG8_STAGE(PG8_SA(1, 0), a3, voffA);
;             PG8_WAIT_V(8); PG8_WAIT_L(0); PG8_BAR; PG8_MMA(1, 0, At, B0); PG8_MMA(1, 1, At, B1); PG8_BAR; PG8_SCHED;
;     ...
;         if constexpr (ALIGN_EPI) { if (wr == 0) PG8_BAR; }
	s_add_i32 s26, s53, s37
	v_lshl_add_u64 v[160:161], v[160:161], 0, s[64:65]
	s_mov_b32 m0, s26
	ds_read_b128 v[186:189], v164 offset:49152
	ds_read_b128 v[190:193], v164 offset:50176
	ds_read_b128 v[194:197], v164 offset:51200
	ds_read_b128 v[198:201], v164 offset:52224
	ds_read_b128 v[202:205], v164 offset:53248
	ds_read_b128 v[206:209], v164 offset:54272
	ds_read_b128 v[210:213], v164 offset:55296
	ds_read_b128 v[214:217], v164 offset:56320
	global_load_lds_dwordx4 v[160:161], off
	s_add_i32 m0, s26, 0x2000
	s_add_u32 s24, s24, 0x40080
	v_lshl_add_u64 v[160:161], v[218:219], 0, s[64:65]
	s_addc_u32 s25, s25, 0
	s_add_i32 s26, s57, s37
	global_load_lds_dwordx4 v[160:161], off
	v_lshl_add_u64 v[160:161], s[24:25], 0, v[132:133]
	s_mov_b32 m0, s26
	s_nop 0
	global_load_lds_dwordx4 v[160:161], off
	v_lshl_add_u64 v[160:161], s[24:25], 0, v[136:137]
	s_add_i32 m0, s26, 0x2000
	s_nop 0
	global_load_lds_dwordx4 v[160:161], off
	v_lshl_add_u64 v[160:161], v[220:221], 0, s[64:65]
	s_mov_b32 m0, s43
	s_nop 0
	global_load_lds_dwordx4 v[160:161], off
	v_lshl_add_u64 v[160:161], v[222:223], 0, s[64:65]
	s_mov_b32 m0, s49
	s_nop 0
	global_load_lds_dwordx4 v[160:161], off
	s_waitcnt vmcnt(8)
	s_waitcnt lgkmcnt(0)
	s_setprio 1
	s_barrier
	v_mfma_f32_16x16x32_bf16 v[62:65], v[148:151], v[186:189], v[62:65]
	v_mfma_f32_16x16x32_bf16 v[58:61], v[156:159], v[186:189], v[58:61]
	v_mfma_f32_16x16x32_bf16 v[54:57], v[148:151], v[194:197], v[54:57]
	v_mfma_f32_16x16x32_bf16 v[50:53], v[156:159], v[194:197], v[50:53]
	v_mfma_f32_16x16x32_bf16 v[46:49], v[148:151], v[202:205], v[46:49]
	v_mfma_f32_16x16x32_bf16 v[42:45], v[156:159], v[202:205], v[42:45]
	v_mfma_f32_16x16x32_bf16 v[38:41], v[148:151], v[210:213], v[38:41]
	v_mfma_f32_16x16x32_bf16 v[34:37], v[156:159], v[210:213], v[34:37]
	v_mfma_f32_16x16x32_bf16 v[62:65], v[152:155], v[190:193], v[62:65]
	v_mfma_f32_16x16x32_bf16 v[58:61], v[166:169], v[190:193], v[58:61]
	v_mfma_f32_16x16x32_bf16 v[54:57], v[152:155], v[198:201], v[54:57]
	v_mfma_f32_16x16x32_bf16 v[50:53], v[166:169], v[198:201], v[50:53]
	v_mfma_f32_16x16x32_bf16 v[46:49], v[152:155], v[206:209], v[46:49]
	v_mfma_f32_16x16x32_bf16 v[42:45], v[166:169], v[206:209], v[42:45]
	v_mfma_f32_16x16x32_bf16 v[38:41], v[152:155], v[214:217], v[38:41]
	v_mfma_f32_16x16x32_bf16 v[34:37], v[166:169], v[214:217], v[34:37]
	v_mfma_f32_16x16x32_bf16 v[30:33], v[170:173], v[186:189], v[30:33]
	v_mfma_f32_16x16x32_bf16 v[26:29], v[178:181], v[186:189], v[26:29]
	v_mfma_f32_16x16x32_bf16 v[22:25], v[170:173], v[194:197], v[22:25]
	v_mfma_f32_16x16x32_bf16 v[18:21], v[178:181], v[194:197], v[18:21]
	v_mfma_f32_16x16x32_bf16 v[14:17], v[170:173], v[202:205], v[14:17]
	v_mfma_f32_16x16x32_bf16 v[10:13], v[178:181], v[202:205], v[10:13]
	v_mfma_f32_16x16x32_bf16 v[6:9], v[170:173], v[210:213], v[6:9]
	v_mfma_f32_16x16x32_bf16 v[2:5], v[178:181], v[210:213], v[2:5]
	v_mfma_f32_16x16x32_bf16 v[30:33], v[174:177], v[190:193], v[30:33]
	v_mfma_f32_16x16x32_bf16 v[26:29], v[182:185], v[190:193], v[26:29]
	v_mfma_f32_16x16x32_bf16 v[22:25], v[174:177], v[198:201], v[22:25]
	v_mfma_f32_16x16x32_bf16 v[18:21], v[182:185], v[198:201], v[18:21]
	v_mfma_f32_16x16x32_bf16 v[14:17], v[174:177], v[206:209], v[14:17]
	v_mfma_f32_16x16x32_bf16 v[10:13], v[182:185], v[206:209], v[10:13]
	v_mfma_f32_16x16x32_bf16 v[6:9], v[174:177], v[214:217], v[6:9]
	v_mfma_f32_16x16x32_bf16 v[2:5], v[182:185], v[214:217], v[2:5]
	s_setprio 0
	s_barrier
	s_add_u32 s22, s22, 0x100
	s_addc_u32 s23, s23, 0
	s_cmp_gt_u32 s56, 13
	s_cbranch_scc0 .LBB0_1685
	s_and_b64 vcc, exec, s[4:5]
	s_cbranch_vccz .LBB0_1688
	s_barrier

; #define PG8_STAGE(bufoff, gbase, voff) do { _Pragma("unroll") for (int _i = 0; _i < 2; ++_i) \
;         __builtin_amdgcn_global_load_lds((const unsigned*)((const char*)(gbase) + (voff)[_i]), (PG8_LAS unsigned*)(lds + (bufoff) + ldsw + _i * 8192), 16, 0, 0); } while (0)
; #define PG8_LDA(dst, b, h) do { _Pragma("unroll") for (int m = 0; m < 4; ++m) _Pragma("unroll") for (int k = 0; k < 2; ++k) dst[m][k] = *(const PG8_LAS bf16x8*)(lds + PG8_SA(b, h) + aoff + m * 2048 + k * 1024); } while (0)
; #define PG8_LDB(dst, b, h) do { _Pragma("unroll") for (int n = 0; n < 2; ++n) _Pragma("unroll") for (int k = 0; k < 2; ++k) dst[n][k] = *(const PG8_LAS bf16x8*)(lds + PG8_SB(b, h) + boff + n * 2048 + k * 1024); } while (0)
; #define PG8_MMA(ai, bj, At, Bt) do { __builtin_amdgcn_s_setprio(1); _Pragma("unroll") for (int m = 0; m < 4; ++m) _Pragma("unroll") for (int n = 0; n < 2; ++n) _Pragma("unroll") for (int k = 0; k < 2; ++k) \
;         acc[ai][bj][m][n] = __builtin_amdgcn_mfma_f32_16x16x32_bf16(Bt[n][k], At[m][k], acc[ai][bj][m][n], 0, 0, 0); __builtin_amdgcn_s_setprio(0); } while (0)
; #define PG8_WAIT_V(n) asm volatile("s_waitcnt vmcnt(" #n ")" ::: "memory")
; #define PG8_WAIT_VN(n) asm volatile("s_waitcnt vmcnt(%0)" :: "n"(n) : "memory")
; #define PG8_WAIT_L(n) asm volatile("s_waitcnt lgkmcnt(" #n ")" ::: "memory")
; #define PG8_BAR __builtin_amdgcn_s_barrier()
; #define PG8_SCHED __builtin_amdgcn_sched_barrier(0)
; template <class Epi, class Sched, bool ALIGN_EPI = false, bool SP2 = false>
; __device__ __forceinline__ void gemm_phase(PG8_LAS unsigned char* lds, const Gemm g, const Sched& S, const Epi& E, const int wave_id) {
;     ...
;             PG8_WAIT_VN(8 + Epi::NS); if (strict) PG8_WAIT_V(8); PG8_WAIT_L(0); PG8_BAR; PG8_MMA(1, 0, At, B0); PG8_MMA(1, 1, At, B1); PG8_BAR; PG8_SCHED;
;             PG8_LDB(B0, 1, 0); PG8_LDB(B1, 1, 1); PG8_SCHED; PG8_LDA(At, 1, 0); PG8_STAGE(PG8_SA(0, 1), a2 + hstep, voffA);
;             PG8_WAIT_V(8); PG8_WAIT_L(0); PG8_BAR; PG8_MMA(0, 0, At, B0); PG8_MMA(0, 1, At, B1); PG8_BAR; PG8_SCHED;
.LBB0_1821:
	s_waitcnt lgkmcnt(0)
	s_setprio 1
	s_barrier
	v_mfma_f32_16x16x32_bf16 v[62:65], v[146:149], v[186:189], v[62:65]
	v_mfma_f32_16x16x32_bf16 v[58:61], v[154:157], v[186:189], v[58:61]
	v_mfma_f32_16x16x32_bf16 v[46:49], v[146:149], v[178:181], v[46:49]
	v_mfma_f32_16x16x32_bf16 v[42:45], v[154:157], v[178:181], v[42:45]
	v_mfma_f32_16x16x32_bf16 v[30:33], v[146:149], v[170:173], v[30:33]
	v_mfma_f32_16x16x32_bf16 v[26:29], v[154:157], v[170:173], v[26:29]
	v_mfma_f32_16x16x32_bf16 v[14:17], v[146:149], v[162:165], v[14:17]
	v_mfma_f32_16x16x32_bf16 v[10:13], v[154:157], v[162:165], v[10:13]
	v_mfma_f32_16x16x32_bf16 v[62:65], v[150:153], v[190:193], v[62:65]
	v_mfma_f32_16x16x32_bf16 v[58:61], v[158:161], v[190:193], v[58:61]
	v_mfma_f32_16x16x32_bf16 v[46:49], v[150:153], v[182:185], v[46:49]
	v_mfma_f32_16x16x32_bf16 v[42:45], v[158:161], v[182:185], v[42:45]
	v_mfma_f32_16x16x32_bf16 v[30:33], v[150:153], v[174:177], v[30:33]
	v_mfma_f32_16x16x32_bf16 v[26:29], v[158:161], v[174:177], v[26:29]
	v_mfma_f32_16x16x32_bf16 v[14:17], v[150:153], v[166:169], v[14:17]
	v_mfma_f32_16x16x32_bf16 v[10:13], v[158:161], v[166:169], v[10:13]
	v_mfma_f32_16x16x32_bf16 v[54:57], v[130:133], v[186:189], v[54:57]
	v_mfma_f32_16x16x32_bf16 v[50:53], v[138:141], v[186:189], v[50:53]
	v_mfma_f32_16x16x32_bf16 v[38:41], v[130:133], v[178:181], v[38:41]
	v_mfma_f32_16x16x32_bf16 v[34:37], v[138:141], v[178:181], v[34:37]
	v_mfma_f32_16x16x32_bf16 v[22:25], v[130:133], v[170:173], v[22:25]
	v_mfma_f32_16x16x32_bf16 v[18:21], v[138:141], v[170:173], v[18:21]
	v_mfma_f32_16x16x32_bf16 v[6:9], v[130:133], v[162:165], v[6:9]
	v_mfma_f32_16x16x32_bf16 v[2:5], v[138:141], v[162:165], v[2:5]
	v_mfma_f32_16x16x32_bf16 v[54:57], v[134:137], v[190:193], v[54:57]
	v_mfma_f32_16x16x32_bf16 v[50:53], v[142:145], v[190:193], v[50:53]
	v_mfma_f32_16x16x32_bf16 v[38:41], v[134:137], v[182:185], v[38:41]
	v_mfma_f32_16x16x32_bf16 v[34:37], v[142:145], v[182:185], v[34:37]
	v_mfma_f32_16x16x32_bf16 v[22:25], v[134:137], v[174:177], v[22:25]
	v_mfma_f32_16x16x32_bf16 v[18:21], v[142:145], v[174:177], v[18:21]
	v_mfma_f32_16x16x32_bf16 v[6:9], v[134:137], v[166:169], v[6:9]
	v_mfma_f32_16x16x32_bf16 v[2:5], v[142:145], v[166:169], v[2:5]
	s_setprio 0
	s_barrier
	s_add_i32 s26, 0, 0x18000
	s_add_i32 s27, 0, 0x1c000
	v_add_u32_e32 v142, s26, v246
	v_add_u32_e32 v158, s27, v246
	ds_read_b128 v[130:133], v142
	ds_read_b128 v[134:137], v142 offset:1024
	ds_read_b128 v[138:141], v142 offset:2048
	ds_read_b128 v[142:145], v142 offset:3072
	ds_read_b128 v[146:149], v158
	ds_read_b128 v[150:153], v158 offset:1024
	ds_read_b128 v[154:157], v158 offset:2048
	ds_read_b128 v[158:161], v158 offset:3072
	s_add_u32 s24, s24, 0x40000
	s_addc_u32 s25, s25, 0
	s_mov_b32 m0, s50
	v_lshl_add_u64 v[194:195], s[24:25], 0, v[210:211]
	ds_read_b128 v[162:165], v247 offset:32768
	ds_read_b128 v[166:169], v247 offset:33792
	ds_read_b128 v[170:173], v247 offset:34816
	ds_read_b128 v[174:177], v247 offset:35840
	ds_read_b128 v[178:181], v247 offset:36864
	ds_read_b128 v[182:185], v247 offset:37888
	ds_read_b128 v[186:189], v247 offset:38912
	ds_read_b128 v[190:193], v247 offset:39936
	global_load_lds_dwordx4 v[194:195], off
	v_lshl_add_u64 v[194:195], s[24:25], 0, v[214:215]
	s_mov_b32 m0, s51
	s_nop 0
	global_load_lds_dwordx4 v[194:195], off
	s_waitcnt vmcnt(26)
	s_cmp_eq_u32 s100, 0
	s_cbranch_scc1 .Lthird_wait_relaxed_3
	s_waitcnt vmcnt(8)
; #define PG8_STAGE(bufoff, gbase, voff) do { _Pragma("unroll") for (int _i = 0; _i < 2; ++_i) \
;         __builtin_amdgcn_global_load_lds((const unsigned*)((const char*)(gbase) + (voff)[_i]), (PG8_LAS unsigned*)(lds + (bufoff) + ldsw + _i * 8192), 16, 0, 0); } while (0)
; #define PG8_LDA(dst, b, h) do { _Pragma("unroll") for (int m = 0; m < 4; ++m) _Pragma("unroll") for (int k = 0; k < 2; ++k) dst[m][k] = *(const PG8_LAS bf16x8*)(lds + PG8_SA(b, h) + aoff + m * 2048 + k * 1024); } while (0)
; #define PG8_MMA(ai, bj, At, Bt) do { __builtin_amdgcn_s_setprio(1); _Pragma("unroll") for (int m = 0; m < 4; ++m) _Pragma("unroll") for (int n = 0; n < 2; ++n) _Pragma("unroll") for (int k = 0; k < 2; ++k) \
;         acc[ai][bj][m][n] = __builtin_amdgcn_mfma_f32_16x16x32_bf16(Bt[n][k], At[m][k], acc[ai][bj][m][n], 0, 0, 0); __builtin_amdgcn_s_setprio(0); } while (0)
; #define PG8_WAIT_V(n) asm volatile("s_waitcnt vmcnt(" #n ")" ::: "memory")
; #define PG8_WAIT_L(n) asm volatile("s_waitcnt lgkmcnt(" #n ")" ::: "memory")
; #define PG8_BAR __builtin_amdgcn_s_barrier()
; #define PG8_SCHED __builtin_amdgcn_sched_barrier(0)
; template <class Epi, class Sched, bool ALIGN_EPI = false, bool SP2 = false>
; __device__ __forceinline__ void gemm_phase(PG8_LAS unsigned char* lds, const Gemm g, const Sched& S, const Epi& E, const int wave_id) {
;     ...
;             PG8_WAIT_V(8); PG8_WAIT_L(0); PG8_BAR; PG8_MMA(0, 0, At, B0); PG8_MMA(0, 1, At, B1); PG8_BAR; PG8_SCHED;
;             PG8_LDA(At, 1, 1); PG8_STAGE(PG8_SB(1, 0), b3, voffB); PG8_STAGE(PG8_SB(1, 1), b3 + hstep, voffB); PG8_STAGE(PG8_SA(1, 0), a3, voffA);
;             PG8_WAIT_V(8); PG8_WAIT_L(0); PG8_BAR; PG8_MMA(1, 0, At, B0); PG8_MMA(1, 1, At, B1); PG8_BAR; PG8_SCHED;
.Lthird_wait_relaxed_3:
	s_waitcnt lgkmcnt(0)
	s_setprio 1
	s_barrier
	v_mfma_f32_16x16x32_bf16 v[126:129], v[130:133], v[162:165], v[126:129]
	v_mfma_f32_16x16x32_bf16 v[122:125], v[138:141], v[162:165], v[122:125]
	v_mfma_f32_16x16x32_bf16 v[110:113], v[130:133], v[170:173], v[110:113]
	v_mfma_f32_16x16x32_bf16 v[106:109], v[138:141], v[170:173], v[106:109]
	v_mfma_f32_16x16x32_bf16 v[94:97], v[130:133], v[178:181], v[94:97]
	v_mfma_f32_16x16x32_bf16 v[90:93], v[138:141], v[178:181], v[90:93]
	v_mfma_f32_16x16x32_bf16 v[78:81], v[130:133], v[186:189], v[78:81]
	v_mfma_f32_16x16x32_bf16 v[74:77], v[138:141], v[186:189], v[74:77]
	v_mfma_f32_16x16x32_bf16 v[126:129], v[134:137], v[166:169], v[126:129]
	v_mfma_f32_16x16x32_bf16 v[122:125], v[142:145], v[166:169], v[122:125]
	v_mfma_f32_16x16x32_bf16 v[110:113], v[134:137], v[174:177], v[110:113]
	v_mfma_f32_16x16x32_bf16 v[106:109], v[142:145], v[174:177], v[106:109]
	v_mfma_f32_16x16x32_bf16 v[94:97], v[134:137], v[182:185], v[94:97]
	v_mfma_f32_16x16x32_bf16 v[90:93], v[142:145], v[182:185], v[90:93]
	v_mfma_f32_16x16x32_bf16 v[78:81], v[134:137], v[190:193], v[78:81]
	v_mfma_f32_16x16x32_bf16 v[74:77], v[142:145], v[190:193], v[74:77]
	v_mfma_f32_16x16x32_bf16 v[118:121], v[146:149], v[162:165], v[118:121]
	v_mfma_f32_16x16x32_bf16 v[114:117], v[154:157], v[162:165], v[114:117]
	v_mfma_f32_16x16x32_bf16 v[102:105], v[146:149], v[170:173], v[102:105]
	v_mfma_f32_16x16x32_bf16 v[98:101], v[154:157], v[170:173], v[98:101]
	v_mfma_f32_16x16x32_bf16 v[86:89], v[146:149], v[178:181], v[86:89]
	v_mfma_f32_16x16x32_bf16 v[82:85], v[154:157], v[178:181], v[82:85]
	v_mfma_f32_16x16x32_bf16 v[70:73], v[146:149], v[186:189], v[70:73]
	v_mfma_f32_16x16x32_bf16 v[66:69], v[154:157], v[186:189], v[66:69]
	v_mfma_f32_16x16x32_bf16 v[118:121], v[150:153], v[166:169], v[118:121]
	v_mfma_f32_16x16x32_bf16 v[114:117], v[158:161], v[166:169], v[114:117]
	v_mfma_f32_16x16x32_bf16 v[102:105], v[150:153], v[174:177], v[102:105]
	v_mfma_f32_16x16x32_bf16 v[98:101], v[158:161], v[174:177], v[98:101]
	v_mfma_f32_16x16x32_bf16 v[86:89], v[150:153], v[182:185], v[86:89]
	v_mfma_f32_16x16x32_bf16 v[82:85], v[158:161], v[182:185], v[82:85]
	v_mfma_f32_16x16x32_bf16 v[70:73], v[150:153], v[190:193], v[70:73]
	v_mfma_f32_16x16x32_bf16 v[66:69], v[158:161], v[190:193], v[66:69]
	s_setprio 0
	s_barrier
	s_add_i32 s24, s26, s38
	v_lshl_add_u64 v[194:195], v[232:233], 0, s[64:65]
	s_mov_b32 m0, s24
	ds_read_b128 v[162:165], v247 offset:49152
	ds_read_b128 v[166:169], v247 offset:50176
	ds_read_b128 v[170:173], v247 offset:51200
	ds_read_b128 v[174:177], v247 offset:52224
	ds_read_b128 v[178:181], v247 offset:53248
	ds_read_b128 v[182:185], v247 offset:54272
	ds_read_b128 v[186:189], v247 offset:55296
	ds_read_b128 v[190:193], v247 offset:56320
	global_load_lds_dwordx4 v[194:195], off
	s_add_i32 m0, s24, 0x2000
	s_add_u32 s22, s22, 0x40080
	v_lshl_add_u64 v[194:195], v[230:231], 0, s[64:65]
	s_addc_u32 s23, s23, 0
	s_add_i32 s24, s27, s38
	global_load_lds_dwordx4 v[194:195], off
	v_lshl_add_u64 v[194:195], s[22:23], 0, v[212:213]
	s_mov_b32 m0, s24
	s_nop 0
	global_load_lds_dwordx4 v[194:195], off
	v_lshl_add_u64 v[194:195], s[22:23], 0, v[216:217]
	s_add_i32 m0, s24, 0x2000
	s_nop 0
	global_load_lds_dwordx4 v[194:195], off
	v_lshl_add_u64 v[194:195], v[226:227], 0, s[64:65]
	s_mov_b32 m0, s54
	s_nop 0
	global_load_lds_dwordx4 v[194:195], off
	v_lshl_add_u64 v[194:195], v[228:229], 0, s[64:65]
	s_mov_b32 m0, s56
	s_nop 0
	global_load_lds_dwordx4 v[194:195], off
	s_waitcnt vmcnt(8)
	s_waitcnt lgkmcnt(0)
	s_setprio 1
	s_barrier
	v_mfma_f32_16x16x32_bf16 v[62:65], v[130:133], v[162:165], v[62:65]
	v_mfma_f32_16x16x32_bf16 v[58:61], v[138:141], v[162:165], v[58:61]
	v_mfma_f32_16x16x32_bf16 v[46:49], v[130:133], v[170:173], v[46:49]
	v_mfma_f32_16x16x32_bf16 v[42:45], v[138:141], v[170:173], v[42:45]
	v_mfma_f32_16x16x32_bf16 v[30:33], v[130:133], v[178:181], v[30:33]
	v_mfma_f32_16x16x32_bf16 v[26:29], v[138:141], v[178:181], v[26:29]
	v_mfma_f32_16x16x32_bf16 v[14:17], v[130:133], v[186:189], v[14:17]
	v_mfma_f32_16x16x32_bf16 v[10:13], v[138:141], v[186:189], v[10:13]
	v_mfma_f32_16x16x32_bf16 v[62:65], v[134:137], v[166:169], v[62:65]
	v_mfma_f32_16x16x32_bf16 v[58:61], v[142:145], v[166:169], v[58:61]
	v_mfma_f32_16x16x32_bf16 v[46:49], v[134:137], v[174:177], v[46:49]
	v_mfma_f32_16x16x32_bf16 v[42:45], v[142:145], v[174:177], v[42:45]
	v_mfma_f32_16x16x32_bf16 v[30:33], v[134:137], v[182:185], v[30:33]
	v_mfma_f32_16x16x32_bf16 v[26:29], v[142:145], v[182:185], v[26:29]
	v_mfma_f32_16x16x32_bf16 v[14:17], v[134:137], v[190:193], v[14:17]
	v_mfma_f32_16x16x32_bf16 v[10:13], v[142:145], v[190:193], v[10:13]
	v_mfma_f32_16x16x32_bf16 v[54:57], v[146:149], v[162:165], v[54:57]
	v_mfma_f32_16x16x32_bf16 v[50:53], v[154:157], v[162:165], v[50:53]
	v_mfma_f32_16x16x32_bf16 v[38:41], v[146:149], v[170:173], v[38:41]
	v_mfma_f32_16x16x32_bf16 v[34:37], v[154:157], v[170:173], v[34:37]
	v_mfma_f32_16x16x32_bf16 v[22:25], v[146:149], v[178:181], v[22:25]
	v_mfma_f32_16x16x32_bf16 v[18:21], v[154:157], v[178:181], v[18:21]
	v_mfma_f32_16x16x32_bf16 v[6:9], v[146:149], v[186:189], v[6:9]
	v_mfma_f32_16x16x32_bf16 v[2:5], v[154:157], v[186:189], v[2:5]
	v_mfma_f32_16x16x32_bf16 v[54:57], v[150:153], v[166:169], v[54:57]
	v_mfma_f32_16x16x32_bf16 v[50:53], v[158:161], v[166:169], v[50:53]
	v_mfma_f32_16x16x32_bf16 v[38:41], v[150:153], v[174:177], v[38:41]
	v_mfma_f32_16x16x32_bf16 v[34:37], v[158:161], v[174:177], v[34:37]
	v_mfma_f32_16x16x32_bf16 v[22:25], v[150:153], v[182:185], v[22:25]
	v_mfma_f32_16x16x32_bf16 v[18:21], v[158:161], v[182:185], v[18:21]
	v_mfma_f32_16x16x32_bf16 v[6:9], v[150:153], v[190:193], v[6:9]
	v_mfma_f32_16x16x32_bf16 v[2:5], v[158:161], v[190:193], v[2:5]
	s_setprio 0
	s_barrier
	s_add_i32 s74, s74, 2
	s_add_u32 s20, s20, 0x100
	s_addc_u32 s21, s21, 0
	s_cmp_gt_u32 s74, 13
	s_cbranch_scc1 .LBB0_1826

; #define PG8_STAGE(bufoff, gbase, voff) do { _Pragma("unroll") for (int _i = 0; _i < 2; ++_i) \
;         __builtin_amdgcn_global_load_lds((const unsigned*)((const char*)(gbase) + (voff)[_i]), (PG8_LAS unsigned*)(lds + (bufoff) + ldsw + _i * 8192), 16, 0, 0); } while (0)
; #define PG8_LDA(dst, b, h) do { _Pragma("unroll") for (int m = 0; m < 4; ++m) _Pragma("unroll") for (int k = 0; k < 2; ++k) dst[m][k] = *(const PG8_LAS bf16x8*)(lds + PG8_SA(b, h) + aoff + m * 2048 + k * 1024); } while (0)
; #define PG8_LDB(dst, b, h) do { _Pragma("unroll") for (int n = 0; n < 2; ++n) _Pragma("unroll") for (int k = 0; k < 2; ++k) dst[n][k] = *(const PG8_LAS bf16x8*)(lds + PG8_SB(b, h) + boff + n * 2048 + k * 1024); } while (0)
; #define PG8_WAIT_V(n) asm volatile("s_waitcnt vmcnt(" #n ")" ::: "memory")
; #define PG8_WAIT_VN(n) asm volatile("s_waitcnt vmcnt(%0)" :: "n"(n) : "memory")
; #define PG8_WAIT_L(n) asm volatile("s_waitcnt lgkmcnt(" #n ")" ::: "memory")
; #define PG8_BAR __builtin_amdgcn_s_barrier()
; #define PG8_SCHED __builtin_amdgcn_sched_barrier(0)
; template <class Epi, class Sched, bool ALIGN_EPI = false, bool SP2 = false>
; __device__ __forceinline__ void gemm_phase(PG8_LAS unsigned char* lds, const Gemm g, const Sched& S, const Epi& E, const int wave_id) {
;     ...
;             const char* a1 = cA + (size_t)(t + 1) * kstep;
;             const char* a2 = last ? nA : cA + (size_t)(t + 2) * kstep; const char* b2 = last ? nB : cB + (size_t)(t + 2) * kstep;
;             const char* a3 = a2 + kstep; const char* b3 = b2 + kstep;
;             if (last && has_next) S.a_ready(nxt);
;             if constexpr (SP2) {
;             int tz_ = __builtin_amdgcn_readfirstlane(t | (ui > 0 ? 0 : 1)); asm volatile("" : "+s"(tz_));
;             const bool strict = !(Epi::NS > 0 && tz_ == 0);
;             PG8_LDB(B0, 0, 0); PG8_LDB(B1, 0, 1); PG8_SCHED; PG8_LDA(At, 0, 0); PG8_STAGE(PG8_SA(1, 1), a1 + hstep, voffA);
;             PG8_WAIT_VN(8 + Epi::NS); if (strict) PG8_WAIT_V(8); PG8_WAIT_L(0); PG8_BAR; PG8_MMA(0, 0, At, B0); PG8_MMA(0, 1, At, B1); PG8_BAR; PG8_SCHED;
;             PG8_LDA(At, 0, 1); PG8_STAGE(PG8_SB(0, 0), b2, voffB); PG8_STAGE(PG8_SB(0, 1), b2 + hstep, voffB); PG8_STAGE(PG8_SA(0, 0), a2, voffA);
;             PG8_WAIT_VN(8 + Epi::NS); if (strict) PG8_WAIT_V(8); PG8_WAIT_L(0); PG8_BAR; PG8_MMA(1, 0, At, B0); PG8_MMA(1, 1, At, B1); PG8_BAR; PG8_SCHED;
.LBB0_1824:
	s_add_u32 s22, s18, s20
	s_addc_u32 s23, s19, s21
	s_add_u32 s22, s22, 0x100
	s_addc_u32 s23, s23, 0
	s_add_u32 s53, s68, s20
	s_addc_u32 s75, s69, s21
	s_cmpk_eq_i32 s20, 0x700
	s_cselect_b32 s25, s11, s23
	s_cselect_b32 s24, s63, s22
	s_cselect_b32 s23, s9, s75
	s_cselect_b32 s22, s67, s53
	s_waitcnt lgkmcnt(0)
	s_setprio 1
	s_barrier
	v_mfma_f32_16x16x32_bf16 v[126:129], v[146:149], v[186:189], v[126:129]
	v_mfma_f32_16x16x32_bf16 v[122:125], v[154:157], v[186:189], v[122:125]
	v_mfma_f32_16x16x32_bf16 v[110:113], v[146:149], v[178:181], v[110:113]
	v_mfma_f32_16x16x32_bf16 v[106:109], v[154:157], v[178:181], v[106:109]
	v_mfma_f32_16x16x32_bf16 v[94:97], v[146:149], v[170:173], v[94:97]
	v_mfma_f32_16x16x32_bf16 v[90:93], v[154:157], v[170:173], v[90:93]
	v_mfma_f32_16x16x32_bf16 v[78:81], v[146:149], v[162:165], v[78:81]
	v_mfma_f32_16x16x32_bf16 v[74:77], v[154:157], v[162:165], v[74:77]
	v_mfma_f32_16x16x32_bf16 v[126:129], v[150:153], v[190:193], v[126:129]
	v_mfma_f32_16x16x32_bf16 v[122:125], v[158:161], v[190:193], v[122:125]
	v_mfma_f32_16x16x32_bf16 v[110:113], v[150:153], v[182:185], v[110:113]
	v_mfma_f32_16x16x32_bf16 v[106:109], v[158:161], v[182:185], v[106:109]
	v_mfma_f32_16x16x32_bf16 v[94:97], v[150:153], v[174:177], v[94:97]
	v_mfma_f32_16x16x32_bf16 v[90:93], v[158:161], v[174:177], v[90:93]
	v_mfma_f32_16x16x32_bf16 v[78:81], v[150:153], v[166:169], v[78:81]
	v_mfma_f32_16x16x32_bf16 v[74:77], v[158:161], v[166:169], v[74:77]
	v_mfma_f32_16x16x32_bf16 v[118:121], v[130:133], v[186:189], v[118:121]
	v_mfma_f32_16x16x32_bf16 v[114:117], v[138:141], v[186:189], v[114:117]
	v_mfma_f32_16x16x32_bf16 v[102:105], v[130:133], v[178:181], v[102:105]
	v_mfma_f32_16x16x32_bf16 v[98:101], v[138:141], v[178:181], v[98:101]
	v_mfma_f32_16x16x32_bf16 v[86:89], v[130:133], v[170:173], v[86:89]
	v_mfma_f32_16x16x32_bf16 v[82:85], v[138:141], v[170:173], v[82:85]
	v_mfma_f32_16x16x32_bf16 v[70:73], v[130:133], v[162:165], v[70:73]
	v_mfma_f32_16x16x32_bf16 v[66:69], v[138:141], v[162:165], v[66:69]
	v_mfma_f32_16x16x32_bf16 v[118:121], v[134:137], v[190:193], v[118:121]
	v_mfma_f32_16x16x32_bf16 v[114:117], v[142:145], v[190:193], v[114:117]
	v_mfma_f32_16x16x32_bf16 v[102:105], v[134:137], v[182:185], v[102:105]
	v_mfma_f32_16x16x32_bf16 v[98:101], v[142:145], v[182:185], v[98:101]
	v_mfma_f32_16x16x32_bf16 v[86:89], v[134:137], v[174:177], v[86:89]
	v_mfma_f32_16x16x32_bf16 v[82:85], v[142:145], v[174:177], v[82:85]
	v_mfma_f32_16x16x32_bf16 v[70:73], v[134:137], v[166:169], v[70:73]
	v_mfma_f32_16x16x32_bf16 v[66:69], v[142:145], v[166:169], v[66:69]
	s_setprio 0
	s_barrier
	s_mov_b32 m0, s40
	v_lshl_add_u64 v[232:233], s[22:23], 0, v[212:213]
	s_add_u32 s90, s22, 0x40000
	ds_read_b128 v[186:189], v247 offset:16384
	ds_read_b128 v[190:193], v247 offset:17408
	ds_read_b128 v[178:181], v247 offset:18432
	ds_read_b128 v[182:185], v247 offset:19456
	ds_read_b128 v[170:173], v247 offset:20480
	ds_read_b128 v[174:177], v247 offset:21504
	ds_read_b128 v[162:165], v247 offset:22528
	ds_read_b128 v[166:169], v247 offset:23552
	global_load_lds_dwordx4 v[232:233], off
	v_lshl_add_u64 v[230:231], s[22:23], 0, v[216:217]
	s_mov_b32 m0, s41
	s_addc_u32 s91, s23, 0
	global_load_lds_dwordx4 v[230:231], off
	v_lshl_add_u64 v[194:195], s[90:91], 0, v[212:213]
	s_mov_b32 m0, s42
	v_lshl_add_u64 v[226:227], s[24:25], 0, v[210:211]
	global_load_lds_dwordx4 v[194:195], off
	v_lshl_add_u64 v[194:195], s[90:91], 0, v[216:217]
	s_mov_b32 m0, s43
	v_lshl_add_u64 v[228:229], s[24:25], 0, v[214:215]
	global_load_lds_dwordx4 v[194:195], off
	s_mov_b32 m0, s39
	s_andn2_b64 vcc, exec, s[26:27]
	global_load_lds_dwordx4 v[226:227], off
	s_mov_b32 m0, s49
	s_nop 0
	global_load_lds_dwordx4 v[228:229], off
	s_waitcnt vmcnt(24)
	s_cbranch_vccnz .LBB0_1821
	s_waitcnt vmcnt(8)
	s_branch .LBB0_1821

; #define PG8_STAGE(bufoff, gbase, voff) do { _Pragma("unroll") for (int _i = 0; _i < 2; ++_i) \
;         __builtin_amdgcn_global_load_lds((const unsigned*)((const char*)(gbase) + (voff)[_i]), (PG8_LAS unsigned*)(lds + (bufoff) + ldsw + _i * 8192), 16, 0, 0); } while (0)
; #define PG8_LDA(dst, b, h) do { _Pragma("unroll") for (int m = 0; m < 4; ++m) _Pragma("unroll") for (int k = 0; k < 2; ++k) dst[m][k] = *(const PG8_LAS bf16x8*)(lds + PG8_SA(b, h) + aoff + m * 2048 + k * 1024); } while (0)
; #define PG8_LDB(dst, b, h) do { _Pragma("unroll") for (int n = 0; n < 2; ++n) _Pragma("unroll") for (int k = 0; k < 2; ++k) dst[n][k] = *(const PG8_LAS bf16x8*)(lds + PG8_SB(b, h) + boff + n * 2048 + k * 1024); } while (0)
; #define PG8_MMA(ai, bj, At, Bt) do { __builtin_amdgcn_s_setprio(1); _Pragma("unroll") for (int m = 0; m < 4; ++m) _Pragma("unroll") for (int n = 0; n < 2; ++n) _Pragma("unroll") for (int k = 0; k < 2; ++k) \
;         acc[ai][bj][m][n] = __builtin_amdgcn_mfma_f32_16x16x32_bf16(Bt[n][k], At[m][k], acc[ai][bj][m][n], 0, 0, 0); __builtin_amdgcn_s_setprio(0); } while (0)
; #define PG8_WAIT_V(n) asm volatile("s_waitcnt vmcnt(" #n ")" ::: "memory")
; #define PG8_WAIT_VN(n) asm volatile("s_waitcnt vmcnt(%0)" :: "n"(n) : "memory")
; #define PG8_WAIT_L(n) asm volatile("s_waitcnt lgkmcnt(" #n ")" ::: "memory")
; #define PG8_BAR __builtin_amdgcn_s_barrier()
; #define PG8_SCHED __builtin_amdgcn_sched_barrier(0)
; template <class Epi, class Sched, bool ALIGN_EPI = false, bool SP2 = false>
; __device__ __forceinline__ void gemm_phase(PG8_LAS unsigned char* lds, const Gemm g, const Sched& S, const Epi& E, const int wave_id) {
;     ...
;             PG8_WAIT_VN(8 + Epi::NS); if (strict) PG8_WAIT_V(8); PG8_WAIT_L(0); PG8_BAR; PG8_MMA(0, 0, At, B0); PG8_MMA(0, 1, At, B1); PG8_BAR; PG8_SCHED;
;             PG8_LDA(At, 0, 1); PG8_STAGE(PG8_SB(0, 0), b2, voffB); PG8_STAGE(PG8_SB(0, 1), b2 + hstep, voffB); PG8_STAGE(PG8_SA(0, 0), a2, voffA);
;             PG8_WAIT_VN(8 + Epi::NS); if (strict) PG8_WAIT_V(8); PG8_WAIT_L(0); PG8_BAR; PG8_MMA(1, 0, At, B0); PG8_MMA(1, 1, At, B1); PG8_BAR; PG8_SCHED;
;             PG8_LDB(B0, 1, 0); PG8_LDB(B1, 1, 1); PG8_SCHED; PG8_LDA(At, 1, 0); PG8_STAGE(PG8_SA(0, 1), a2 + hstep, voffA);
;             PG8_WAIT_V(8); PG8_WAIT_L(0); PG8_BAR; PG8_MMA(0, 0, At, B0); PG8_MMA(0, 1, At, B1); PG8_BAR; PG8_SCHED;
.LBB0_1889:
	s_waitcnt lgkmcnt(0)
	s_setprio 1
	s_barrier
	v_mfma_f32_16x16x32_bf16 v[62:65], v[146:149], v[186:189], v[62:65]
	v_mfma_f32_16x16x32_bf16 v[58:61], v[154:157], v[186:189], v[58:61]
	v_mfma_f32_16x16x32_bf16 v[54:57], v[146:149], v[178:181], v[54:57]
	v_mfma_f32_16x16x32_bf16 v[50:53], v[154:157], v[178:181], v[50:53]
	v_mfma_f32_16x16x32_bf16 v[30:33], v[146:149], v[170:173], v[30:33]
	v_mfma_f32_16x16x32_bf16 v[26:29], v[154:157], v[170:173], v[26:29]
	v_mfma_f32_16x16x32_bf16 v[22:25], v[146:149], v[162:165], v[22:25]
	v_mfma_f32_16x16x32_bf16 v[18:21], v[154:157], v[162:165], v[18:21]
	v_mfma_f32_16x16x32_bf16 v[62:65], v[150:153], v[190:193], v[62:65]
	v_mfma_f32_16x16x32_bf16 v[58:61], v[158:161], v[190:193], v[58:61]
	v_mfma_f32_16x16x32_bf16 v[54:57], v[150:153], v[182:185], v[54:57]
	v_mfma_f32_16x16x32_bf16 v[50:53], v[158:161], v[182:185], v[50:53]
	v_mfma_f32_16x16x32_bf16 v[30:33], v[150:153], v[174:177], v[30:33]
	v_mfma_f32_16x16x32_bf16 v[26:29], v[158:161], v[174:177], v[26:29]
	v_mfma_f32_16x16x32_bf16 v[22:25], v[150:153], v[166:169], v[22:25]
	v_mfma_f32_16x16x32_bf16 v[18:21], v[158:161], v[166:169], v[18:21]
	v_mfma_f32_16x16x32_bf16 v[46:49], v[130:133], v[186:189], v[46:49]
	v_mfma_f32_16x16x32_bf16 v[42:45], v[138:141], v[186:189], v[42:45]
	v_mfma_f32_16x16x32_bf16 v[38:41], v[130:133], v[178:181], v[38:41]
	v_mfma_f32_16x16x32_bf16 v[34:37], v[138:141], v[178:181], v[34:37]
	v_mfma_f32_16x16x32_bf16 v[14:17], v[130:133], v[170:173], v[14:17]
	v_mfma_f32_16x16x32_bf16 v[10:13], v[138:141], v[170:173], v[10:13]
	v_mfma_f32_16x16x32_bf16 v[6:9], v[130:133], v[162:165], v[6:9]
	v_mfma_f32_16x16x32_bf16 v[2:5], v[138:141], v[162:165], v[2:5]
	v_mfma_f32_16x16x32_bf16 v[46:49], v[134:137], v[190:193], v[46:49]
	v_mfma_f32_16x16x32_bf16 v[42:45], v[142:145], v[190:193], v[42:45]
	v_mfma_f32_16x16x32_bf16 v[38:41], v[134:137], v[182:185], v[38:41]
	v_mfma_f32_16x16x32_bf16 v[34:37], v[142:145], v[182:185], v[34:37]
	v_mfma_f32_16x16x32_bf16 v[14:17], v[134:137], v[174:177], v[14:17]
	v_mfma_f32_16x16x32_bf16 v[10:13], v[142:145], v[174:177], v[10:13]
	v_mfma_f32_16x16x32_bf16 v[6:9], v[134:137], v[166:169], v[6:9]
	v_mfma_f32_16x16x32_bf16 v[2:5], v[142:145], v[166:169], v[2:5]
	s_setprio 0
	s_barrier
	s_add_i32 s16, 0, 0x18000
	s_add_i32 s17, 0, 0x1c000
	v_add_u32_e32 v142, s16, v231
	v_add_u32_e32 v158, s17, v231
	ds_read_b128 v[130:133], v142
	ds_read_b128 v[134:137], v142 offset:1024
	ds_read_b128 v[138:141], v142 offset:2048
	ds_read_b128 v[142:145], v142 offset:3072
	ds_read_b128 v[146:149], v158
	ds_read_b128 v[150:153], v158 offset:1024
	ds_read_b128 v[154:157], v158 offset:2048
	ds_read_b128 v[158:161], v158 offset:3072
	s_add_u32 s14, s14, 0x40000
	s_addc_u32 s15, s15, 0
	s_mov_b32 m0, s28
	v_lshl_add_u64 v[194:195], s[14:15], 0, v[210:211]
	ds_read_b128 v[162:165], v232 offset:32768
	ds_read_b128 v[166:169], v232 offset:33792
	ds_read_b128 v[170:173], v232 offset:34816
	ds_read_b128 v[174:177], v232 offset:35840
	ds_read_b128 v[178:181], v232 offset:36864
	ds_read_b128 v[182:185], v232 offset:37888
	ds_read_b128 v[186:189], v232 offset:38912
	ds_read_b128 v[190:193], v232 offset:39936
	global_load_lds_dwordx4 v[194:195], off
	v_lshl_add_u64 v[194:195], s[14:15], 0, v[214:215]
	s_mov_b32 m0, s29
	s_nop 0
	global_load_lds_dwordx4 v[194:195], off
	s_waitcnt vmcnt(8)
	s_waitcnt lgkmcnt(0)
	s_setprio 1
	s_barrier
	v_mfma_f32_16x16x32_bf16 v[126:129], v[130:133], v[162:165], v[126:129]
	v_mfma_f32_16x16x32_bf16 v[122:125], v[138:141], v[162:165], v[122:125]
	v_mfma_f32_16x16x32_bf16 v[118:121], v[130:133], v[170:173], v[118:121]
	v_mfma_f32_16x16x32_bf16 v[114:117], v[138:141], v[170:173], v[114:117]
	v_mfma_f32_16x16x32_bf16 v[94:97], v[130:133], v[178:181], v[94:97]
	v_mfma_f32_16x16x32_bf16 v[90:93], v[138:141], v[178:181], v[90:93]
	v_mfma_f32_16x16x32_bf16 v[86:89], v[130:133], v[186:189], v[86:89]
	v_mfma_f32_16x16x32_bf16 v[82:85], v[138:141], v[186:189], v[82:85]
	v_mfma_f32_16x16x32_bf16 v[126:129], v[134:137], v[166:169], v[126:129]
	v_mfma_f32_16x16x32_bf16 v[122:125], v[142:145], v[166:169], v[122:125]
	v_mfma_f32_16x16x32_bf16 v[118:121], v[134:137], v[174:177], v[118:121]
	v_mfma_f32_16x16x32_bf16 v[114:117], v[142:145], v[174:177], v[114:117]
	v_mfma_f32_16x16x32_bf16 v[94:97], v[134:137], v[182:185], v[94:97]
	v_mfma_f32_16x16x32_bf16 v[90:93], v[142:145], v[182:185], v[90:93]
	v_mfma_f32_16x16x32_bf16 v[86:89], v[134:137], v[190:193], v[86:89]
	v_mfma_f32_16x16x32_bf16 v[82:85], v[142:145], v[190:193], v[82:85]
	v_mfma_f32_16x16x32_bf16 v[110:113], v[146:149], v[162:165], v[110:113]
	v_mfma_f32_16x16x32_bf16 v[106:109], v[154:157], v[162:165], v[106:109]
	v_mfma_f32_16x16x32_bf16 v[102:105], v[146:149], v[170:173], v[102:105]
	v_mfma_f32_16x16x32_bf16 v[98:101], v[154:157], v[170:173], v[98:101]
	v_mfma_f32_16x16x32_bf16 v[78:81], v[146:149], v[178:181], v[78:81]
	v_mfma_f32_16x16x32_bf16 v[74:77], v[154:157], v[178:181], v[74:77]
	v_mfma_f32_16x16x32_bf16 v[70:73], v[146:149], v[186:189], v[70:73]
	v_mfma_f32_16x16x32_bf16 v[66:69], v[154:157], v[186:189], v[66:69]
	v_mfma_f32_16x16x32_bf16 v[110:113], v[150:153], v[166:169], v[110:113]
	v_mfma_f32_16x16x32_bf16 v[106:109], v[158:161], v[166:169], v[106:109]
	v_mfma_f32_16x16x32_bf16 v[102:105], v[150:153], v[174:177], v[102:105]
	v_mfma_f32_16x16x32_bf16 v[98:101], v[158:161], v[174:177], v[98:101]
	v_mfma_f32_16x16x32_bf16 v[78:81], v[150:153], v[182:185], v[78:81]
	v_mfma_f32_16x16x32_bf16 v[74:77], v[158:161], v[182:185], v[74:77]
	v_mfma_f32_16x16x32_bf16 v[70:73], v[150:153], v[190:193], v[70:73]
	v_mfma_f32_16x16x32_bf16 v[66:69], v[158:161], v[190:193], v[66:69]
	s_setprio 0
	s_barrier
; #define PG8_STAGE(bufoff, gbase, voff) do { _Pragma("unroll") for (int _i = 0; _i < 2; ++_i) \
;         __builtin_amdgcn_global_load_lds((const unsigned*)((const char*)(gbase) + (voff)[_i]), (PG8_LAS unsigned*)(lds + (bufoff) + ldsw + _i * 8192), 16, 0, 0); } while (0)
; #define PG8_LDA(dst, b, h) do { _Pragma("unroll") for (int m = 0; m < 4; ++m) _Pragma("unroll") for (int k = 0; k < 2; ++k) dst[m][k] = *(const PG8_LAS bf16x8*)(lds + PG8_SA(b, h) + aoff + m * 2048 + k * 1024); } while (0)
; #define PG8_MMA(ai, bj, At, Bt) do { __builtin_amdgcn_s_setprio(1); _Pragma("unroll") for (int m = 0; m < 4; ++m) _Pragma("unroll") for (int n = 0; n < 2; ++n) _Pragma("unroll") for (int k = 0; k < 2; ++k) \
;         acc[ai][bj][m][n] = __builtin_amdgcn_mfma_f32_16x16x32_bf16(Bt[n][k], At[m][k], acc[ai][bj][m][n], 0, 0, 0); __builtin_amdgcn_s_setprio(0); } while (0)
; #define PG8_WAIT_V(n) asm volatile("s_waitcnt vmcnt(" #n ")" ::: "memory")
; #define PG8_WAIT_L(n) asm volatile("s_waitcnt lgkmcnt(" #n ")" ::: "memory")
; #define PG8_BAR __builtin_amdgcn_s_barrier()
; #define PG8_SCHED __builtin_amdgcn_sched_barrier(0)
; template <class Epi, class Sched, bool ALIGN_EPI = false, bool SP2 = false>
; __device__ __forceinline__ void gemm_phase(PG8_LAS unsigned char* lds, const Gemm g, const Sched& S, const Epi& E, const int wave_id) {
;     ...
;             PG8_WAIT_V(8); PG8_WAIT_L(0); PG8_BAR; PG8_MMA(0, 0, At, B0); PG8_MMA(0, 1, At, B1); PG8_BAR; PG8_SCHED;
;             PG8_LDA(At, 1, 1); PG8_STAGE(PG8_SB(1, 0), b3, voffB); PG8_STAGE(PG8_SB(1, 1), b3 + hstep, voffB); PG8_STAGE(PG8_SA(1, 0), a3, voffA);
;             PG8_WAIT_V(8); PG8_WAIT_L(0); PG8_BAR; PG8_MMA(1, 0, At, B0); PG8_MMA(1, 1, At, B1); PG8_BAR; PG8_SCHED;
	s_add_i32 s14, s16, s21
	v_lshl_add_u64 v[194:195], v[228:229], 0, s[64:65]
	s_mov_b32 m0, s14
	ds_read_b128 v[162:165], v232 offset:49152
	ds_read_b128 v[166:169], v232 offset:50176
	ds_read_b128 v[170:173], v232 offset:51200
	ds_read_b128 v[174:177], v232 offset:52224
	ds_read_b128 v[178:181], v232 offset:53248
	ds_read_b128 v[182:185], v232 offset:54272
	ds_read_b128 v[186:189], v232 offset:55296
	ds_read_b128 v[190:193], v232 offset:56320
	global_load_lds_dwordx4 v[194:195], off
	s_add_i32 m0, s14, 0x2000
	s_add_u32 s12, s12, 0x40080
	v_lshl_add_u64 v[194:195], v[226:227], 0, s[64:65]
	s_addc_u32 s13, s13, 0
	s_add_i32 s14, s17, s21
	global_load_lds_dwordx4 v[194:195], off
	v_lshl_add_u64 v[194:195], s[12:13], 0, v[212:213]
	s_mov_b32 m0, s14
	s_nop 0
	global_load_lds_dwordx4 v[194:195], off
	v_lshl_add_u64 v[194:195], s[12:13], 0, v[216:217]
	s_add_i32 m0, s14, 0x2000
	s_nop 0
	global_load_lds_dwordx4 v[194:195], off
	v_lshl_add_u64 v[194:195], v[222:223], 0, s[64:65]
	s_mov_b32 m0, s30
	s_nop 0
	global_load_lds_dwordx4 v[194:195], off
	v_lshl_add_u64 v[194:195], v[224:225], 0, s[64:65]
	s_mov_b32 m0, s31
	s_nop 0
	global_load_lds_dwordx4 v[194:195], off
	s_waitcnt vmcnt(8)
	s_waitcnt lgkmcnt(0)
	s_setprio 1
	s_barrier
	v_mfma_f32_16x16x32_bf16 v[62:65], v[130:133], v[162:165], v[62:65]
	v_mfma_f32_16x16x32_bf16 v[58:61], v[138:141], v[162:165], v[58:61]
	v_mfma_f32_16x16x32_bf16 v[54:57], v[130:133], v[170:173], v[54:57]
	v_mfma_f32_16x16x32_bf16 v[50:53], v[138:141], v[170:173], v[50:53]
	v_mfma_f32_16x16x32_bf16 v[30:33], v[130:133], v[178:181], v[30:33]
	v_mfma_f32_16x16x32_bf16 v[26:29], v[138:141], v[178:181], v[26:29]
	v_mfma_f32_16x16x32_bf16 v[22:25], v[130:133], v[186:189], v[22:25]
	v_mfma_f32_16x16x32_bf16 v[18:21], v[138:141], v[186:189], v[18:21]
	v_mfma_f32_16x16x32_bf16 v[62:65], v[134:137], v[166:169], v[62:65]
	v_mfma_f32_16x16x32_bf16 v[58:61], v[142:145], v[166:169], v[58:61]
	v_mfma_f32_16x16x32_bf16 v[54:57], v[134:137], v[174:177], v[54:57]
	v_mfma_f32_16x16x32_bf16 v[50:53], v[142:145], v[174:177], v[50:53]
	v_mfma_f32_16x16x32_bf16 v[30:33], v[134:137], v[182:185], v[30:33]
	v_mfma_f32_16x16x32_bf16 v[26:29], v[142:145], v[182:185], v[26:29]
	v_mfma_f32_16x16x32_bf16 v[22:25], v[134:137], v[190:193], v[22:25]
	v_mfma_f32_16x16x32_bf16 v[18:21], v[142:145], v[190:193], v[18:21]
	v_mfma_f32_16x16x32_bf16 v[46:49], v[146:149], v[162:165], v[46:49]
	v_mfma_f32_16x16x32_bf16 v[42:45], v[154:157], v[162:165], v[42:45]
	v_mfma_f32_16x16x32_bf16 v[38:41], v[146:149], v[170:173], v[38:41]
	v_mfma_f32_16x16x32_bf16 v[34:37], v[154:157], v[170:173], v[34:37]
	v_mfma_f32_16x16x32_bf16 v[14:17], v[146:149], v[178:181], v[14:17]
	v_mfma_f32_16x16x32_bf16 v[10:13], v[154:157], v[178:181], v[10:13]
	v_mfma_f32_16x16x32_bf16 v[6:9], v[146:149], v[186:189], v[6:9]
	v_mfma_f32_16x16x32_bf16 v[2:5], v[154:157], v[186:189], v[2:5]
	v_mfma_f32_16x16x32_bf16 v[46:49], v[150:153], v[166:169], v[46:49]
	v_mfma_f32_16x16x32_bf16 v[42:45], v[158:161], v[166:169], v[42:45]
	v_mfma_f32_16x16x32_bf16 v[38:41], v[150:153], v[174:177], v[38:41]
	v_mfma_f32_16x16x32_bf16 v[34:37], v[158:161], v[174:177], v[34:37]
	v_mfma_f32_16x16x32_bf16 v[14:17], v[150:153], v[182:185], v[14:17]
	v_mfma_f32_16x16x32_bf16 v[10:13], v[158:161], v[182:185], v[10:13]
	v_mfma_f32_16x16x32_bf16 v[6:9], v[150:153], v[190:193], v[6:9]
	v_mfma_f32_16x16x32_bf16 v[2:5], v[158:161], v[190:193], v[2:5]
	s_setprio 0
	s_barrier
	s_add_u32 s10, s10, 0x100
	s_addc_u32 s11, s11, 0
	s_cmp_gt_u32 s38, 13
	v_readlane_b32 s40, v254, 55
	s_cbranch_scc1 .LBB0_1894

; #define PG8_STAGE(bufoff, gbase, voff) do { _Pragma("unroll") for (int _i = 0; _i < 2; ++_i) \
;         __builtin_amdgcn_global_load_lds((const unsigned*)((const char*)(gbase) + (voff)[_i]), (PG8_LAS unsigned*)(lds + (bufoff) + ldsw + _i * 8192), 16, 0, 0); } while (0)
; #define PG8_LDA(dst, b, h) do { _Pragma("unroll") for (int m = 0; m < 4; ++m) _Pragma("unroll") for (int k = 0; k < 2; ++k) dst[m][k] = *(const PG8_LAS bf16x8*)(lds + PG8_SA(b, h) + aoff + m * 2048 + k * 1024); } while (0)
; #define PG8_LDB(dst, b, h) do { _Pragma("unroll") for (int n = 0; n < 2; ++n) _Pragma("unroll") for (int k = 0; k < 2; ++k) dst[n][k] = *(const PG8_LAS bf16x8*)(lds + PG8_SB(b, h) + boff + n * 2048 + k * 1024); } while (0)
; #define PG8_WAIT_V(n) asm volatile("s_waitcnt vmcnt(" #n ")" ::: "memory")
; #define PG8_WAIT_VN(n) asm volatile("s_waitcnt vmcnt(%0)" :: "n"(n) : "memory")
; #define PG8_WAIT_L(n) asm volatile("s_waitcnt lgkmcnt(" #n ")" ::: "memory")
; template <class Epi, class Sched, bool ALIGN_EPI = false, bool SP2 = false>
; __device__ __forceinline__ void gemm_phase(PG8_LAS unsigned char* lds, const Gemm g, const Sched& S, const Epi& E, const int wave_id) {
;     ...
;         for (int t = 0; t < nt; t += 2) {
;             const bool last = (t == nt - 2);
;             const char* a1 = cA + (size_t)(t + 1) * kstep;
;             const char* a2 = last ? nA : cA + (size_t)(t + 2) * kstep; const char* b2 = last ? nB : cB + (size_t)(t + 2) * kstep;
;             const char* a3 = a2 + kstep; const char* b3 = b2 + kstep;
;             if (last && has_next) S.a_ready(nxt);
;             if constexpr (SP2) {
;             int tz_ = __builtin_amdgcn_readfirstlane(t | (ui > 0 ? 0 : 1)); asm volatile("" : "+s"(tz_));
;             const bool strict = !(Epi::NS > 0 && tz_ == 0);
;             PG8_LDB(B0, 0, 0); PG8_LDB(B1, 0, 1); PG8_SCHED; PG8_LDA(At, 0, 0); PG8_STAGE(PG8_SA(1, 1), a1 + hstep, voffA);
;             PG8_WAIT_VN(8 + Epi::NS); if (strict) PG8_WAIT_V(8); PG8_WAIT_L(0); PG8_BAR; PG8_MMA(0, 0, At, B0); PG8_MMA(0, 1, At, B1); PG8_BAR; PG8_SCHED;
;             PG8_LDA(At, 0, 1); PG8_STAGE(PG8_SB(0, 0), b2, voffB); PG8_STAGE(PG8_SB(0, 1), b2 + hstep, voffB); PG8_STAGE(PG8_SA(0, 0), a2, voffA);
;             PG8_WAIT_VN(8 + Epi::NS); if (strict) PG8_WAIT_V(8); PG8_WAIT_L(0); PG8_BAR; PG8_MMA(1, 0, At, B0); PG8_MMA(1, 1, At, B1); PG8_BAR; PG8_SCHED;
.LBB0_1892:
	s_add_u32 s12, s36, s10
	s_addc_u32 s13, s37, s11
	s_add_u32 s12, s12, 0x8200100
	s_addc_u32 s13, s13, 0
	s_add_u32 s39, s34, s10
	s_addc_u32 s40, s35, s11
	s_cmpk_eq_i32 s10, 0x700
	s_cselect_b32 s15, s9, s13
	s_cselect_b32 s14, s8, s12
	s_cselect_b32 s13, s7, s40
	s_cselect_b32 s12, s6, s39
	s_waitcnt lgkmcnt(0)
	s_setprio 1
	s_barrier
	v_mfma_f32_16x16x32_bf16 v[126:129], v[146:149], v[186:189], v[126:129]
	v_mfma_f32_16x16x32_bf16 v[122:125], v[154:157], v[186:189], v[122:125]
	v_mfma_f32_16x16x32_bf16 v[118:121], v[146:149], v[178:181], v[118:121]
	v_mfma_f32_16x16x32_bf16 v[114:117], v[154:157], v[178:181], v[114:117]
	v_mfma_f32_16x16x32_bf16 v[94:97], v[146:149], v[170:173], v[94:97]
	v_mfma_f32_16x16x32_bf16 v[90:93], v[154:157], v[170:173], v[90:93]
	v_mfma_f32_16x16x32_bf16 v[86:89], v[146:149], v[162:165], v[86:89]
	v_mfma_f32_16x16x32_bf16 v[82:85], v[154:157], v[162:165], v[82:85]
	v_mfma_f32_16x16x32_bf16 v[126:129], v[150:153], v[190:193], v[126:129]
	v_mfma_f32_16x16x32_bf16 v[122:125], v[158:161], v[190:193], v[122:125]
	v_mfma_f32_16x16x32_bf16 v[118:121], v[150:153], v[182:185], v[118:121]
	v_mfma_f32_16x16x32_bf16 v[114:117], v[158:161], v[182:185], v[114:117]
	v_mfma_f32_16x16x32_bf16 v[94:97], v[150:153], v[174:177], v[94:97]
	v_mfma_f32_16x16x32_bf16 v[90:93], v[158:161], v[174:177], v[90:93]
	v_mfma_f32_16x16x32_bf16 v[86:89], v[150:153], v[166:169], v[86:89]
	v_mfma_f32_16x16x32_bf16 v[82:85], v[158:161], v[166:169], v[82:85]
	v_mfma_f32_16x16x32_bf16 v[110:113], v[130:133], v[186:189], v[110:113]
	v_mfma_f32_16x16x32_bf16 v[106:109], v[138:141], v[186:189], v[106:109]
	v_mfma_f32_16x16x32_bf16 v[102:105], v[130:133], v[178:181], v[102:105]
	v_mfma_f32_16x16x32_bf16 v[98:101], v[138:141], v[178:181], v[98:101]
	v_mfma_f32_16x16x32_bf16 v[78:81], v[130:133], v[170:173], v[78:81]
	v_mfma_f32_16x16x32_bf16 v[74:77], v[138:141], v[170:173], v[74:77]
	v_mfma_f32_16x16x32_bf16 v[70:73], v[130:133], v[162:165], v[70:73]
	v_mfma_f32_16x16x32_bf16 v[66:69], v[138:141], v[162:165], v[66:69]
	v_mfma_f32_16x16x32_bf16 v[110:113], v[134:137], v[190:193], v[110:113]
	v_mfma_f32_16x16x32_bf16 v[106:109], v[142:145], v[190:193], v[106:109]
	v_mfma_f32_16x16x32_bf16 v[102:105], v[134:137], v[182:185], v[102:105]
	v_mfma_f32_16x16x32_bf16 v[98:101], v[142:145], v[182:185], v[98:101]
	v_mfma_f32_16x16x32_bf16 v[78:81], v[134:137], v[174:177], v[78:81]
	v_mfma_f32_16x16x32_bf16 v[74:77], v[142:145], v[174:177], v[74:77]
	v_mfma_f32_16x16x32_bf16 v[70:73], v[134:137], v[166:169], v[70:73]
	v_mfma_f32_16x16x32_bf16 v[66:69], v[142:145], v[166:169], v[66:69]
	s_setprio 0
	s_barrier
	s_mov_b32 m0, s22
	v_lshl_add_u64 v[228:229], s[12:13], 0, v[212:213]
	s_add_u32 s40, s12, 0x40000
	ds_read_b128 v[186:189], v232 offset:16384
	ds_read_b128 v[190:193], v232 offset:17408
	ds_read_b128 v[178:181], v232 offset:18432
	ds_read_b128 v[182:185], v232 offset:19456
	ds_read_b128 v[170:173], v232 offset:20480
	ds_read_b128 v[174:177], v232 offset:21504
	ds_read_b128 v[162:165], v232 offset:22528
	ds_read_b128 v[166:169], v232 offset:23552
	global_load_lds_dwordx4 v[228:229], off
	v_lshl_add_u64 v[226:227], s[12:13], 0, v[216:217]
	s_mov_b32 m0, s23
	s_addc_u32 s41, s13, 0
	global_load_lds_dwordx4 v[226:227], off
	v_lshl_add_u64 v[194:195], s[40:41], 0, v[212:213]
	s_mov_b32 m0, s24
	v_lshl_add_u64 v[222:223], s[14:15], 0, v[210:211]
	global_load_lds_dwordx4 v[194:195], off
	v_lshl_add_u64 v[194:195], s[40:41], 0, v[216:217]
	s_mov_b32 m0, s25
	v_lshl_add_u64 v[224:225], s[14:15], 0, v[214:215]
	global_load_lds_dwordx4 v[194:195], off
	s_mov_b32 m0, s5
	s_andn2_b64 vcc, exec, s[16:17]
	global_load_lds_dwordx4 v[222:223], off
	s_mov_b32 m0, s26
	s_nop 0
	global_load_lds_dwordx4 v[224:225], off
	s_waitcnt vmcnt(16)
	s_cbranch_vccnz .LBB0_1889
	s_waitcnt vmcnt(8)
	s_branch .LBB0_1889

; #define PG8_STAGE(bufoff, gbase, voff) do { _Pragma("unroll") for (int _i = 0; _i < 2; ++_i) \
;         __builtin_amdgcn_global_load_lds((const unsigned*)((const char*)(gbase) + (voff)[_i]), (PG8_LAS unsigned*)(lds + (bufoff) + ldsw + _i * 8192), 16, 0, 0); } while (0)
; #define PG8_LDA(dst, b, h) do { _Pragma("unroll") for (int m = 0; m < 4; ++m) _Pragma("unroll") for (int k = 0; k < 2; ++k) dst[m][k] = *(const PG8_LAS bf16x8*)(lds + PG8_SA(b, h) + aoff + m * 2048 + k * 1024); } while (0)
; #define PG8_LDB(dst, b, h) do { _Pragma("unroll") for (int n = 0; n < 2; ++n) _Pragma("unroll") for (int k = 0; k < 2; ++k) dst[n][k] = *(const PG8_LAS bf16x8*)(lds + PG8_SB(b, h) + boff + n * 2048 + k * 1024); } while (0)
; #define PG8_MMA(ai, bj, At, Bt) do { __builtin_amdgcn_s_setprio(1); _Pragma("unroll") for (int m = 0; m < 4; ++m) _Pragma("unroll") for (int n = 0; n < 2; ++n) _Pragma("unroll") for (int k = 0; k < 2; ++k) \
;         acc[ai][bj][m][n] = __builtin_amdgcn_mfma_f32_16x16x32_bf16(Bt[n][k], At[m][k], acc[ai][bj][m][n], 0, 0, 0); __builtin_amdgcn_s_setprio(0); } while (0)
; #define PG8_WAIT_V(n) asm volatile("s_waitcnt vmcnt(" #n ")" ::: "memory")
; #define PG8_WAIT_VN(n) asm volatile("s_waitcnt vmcnt(%0)" :: "n"(n) : "memory")
; #define PG8_WAIT_L(n) asm volatile("s_waitcnt lgkmcnt(" #n ")" ::: "memory")
; #define PG8_BAR __builtin_amdgcn_s_barrier()
; #define PG8_SCHED __builtin_amdgcn_sched_barrier(0)
; template <class Epi, class Sched, bool ALIGN_EPI = false, bool SP2 = false>
; __device__ __forceinline__ void gemm_phase(PG8_LAS unsigned char* lds, const Gemm g, const Sched& S, const Epi& E, const int wave_id) {
;     ...
;             PG8_WAIT_VN(8 + Epi::NS); if (strict) PG8_WAIT_V(8); PG8_WAIT_L(0); PG8_BAR; PG8_MMA(1, 0, At, B0); PG8_MMA(1, 1, At, B1); PG8_BAR; PG8_SCHED;
;             PG8_LDB(B0, 1, 0); PG8_LDB(B1, 1, 1); PG8_SCHED; PG8_LDA(At, 1, 0); PG8_STAGE(PG8_SA(0, 1), a2 + hstep, voffA);
;             PG8_WAIT_V(8); PG8_WAIT_L(0); PG8_BAR; PG8_MMA(0, 0, At, B0); PG8_MMA(0, 1, At, B1); PG8_BAR; PG8_SCHED;
.LBB0_1952:
	s_waitcnt lgkmcnt(0)
	s_setprio 1
	s_barrier
	v_mfma_f32_16x16x32_bf16 v[62:65], v[146:149], v[186:189], v[62:65]
	v_mfma_f32_16x16x32_bf16 v[58:61], v[154:157], v[186:189], v[58:61]
	v_mfma_f32_16x16x32_bf16 v[54:57], v[146:149], v[178:181], v[54:57]
	v_mfma_f32_16x16x32_bf16 v[50:53], v[154:157], v[178:181], v[50:53]
	v_mfma_f32_16x16x32_bf16 v[30:33], v[146:149], v[170:173], v[30:33]
	v_mfma_f32_16x16x32_bf16 v[26:29], v[154:157], v[170:173], v[26:29]
	v_mfma_f32_16x16x32_bf16 v[22:25], v[146:149], v[162:165], v[22:25]
	v_mfma_f32_16x16x32_bf16 v[18:21], v[154:157], v[162:165], v[18:21]
	v_mfma_f32_16x16x32_bf16 v[62:65], v[150:153], v[190:193], v[62:65]
	v_mfma_f32_16x16x32_bf16 v[58:61], v[158:161], v[190:193], v[58:61]
	v_mfma_f32_16x16x32_bf16 v[54:57], v[150:153], v[182:185], v[54:57]
	v_mfma_f32_16x16x32_bf16 v[50:53], v[158:161], v[182:185], v[50:53]
	v_mfma_f32_16x16x32_bf16 v[30:33], v[150:153], v[174:177], v[30:33]
	v_mfma_f32_16x16x32_bf16 v[26:29], v[158:161], v[174:177], v[26:29]
	v_mfma_f32_16x16x32_bf16 v[22:25], v[150:153], v[166:169], v[22:25]
	v_mfma_f32_16x16x32_bf16 v[18:21], v[158:161], v[166:169], v[18:21]
	v_mfma_f32_16x16x32_bf16 v[46:49], v[130:133], v[186:189], v[46:49]
	v_mfma_f32_16x16x32_bf16 v[42:45], v[138:141], v[186:189], v[42:45]
	v_mfma_f32_16x16x32_bf16 v[38:41], v[130:133], v[178:181], v[38:41]
	v_mfma_f32_16x16x32_bf16 v[34:37], v[138:141], v[178:181], v[34:37]
	v_mfma_f32_16x16x32_bf16 v[14:17], v[130:133], v[170:173], v[14:17]
	v_mfma_f32_16x16x32_bf16 v[10:13], v[138:141], v[170:173], v[10:13]
	v_mfma_f32_16x16x32_bf16 v[6:9], v[130:133], v[162:165], v[6:9]
	v_mfma_f32_16x16x32_bf16 v[2:5], v[138:141], v[162:165], v[2:5]
	v_mfma_f32_16x16x32_bf16 v[46:49], v[134:137], v[190:193], v[46:49]
	v_mfma_f32_16x16x32_bf16 v[42:45], v[142:145], v[190:193], v[42:45]
	v_mfma_f32_16x16x32_bf16 v[38:41], v[134:137], v[182:185], v[38:41]
	v_mfma_f32_16x16x32_bf16 v[34:37], v[142:145], v[182:185], v[34:37]
	v_mfma_f32_16x16x32_bf16 v[14:17], v[134:137], v[174:177], v[14:17]
	v_mfma_f32_16x16x32_bf16 v[10:13], v[142:145], v[174:177], v[10:13]
	v_mfma_f32_16x16x32_bf16 v[6:9], v[134:137], v[166:169], v[6:9]
	v_mfma_f32_16x16x32_bf16 v[2:5], v[142:145], v[166:169], v[2:5]
	s_setprio 0
	s_barrier
	s_add_i32 s28, 0, 0x18000
	s_add_i32 s29, 0, 0x1c000
	v_add_u32_e32 v142, s28, v246
	v_add_u32_e32 v158, s29, v246
	ds_read_b128 v[130:133], v142
	ds_read_b128 v[134:137], v142 offset:1024
	ds_read_b128 v[138:141], v142 offset:2048
	ds_read_b128 v[142:145], v142 offset:3072
	ds_read_b128 v[146:149], v158
	ds_read_b128 v[150:153], v158 offset:1024
	ds_read_b128 v[154:157], v158 offset:2048
	ds_read_b128 v[158:161], v158 offset:3072
	s_add_u32 s26, s26, 0x40000
	s_addc_u32 s27, s27, 0
	s_mov_b32 m0, s52
	v_lshl_add_u64 v[194:195], s[26:27], 0, v[216:217]
	ds_read_b128 v[162:165], v247 offset:32768
	ds_read_b128 v[166:169], v247 offset:33792
	ds_read_b128 v[170:173], v247 offset:34816
	ds_read_b128 v[174:177], v247 offset:35840
	ds_read_b128 v[178:181], v247 offset:36864
	ds_read_b128 v[182:185], v247 offset:37888
	ds_read_b128 v[186:189], v247 offset:38912
	ds_read_b128 v[190:193], v247 offset:39936
	global_load_lds_dwordx4 v[194:195], off
	v_lshl_add_u64 v[194:195], s[26:27], 0, v[212:213]
	s_mov_b32 m0, s54
	s_nop 0
	global_load_lds_dwordx4 v[194:195], off
	s_waitcnt vmcnt(18)
	s_cmp_eq_u32 s100, 0
	s_cbranch_scc1 .Lthird_wait_relaxed_2
	s_waitcnt vmcnt(8)
; #define PG8_STAGE(bufoff, gbase, voff) do { _Pragma("unroll") for (int _i = 0; _i < 2; ++_i) \
;         __builtin_amdgcn_global_load_lds((const unsigned*)((const char*)(gbase) + (voff)[_i]), (PG8_LAS unsigned*)(lds + (bufoff) + ldsw + _i * 8192), 16, 0, 0); } while (0)
; #define PG8_LDA(dst, b, h) do { _Pragma("unroll") for (int m = 0; m < 4; ++m) _Pragma("unroll") for (int k = 0; k < 2; ++k) dst[m][k] = *(const PG8_LAS bf16x8*)(lds + PG8_SA(b, h) + aoff + m * 2048 + k * 1024); } while (0)
; #define PG8_LDB(dst, b, h) do { _Pragma("unroll") for (int n = 0; n < 2; ++n) _Pragma("unroll") for (int k = 0; k < 2; ++k) dst[n][k] = *(const PG8_LAS bf16x8*)(lds + PG8_SB(b, h) + boff + n * 2048 + k * 1024); } while (0)
; #define PG8_MMA(ai, bj, At, Bt) do { __builtin_amdgcn_s_setprio(1); _Pragma("unroll") for (int m = 0; m < 4; ++m) _Pragma("unroll") for (int n = 0; n < 2; ++n) _Pragma("unroll") for (int k = 0; k < 2; ++k) \
;         acc[ai][bj][m][n] = __builtin_amdgcn_mfma_f32_16x16x32_bf16(Bt[n][k], At[m][k], acc[ai][bj][m][n], 0, 0, 0); __builtin_amdgcn_s_setprio(0); } while (0)
; #define PG8_WAIT_V(n) asm volatile("s_waitcnt vmcnt(" #n ")" ::: "memory")
; #define PG8_WAIT_L(n) asm volatile("s_waitcnt lgkmcnt(" #n ")" ::: "memory")
; #define PG8_BAR __builtin_amdgcn_s_barrier()
; #define PG8_SCHED __builtin_amdgcn_sched_barrier(0)
; template <class Epi, class Sched, bool ALIGN_EPI = false, bool SP2 = false>
; __device__ __forceinline__ void gemm_phase(PG8_LAS unsigned char* lds, const Gemm g, const Sched& S, const Epi& E, const int wave_id) {
;     ...
;             PG8_LDB(B0, 1, 0); PG8_LDB(B1, 1, 1); PG8_SCHED; PG8_LDA(At, 1, 0); PG8_STAGE(PG8_SA(0, 1), a2 + hstep, voffA);
;             PG8_WAIT_V(8); PG8_WAIT_L(0); PG8_BAR; PG8_MMA(0, 0, At, B0); PG8_MMA(0, 1, At, B1); PG8_BAR; PG8_SCHED;
;             PG8_LDA(At, 1, 1); PG8_STAGE(PG8_SB(1, 0), b3, voffB); PG8_STAGE(PG8_SB(1, 1), b3 + hstep, voffB); PG8_STAGE(PG8_SA(1, 0), a3, voffA);
;             PG8_WAIT_V(8); PG8_WAIT_L(0); PG8_BAR; PG8_MMA(1, 0, At, B0); PG8_MMA(1, 1, At, B1); PG8_BAR; PG8_SCHED;
.Lthird_wait_relaxed_2:
	s_waitcnt lgkmcnt(0)
	s_setprio 1
	s_barrier
	v_mfma_f32_16x16x32_bf16 v[126:129], v[130:133], v[162:165], v[126:129]
	v_mfma_f32_16x16x32_bf16 v[122:125], v[138:141], v[162:165], v[122:125]
	v_mfma_f32_16x16x32_bf16 v[118:121], v[130:133], v[170:173], v[118:121]
	v_mfma_f32_16x16x32_bf16 v[114:117], v[138:141], v[170:173], v[114:117]
	v_mfma_f32_16x16x32_bf16 v[94:97], v[130:133], v[178:181], v[94:97]
	v_mfma_f32_16x16x32_bf16 v[90:93], v[138:141], v[178:181], v[90:93]
	v_mfma_f32_16x16x32_bf16 v[86:89], v[130:133], v[186:189], v[86:89]
	v_mfma_f32_16x16x32_bf16 v[82:85], v[138:141], v[186:189], v[82:85]
	v_mfma_f32_16x16x32_bf16 v[126:129], v[134:137], v[166:169], v[126:129]
	v_mfma_f32_16x16x32_bf16 v[122:125], v[142:145], v[166:169], v[122:125]
	v_mfma_f32_16x16x32_bf16 v[118:121], v[134:137], v[174:177], v[118:121]
	v_mfma_f32_16x16x32_bf16 v[114:117], v[142:145], v[174:177], v[114:117]
	v_mfma_f32_16x16x32_bf16 v[94:97], v[134:137], v[182:185], v[94:97]
	v_mfma_f32_16x16x32_bf16 v[90:93], v[142:145], v[182:185], v[90:93]
	v_mfma_f32_16x16x32_bf16 v[86:89], v[134:137], v[190:193], v[86:89]
	v_mfma_f32_16x16x32_bf16 v[82:85], v[142:145], v[190:193], v[82:85]
	v_mfma_f32_16x16x32_bf16 v[110:113], v[146:149], v[162:165], v[110:113]
	v_mfma_f32_16x16x32_bf16 v[106:109], v[154:157], v[162:165], v[106:109]
	v_mfma_f32_16x16x32_bf16 v[102:105], v[146:149], v[170:173], v[102:105]
	v_mfma_f32_16x16x32_bf16 v[98:101], v[154:157], v[170:173], v[98:101]
	v_mfma_f32_16x16x32_bf16 v[78:81], v[146:149], v[178:181], v[78:81]
	v_mfma_f32_16x16x32_bf16 v[74:77], v[154:157], v[178:181], v[74:77]
	v_mfma_f32_16x16x32_bf16 v[70:73], v[146:149], v[186:189], v[70:73]
	v_mfma_f32_16x16x32_bf16 v[66:69], v[154:157], v[186:189], v[66:69]
	v_mfma_f32_16x16x32_bf16 v[110:113], v[150:153], v[166:169], v[110:113]
	v_mfma_f32_16x16x32_bf16 v[106:109], v[158:161], v[166:169], v[106:109]
	v_mfma_f32_16x16x32_bf16 v[102:105], v[150:153], v[174:177], v[102:105]
	v_mfma_f32_16x16x32_bf16 v[98:101], v[158:161], v[174:177], v[98:101]
	v_mfma_f32_16x16x32_bf16 v[78:81], v[150:153], v[182:185], v[78:81]
	v_mfma_f32_16x16x32_bf16 v[74:77], v[158:161], v[182:185], v[74:77]
	v_mfma_f32_16x16x32_bf16 v[70:73], v[150:153], v[190:193], v[70:73]
	v_mfma_f32_16x16x32_bf16 v[66:69], v[158:161], v[190:193], v[66:69]
	s_setprio 0
	s_barrier
	s_add_i32 s26, s28, s39
	v_lshl_add_u64 v[194:195], v[232:233], 0, s[64:65]
	s_mov_b32 m0, s26
	ds_read_b128 v[162:165], v247 offset:49152
	ds_read_b128 v[166:169], v247 offset:50176
	ds_read_b128 v[170:173], v247 offset:51200
	ds_read_b128 v[174:177], v247 offset:52224
	ds_read_b128 v[178:181], v247 offset:53248
	ds_read_b128 v[182:185], v247 offset:54272
	ds_read_b128 v[186:189], v247 offset:55296
	ds_read_b128 v[190:193], v247 offset:56320
	global_load_lds_dwordx4 v[194:195], off
	s_add_i32 m0, s26, 0x2000
	s_add_u32 s24, s24, 0x40080
	v_lshl_add_u64 v[194:195], v[230:231], 0, s[64:65]
	s_addc_u32 s25, s25, 0
	s_add_i32 s26, s29, s39
	global_load_lds_dwordx4 v[194:195], off
	v_lshl_add_u64 v[194:195], s[24:25], 0, v[214:215]
	s_mov_b32 m0, s26
	s_nop 0
	global_load_lds_dwordx4 v[194:195], off
	v_lshl_add_u64 v[194:195], s[24:25], 0, v[210:211]
	s_add_i32 m0, s26, 0x2000
	s_nop 0
	global_load_lds_dwordx4 v[194:195], off
	v_lshl_add_u64 v[194:195], v[226:227], 0, s[64:65]
	s_mov_b32 m0, s57
	s_nop 0
	global_load_lds_dwordx4 v[194:195], off
	v_lshl_add_u64 v[194:195], v[228:229], 0, s[64:65]
	s_mov_b32 m0, s62
	s_nop 0
	global_load_lds_dwordx4 v[194:195], off
	s_waitcnt vmcnt(8)
	s_waitcnt lgkmcnt(0)
	s_setprio 1
	s_barrier
	v_mfma_f32_16x16x32_bf16 v[62:65], v[130:133], v[162:165], v[62:65]
	v_mfma_f32_16x16x32_bf16 v[58:61], v[138:141], v[162:165], v[58:61]
	v_mfma_f32_16x16x32_bf16 v[54:57], v[130:133], v[170:173], v[54:57]
	v_mfma_f32_16x16x32_bf16 v[50:53], v[138:141], v[170:173], v[50:53]
	v_mfma_f32_16x16x32_bf16 v[30:33], v[130:133], v[178:181], v[30:33]
	v_mfma_f32_16x16x32_bf16 v[26:29], v[138:141], v[178:181], v[26:29]
	v_mfma_f32_16x16x32_bf16 v[22:25], v[130:133], v[186:189], v[22:25]
	v_mfma_f32_16x16x32_bf16 v[18:21], v[138:141], v[186:189], v[18:21]
	v_mfma_f32_16x16x32_bf16 v[62:65], v[134:137], v[166:169], v[62:65]
	v_mfma_f32_16x16x32_bf16 v[58:61], v[142:145], v[166:169], v[58:61]
	v_mfma_f32_16x16x32_bf16 v[54:57], v[134:137], v[174:177], v[54:57]
	v_mfma_f32_16x16x32_bf16 v[50:53], v[142:145], v[174:177], v[50:53]
	v_mfma_f32_16x16x32_bf16 v[30:33], v[134:137], v[182:185], v[30:33]
	v_mfma_f32_16x16x32_bf16 v[26:29], v[142:145], v[182:185], v[26:29]
	v_mfma_f32_16x16x32_bf16 v[22:25], v[134:137], v[190:193], v[22:25]
	v_mfma_f32_16x16x32_bf16 v[18:21], v[142:145], v[190:193], v[18:21]
	v_mfma_f32_16x16x32_bf16 v[46:49], v[146:149], v[162:165], v[46:49]
	v_mfma_f32_16x16x32_bf16 v[42:45], v[154:157], v[162:165], v[42:45]
	v_mfma_f32_16x16x32_bf16 v[38:41], v[146:149], v[170:173], v[38:41]
	v_mfma_f32_16x16x32_bf16 v[34:37], v[154:157], v[170:173], v[34:37]
	v_mfma_f32_16x16x32_bf16 v[14:17], v[146:149], v[178:181], v[14:17]
	v_mfma_f32_16x16x32_bf16 v[10:13], v[154:157], v[178:181], v[10:13]
	v_mfma_f32_16x16x32_bf16 v[6:9], v[146:149], v[186:189], v[6:9]
	v_mfma_f32_16x16x32_bf16 v[2:5], v[154:157], v[186:189], v[2:5]
	v_mfma_f32_16x16x32_bf16 v[46:49], v[150:153], v[166:169], v[46:49]
	v_mfma_f32_16x16x32_bf16 v[42:45], v[158:161], v[166:169], v[42:45]
	v_mfma_f32_16x16x32_bf16 v[38:41], v[150:153], v[174:177], v[38:41]
	v_mfma_f32_16x16x32_bf16 v[34:37], v[158:161], v[174:177], v[34:37]
	v_mfma_f32_16x16x32_bf16 v[14:17], v[150:153], v[182:185], v[14:17]
	v_mfma_f32_16x16x32_bf16 v[10:13], v[158:161], v[182:185], v[10:13]
	v_mfma_f32_16x16x32_bf16 v[6:9], v[150:153], v[190:193], v[6:9]
	v_mfma_f32_16x16x32_bf16 v[2:5], v[158:161], v[190:193], v[2:5]
	s_setprio 0
	s_barrier
	s_add_i32 s76, s76, 2
	s_add_u32 s22, s22, 0x100
	s_addc_u32 s23, s23, 0
	s_cmp_gt_u32 s76, 13
	s_cbranch_scc1 .LBB0_1957

; #define PG8_STAGE(bufoff, gbase, voff) do { _Pragma("unroll") for (int _i = 0; _i < 2; ++_i) \
;         __builtin_amdgcn_global_load_lds((const unsigned*)((const char*)(gbase) + (voff)[_i]), (PG8_LAS unsigned*)(lds + (bufoff) + ldsw + _i * 8192), 16, 0, 0); } while (0)
; #define PG8_LDA(dst, b, h) do { _Pragma("unroll") for (int m = 0; m < 4; ++m) _Pragma("unroll") for (int k = 0; k < 2; ++k) dst[m][k] = *(const PG8_LAS bf16x8*)(lds + PG8_SA(b, h) + aoff + m * 2048 + k * 1024); } while (0)
; #define PG8_LDB(dst, b, h) do { _Pragma("unroll") for (int n = 0; n < 2; ++n) _Pragma("unroll") for (int k = 0; k < 2; ++k) dst[n][k] = *(const PG8_LAS bf16x8*)(lds + PG8_SB(b, h) + boff + n * 2048 + k * 1024); } while (0)
; #define PG8_WAIT_V(n) asm volatile("s_waitcnt vmcnt(" #n ")" ::: "memory")
; #define PG8_WAIT_VN(n) asm volatile("s_waitcnt vmcnt(%0)" :: "n"(n) : "memory")
; #define PG8_WAIT_L(n) asm volatile("s_waitcnt lgkmcnt(" #n ")" ::: "memory")
; template <class Epi, class Sched, bool ALIGN_EPI = false, bool SP2 = false>
; __device__ __forceinline__ void gemm_phase(PG8_LAS unsigned char* lds, const Gemm g, const Sched& S, const Epi& E, const int wave_id) {
;     ...
;         for (int t = 0; t < nt; t += 2) {
;             const bool last = (t == nt - 2);
;             const char* a1 = cA + (size_t)(t + 1) * kstep;
;             const char* a2 = last ? nA : cA + (size_t)(t + 2) * kstep; const char* b2 = last ? nB : cB + (size_t)(t + 2) * kstep;
;             const char* a3 = a2 + kstep; const char* b3 = b2 + kstep;
;             if (last && has_next) S.a_ready(nxt);
;             if constexpr (SP2) {
;             int tz_ = __builtin_amdgcn_readfirstlane(t | (ui > 0 ? 0 : 1)); asm volatile("" : "+s"(tz_));
;             const bool strict = !(Epi::NS > 0 && tz_ == 0);
;             PG8_LDB(B0, 0, 0); PG8_LDB(B1, 0, 1); PG8_SCHED; PG8_LDA(At, 0, 0); PG8_STAGE(PG8_SA(1, 1), a1 + hstep, voffA);
;             PG8_WAIT_VN(8 + Epi::NS); if (strict) PG8_WAIT_V(8); PG8_WAIT_L(0); PG8_BAR; PG8_MMA(0, 0, At, B0); PG8_MMA(0, 1, At, B1); PG8_BAR; PG8_SCHED;
;             PG8_LDA(At, 0, 1); PG8_STAGE(PG8_SB(0, 0), b2, voffB); PG8_STAGE(PG8_SB(0, 1), b2 + hstep, voffB); PG8_STAGE(PG8_SA(0, 0), a2, voffA);
;             PG8_WAIT_VN(8 + Epi::NS); if (strict) PG8_WAIT_V(8); PG8_WAIT_L(0); PG8_BAR; PG8_MMA(1, 0, At, B0); PG8_MMA(1, 1, At, B1); PG8_BAR; PG8_SCHED;
.LBB0_1955:
	s_add_u32 s24, s20, s22
	s_addc_u32 s25, s21, s23
	s_add_u32 s24, s24, 0x100
	s_addc_u32 s25, s25, 0
	s_add_u32 s53, s74, s22
	s_addc_u32 s78, s75, s23
	s_cmpk_eq_i32 s22, 0x700
	s_cselect_b32 s27, s13, s25
	s_cselect_b32 s26, s68, s24
	s_cselect_b32 s25, s11, s78
	s_cselect_b32 s24, s69, s53
	s_waitcnt lgkmcnt(0)
	s_setprio 1
	s_barrier
	v_mfma_f32_16x16x32_bf16 v[126:129], v[146:149], v[186:189], v[126:129]
	v_mfma_f32_16x16x32_bf16 v[122:125], v[154:157], v[186:189], v[122:125]
	v_mfma_f32_16x16x32_bf16 v[118:121], v[146:149], v[178:181], v[118:121]
	v_mfma_f32_16x16x32_bf16 v[114:117], v[154:157], v[178:181], v[114:117]
	v_mfma_f32_16x16x32_bf16 v[94:97], v[146:149], v[170:173], v[94:97]
	v_mfma_f32_16x16x32_bf16 v[90:93], v[154:157], v[170:173], v[90:93]
	v_mfma_f32_16x16x32_bf16 v[86:89], v[146:149], v[162:165], v[86:89]
	v_mfma_f32_16x16x32_bf16 v[82:85], v[154:157], v[162:165], v[82:85]
	v_mfma_f32_16x16x32_bf16 v[126:129], v[150:153], v[190:193], v[126:129]
	v_mfma_f32_16x16x32_bf16 v[122:125], v[158:161], v[190:193], v[122:125]
	v_mfma_f32_16x16x32_bf16 v[118:121], v[150:153], v[182:185], v[118:121]
	v_mfma_f32_16x16x32_bf16 v[114:117], v[158:161], v[182:185], v[114:117]
	v_mfma_f32_16x16x32_bf16 v[94:97], v[150:153], v[174:177], v[94:97]
	v_mfma_f32_16x16x32_bf16 v[90:93], v[158:161], v[174:177], v[90:93]
	v_mfma_f32_16x16x32_bf16 v[86:89], v[150:153], v[166:169], v[86:89]
	v_mfma_f32_16x16x32_bf16 v[82:85], v[158:161], v[166:169], v[82:85]
	v_mfma_f32_16x16x32_bf16 v[110:113], v[130:133], v[186:189], v[110:113]
	v_mfma_f32_16x16x32_bf16 v[106:109], v[138:141], v[186:189], v[106:109]
	v_mfma_f32_16x16x32_bf16 v[102:105], v[130:133], v[178:181], v[102:105]
	v_mfma_f32_16x16x32_bf16 v[98:101], v[138:141], v[178:181], v[98:101]
	v_mfma_f32_16x16x32_bf16 v[78:81], v[130:133], v[170:173], v[78:81]
	v_mfma_f32_16x16x32_bf16 v[74:77], v[138:141], v[170:173], v[74:77]
	v_mfma_f32_16x16x32_bf16 v[70:73], v[130:133], v[162:165], v[70:73]
	v_mfma_f32_16x16x32_bf16 v[66:69], v[138:141], v[162:165], v[66:69]
	v_mfma_f32_16x16x32_bf16 v[110:113], v[134:137], v[190:193], v[110:113]
	v_mfma_f32_16x16x32_bf16 v[106:109], v[142:145], v[190:193], v[106:109]
	v_mfma_f32_16x16x32_bf16 v[102:105], v[134:137], v[182:185], v[102:105]
	v_mfma_f32_16x16x32_bf16 v[98:101], v[142:145], v[182:185], v[98:101]
	v_mfma_f32_16x16x32_bf16 v[78:81], v[134:137], v[174:177], v[78:81]
	v_mfma_f32_16x16x32_bf16 v[74:77], v[142:145], v[174:177], v[74:77]
	v_mfma_f32_16x16x32_bf16 v[70:73], v[134:137], v[166:169], v[70:73]
	v_mfma_f32_16x16x32_bf16 v[66:69], v[142:145], v[166:169], v[66:69]
	s_setprio 0
	s_barrier
	s_mov_b32 m0, s42
	v_lshl_add_u64 v[232:233], s[24:25], 0, v[214:215]
	s_add_u32 s90, s24, 0x40000
	ds_read_b128 v[186:189], v247 offset:16384
	ds_read_b128 v[190:193], v247 offset:17408
	ds_read_b128 v[178:181], v247 offset:18432
	ds_read_b128 v[182:185], v247 offset:19456
	ds_read_b128 v[170:173], v247 offset:20480
	ds_read_b128 v[174:177], v247 offset:21504
	ds_read_b128 v[162:165], v247 offset:22528
	ds_read_b128 v[166:169], v247 offset:23552
	global_load_lds_dwordx4 v[232:233], off
	v_lshl_add_u64 v[230:231], s[24:25], 0, v[210:211]
	s_mov_b32 m0, s43
	s_addc_u32 s91, s25, 0
	global_load_lds_dwordx4 v[230:231], off
	v_lshl_add_u64 v[194:195], s[90:91], 0, v[214:215]
	s_mov_b32 m0, s49
	v_lshl_add_u64 v[226:227], s[26:27], 0, v[216:217]
	global_load_lds_dwordx4 v[194:195], off
	v_lshl_add_u64 v[194:195], s[90:91], 0, v[210:211]
	s_mov_b32 m0, s50
	v_lshl_add_u64 v[228:229], s[26:27], 0, v[212:213]
	global_load_lds_dwordx4 v[194:195], off
	s_mov_b32 m0, s41
	s_andn2_b64 vcc, exec, s[28:29]
	global_load_lds_dwordx4 v[226:227], off
	s_mov_b32 m0, s51
	s_nop 0
	global_load_lds_dwordx4 v[228:229], off
	s_waitcnt vmcnt(16)
	s_cbranch_vccnz .LBB0_1952
	s_waitcnt vmcnt(8)
	s_branch .LBB0_1952

; #define PG8_STAGE(bufoff, gbase, voff) do { _Pragma("unroll") for (int _i = 0; _i < 2; ++_i) \
;         __builtin_amdgcn_global_load_lds((const unsigned*)((const char*)(gbase) + (voff)[_i]), (PG8_LAS unsigned*)(lds + (bufoff) + ldsw + _i * 8192), 16, 0, 0); } while (0)
; #define PG8_LDA(dst, b, h) do { _Pragma("unroll") for (int m = 0; m < 4; ++m) _Pragma("unroll") for (int k = 0; k < 2; ++k) dst[m][k] = *(const PG8_LAS bf16x8*)(lds + PG8_SA(b, h) + aoff + m * 2048 + k * 1024); } while (0)
; #define PG8_LDB(dst, b, h) do { _Pragma("unroll") for (int n = 0; n < 2; ++n) _Pragma("unroll") for (int k = 0; k < 2; ++k) dst[n][k] = *(const PG8_LAS bf16x8*)(lds + PG8_SB(b, h) + boff + n * 2048 + k * 1024); } while (0)
; #define PG8_WAIT_V(n) asm volatile("s_waitcnt vmcnt(" #n ")" ::: "memory")
; #define PG8_WAIT_VN(n) asm volatile("s_waitcnt vmcnt(%0)" :: "n"(n) : "memory")
; #define PG8_WAIT_L(n) asm volatile("s_waitcnt lgkmcnt(" #n ")" ::: "memory")
; template <class Epi, class Sched, bool ALIGN_EPI = false, bool SP2 = false>
; __device__ __forceinline__ void gemm_phase(PG8_LAS unsigned char* lds, const Gemm g, const Sched& S, const Epi& E, const int wave_id) {
;     ...
;         for (int t = 0; t < nt; t += 2) {
;             const bool last = (t == nt - 2);
;             const char* a1 = cA + (size_t)(t + 1) * kstep;
;             const char* a2 = last ? nA : cA + (size_t)(t + 2) * kstep; const char* b2 = last ? nB : cB + (size_t)(t + 2) * kstep;
;             const char* a3 = a2 + kstep; const char* b3 = b2 + kstep;
;             if (last && has_next) S.a_ready(nxt);
;             if constexpr (SP2) {
;             int tz_ = __builtin_amdgcn_readfirstlane(t | (ui > 0 ? 0 : 1)); asm volatile("" : "+s"(tz_));
;             const bool strict = !(Epi::NS > 0 && tz_ == 0);
;             PG8_LDB(B0, 0, 0); PG8_LDB(B1, 0, 1); PG8_SCHED; PG8_LDA(At, 0, 0); PG8_STAGE(PG8_SA(1, 1), a1 + hstep, voffA);
;             PG8_WAIT_VN(8 + Epi::NS); if (strict) PG8_WAIT_V(8); PG8_WAIT_L(0); PG8_BAR; PG8_MMA(0, 0, At, B0); PG8_MMA(0, 1, At, B1); PG8_BAR; PG8_SCHED;
;             PG8_LDA(At, 0, 1); PG8_STAGE(PG8_SB(0, 0), b2, voffB); PG8_STAGE(PG8_SB(0, 1), b2 + hstep, voffB); PG8_STAGE(PG8_SA(0, 0), a2, voffA);
;             PG8_WAIT_VN(8 + Epi::NS); if (strict) PG8_WAIT_V(8); PG8_WAIT_L(0); PG8_BAR; PG8_MMA(1, 0, At, B0); PG8_MMA(1, 1, At, B1); PG8_BAR; PG8_SCHED;
.LBB0_2033:
	s_add_u32 s16, s12, s14
	s_addc_u32 s17, s13, s15
	s_add_u32 s16, s16, 0x100
	s_addc_u32 s17, s17, 0
	s_add_u32 s53, s57, s14
	s_addc_u32 s67, s62, s15
	s_cmpk_eq_i32 s14, 0x1500
	s_cselect_b32 s19, s9, s17
	s_cselect_b32 s18, s8, s16
	s_cselect_b32 s17, s11, s67
	s_cselect_b32 s16, s10, s53
	s_waitcnt lgkmcnt(0)
	s_setprio 1
	s_barrier
	v_mfma_f32_16x16x32_bf16 v[126:129], v[146:149], v[186:189], v[126:129]
	v_mfma_f32_16x16x32_bf16 v[122:125], v[154:157], v[186:189], v[122:125]
	v_mfma_f32_16x16x32_bf16 v[110:113], v[146:149], v[178:181], v[110:113]
	v_mfma_f32_16x16x32_bf16 v[106:109], v[154:157], v[178:181], v[106:109]
	v_mfma_f32_16x16x32_bf16 v[94:97], v[146:149], v[170:173], v[94:97]
	v_mfma_f32_16x16x32_bf16 v[90:93], v[154:157], v[170:173], v[90:93]
	v_mfma_f32_16x16x32_bf16 v[78:81], v[146:149], v[162:165], v[78:81]
	v_mfma_f32_16x16x32_bf16 v[74:77], v[154:157], v[162:165], v[74:77]
	v_mfma_f32_16x16x32_bf16 v[126:129], v[150:153], v[190:193], v[126:129]
	v_mfma_f32_16x16x32_bf16 v[122:125], v[158:161], v[190:193], v[122:125]
	v_mfma_f32_16x16x32_bf16 v[110:113], v[150:153], v[182:185], v[110:113]
	v_mfma_f32_16x16x32_bf16 v[106:109], v[158:161], v[182:185], v[106:109]
	v_mfma_f32_16x16x32_bf16 v[94:97], v[150:153], v[174:177], v[94:97]
	v_mfma_f32_16x16x32_bf16 v[90:93], v[158:161], v[174:177], v[90:93]
	v_mfma_f32_16x16x32_bf16 v[78:81], v[150:153], v[166:169], v[78:81]
	v_mfma_f32_16x16x32_bf16 v[74:77], v[158:161], v[166:169], v[74:77]
	v_mfma_f32_16x16x32_bf16 v[118:121], v[130:133], v[186:189], v[118:121]
	v_mfma_f32_16x16x32_bf16 v[114:117], v[138:141], v[186:189], v[114:117]
	v_mfma_f32_16x16x32_bf16 v[102:105], v[130:133], v[178:181], v[102:105]
	v_mfma_f32_16x16x32_bf16 v[98:101], v[138:141], v[178:181], v[98:101]
	v_mfma_f32_16x16x32_bf16 v[86:89], v[130:133], v[170:173], v[86:89]
	v_mfma_f32_16x16x32_bf16 v[82:85], v[138:141], v[170:173], v[82:85]
	v_mfma_f32_16x16x32_bf16 v[70:73], v[130:133], v[162:165], v[70:73]
	v_mfma_f32_16x16x32_bf16 v[66:69], v[138:141], v[162:165], v[66:69]
	v_mfma_f32_16x16x32_bf16 v[118:121], v[134:137], v[190:193], v[118:121]
	v_mfma_f32_16x16x32_bf16 v[114:117], v[142:145], v[190:193], v[114:117]
	v_mfma_f32_16x16x32_bf16 v[102:105], v[134:137], v[182:185], v[102:105]
	v_mfma_f32_16x16x32_bf16 v[98:101], v[142:145], v[182:185], v[98:101]
	v_mfma_f32_16x16x32_bf16 v[86:89], v[134:137], v[174:177], v[86:89]
	v_mfma_f32_16x16x32_bf16 v[82:85], v[142:145], v[174:177], v[82:85]
	v_mfma_f32_16x16x32_bf16 v[70:73], v[134:137], v[166:169], v[70:73]
	v_mfma_f32_16x16x32_bf16 v[66:69], v[142:145], v[166:169], v[66:69]
	s_setprio 0
	s_barrier
	s_mov_b32 m0, s34
	v_lshl_add_u64 v[232:233], s[16:17], 0, v[212:213]
	s_add_u32 s68, s16, 0xb0000
	ds_read_b128 v[186:189], v247 offset:16384
	ds_read_b128 v[190:193], v247 offset:17408
	ds_read_b128 v[178:181], v247 offset:18432
	ds_read_b128 v[182:185], v247 offset:19456
	ds_read_b128 v[170:173], v247 offset:20480
	ds_read_b128 v[174:177], v247 offset:21504
	ds_read_b128 v[162:165], v247 offset:22528
	ds_read_b128 v[166:169], v247 offset:23552
	global_load_lds_dwordx4 v[232:233], off
	v_lshl_add_u64 v[230:231], s[16:17], 0, v[216:217]
	s_mov_b32 m0, s35
	s_addc_u32 s69, s17, 0
	global_load_lds_dwordx4 v[230:231], off
	v_lshl_add_u64 v[194:195], s[68:69], 0, v[212:213]
	s_mov_b32 m0, s36
	v_lshl_add_u64 v[226:227], s[18:19], 0, v[210:211]
	global_load_lds_dwordx4 v[194:195], off
	v_lshl_add_u64 v[194:195], s[68:69], 0, v[216:217]
	s_mov_b32 m0, s37
	v_lshl_add_u64 v[228:229], s[18:19], 0, v[214:215]
	global_load_lds_dwordx4 v[194:195], off
	s_mov_b32 m0, s31
	s_andn2_b64 vcc, exec, s[20:21]
	global_load_lds_dwordx4 v[226:227], off
	s_mov_b32 m0, s38
	s_nop 0
	global_load_lds_dwordx4 v[228:229], off
	s_waitcnt vmcnt(24)
	s_cbranch_vccnz .LBB0_2030
	s_waitcnt vmcnt(8)
	s_branch .LBB0_2030
